# GEMM K-loops: no-op priority flip between the two MFMA groups and the duplicate LDS-count wait removed
# speedup vs baseline: 1.0077x; 1.0005x over previous
.LBB11_221:
	ds_read_b128 v[142:145], v161
	ds_read_b128 v[146:149], v161 offset:1024
	ds_read_b128 v[164:167], v161 offset:2048
	ds_read_b128 v[168:171], v161 offset:3072
	ds_read_b128 v[172:175], v162
	ds_read_b128 v[176:179], v162 offset:1024
	ds_read_b128 v[180:183], v162 offset:2048
	ds_read_b128 v[184:187], v162 offset:3072
	s_add_u32 s22, s20, 0xfffc0080
	s_addc_u32 s23, s21, -1
	s_cmp_eq_u32 s63, 12
	s_cselect_b32 s25, s7, s23
	s_cselect_b32 s24, s26, s22
	s_cselect_b32 s23, s27, s62
	s_cselect_b32 s22, s60, s61
	s_mov_b32 m0, s47
	v_lshl_add_u64 v[196:197], s[20:21], 0, v[138:139]
	ds_read_b128 v[188:191], v163
	ds_read_b128 v[192:195], v163 offset:1024
	ds_read_b128 v[200:203], v163 offset:2048
	ds_read_b128 v[204:207], v163 offset:3072
	ds_read_b128 v[208:211], v163 offset:4096
	ds_read_b128 v[212:215], v163 offset:5120
	ds_read_b128 v[216:219], v163 offset:6144
	ds_read_b128 v[220:223], v163 offset:7168
	global_load_lds_dwordx4 v[196:197], off
	v_lshl_add_u64 v[196:197], s[20:21], 0, v[140:141]
	s_mov_b32 m0, s51
	s_nop 0
	global_load_lds_dwordx4 v[196:197], off
	s_waitcnt vmcnt(8)
	s_waitcnt lgkmcnt(0)
	s_barrier
	s_setprio 1
	v_mfma_f32_16x16x32_bf16 v[124:127], v[142:145], v[188:191], v[124:127]
	v_mfma_f32_16x16x32_bf16 v[120:123], v[164:167], v[188:191], v[120:123]
	v_mfma_f32_16x16x32_bf16 v[108:111], v[142:145], v[200:203], v[108:111]
	v_mfma_f32_16x16x32_bf16 v[104:107], v[164:167], v[200:203], v[104:107]
	v_mfma_f32_16x16x32_bf16 v[92:95], v[142:145], v[208:211], v[92:95]
	v_mfma_f32_16x16x32_bf16 v[88:91], v[164:167], v[208:211], v[88:91]
	v_mfma_f32_16x16x32_bf16 v[76:79], v[142:145], v[216:219], v[76:79]
	v_mfma_f32_16x16x32_bf16 v[72:75], v[164:167], v[216:219], v[72:75]
	v_mfma_f32_16x16x32_bf16 v[124:127], v[146:149], v[192:195], v[124:127]
	v_mfma_f32_16x16x32_bf16 v[120:123], v[168:171], v[192:195], v[120:123]
	v_mfma_f32_16x16x32_bf16 v[108:111], v[146:149], v[204:207], v[108:111]
	v_mfma_f32_16x16x32_bf16 v[104:107], v[168:171], v[204:207], v[104:107]
	v_mfma_f32_16x16x32_bf16 v[92:95], v[146:149], v[212:215], v[92:95]
	v_mfma_f32_16x16x32_bf16 v[88:91], v[168:171], v[212:215], v[88:91]
	v_mfma_f32_16x16x32_bf16 v[76:79], v[146:149], v[220:223], v[76:79]
	v_mfma_f32_16x16x32_bf16 v[72:75], v[168:171], v[220:223], v[72:75]
	v_mfma_f32_16x16x32_bf16 v[116:119], v[172:175], v[188:191], v[116:119]
	v_mfma_f32_16x16x32_bf16 v[112:115], v[180:183], v[188:191], v[112:115]
	v_mfma_f32_16x16x32_bf16 v[100:103], v[172:175], v[200:203], v[100:103]
	v_mfma_f32_16x16x32_bf16 v[96:99], v[180:183], v[200:203], v[96:99]
	v_mfma_f32_16x16x32_bf16 v[84:87], v[172:175], v[208:211], v[84:87]
	v_mfma_f32_16x16x32_bf16 v[80:83], v[180:183], v[208:211], v[80:83]
	v_mfma_f32_16x16x32_bf16 v[68:71], v[172:175], v[216:219], v[68:71]
	v_mfma_f32_16x16x32_bf16 v[64:67], v[180:183], v[216:219], v[64:67]
	v_mfma_f32_16x16x32_bf16 v[116:119], v[176:179], v[192:195], v[116:119]
	v_mfma_f32_16x16x32_bf16 v[112:115], v[184:187], v[192:195], v[112:115]
	v_mfma_f32_16x16x32_bf16 v[100:103], v[176:179], v[204:207], v[100:103]
	v_mfma_f32_16x16x32_bf16 v[96:99], v[184:187], v[204:207], v[96:99]
	v_mfma_f32_16x16x32_bf16 v[84:87], v[176:179], v[212:215], v[84:87]
	v_mfma_f32_16x16x32_bf16 v[80:83], v[184:187], v[212:215], v[80:83]
	v_mfma_f32_16x16x32_bf16 v[68:71], v[176:179], v[220:223], v[68:71]
	v_mfma_f32_16x16x32_bf16 v[64:67], v[184:187], v[220:223], v[64:67]
	s_setprio 0
	s_barrier
	s_mov_b32 m0, s56
	v_lshl_add_u64 v[196:197], s[22:23], 0, v[132:133]
	ds_read_b128 v[188:191], v163 offset:16384
	ds_read_b128 v[192:195], v163 offset:17408
	ds_read_b128 v[200:203], v163 offset:18432
	ds_read_b128 v[204:207], v163 offset:19456
	ds_read_b128 v[208:211], v163 offset:20480
	ds_read_b128 v[212:215], v163 offset:21504
	ds_read_b128 v[216:219], v163 offset:22528
	ds_read_b128 v[220:223], v163 offset:23552
	global_load_lds_dwordx4 v[196:197], off
	s_add_i32 m0, s56, 0x2000
	s_add_u32 s64, s22, 0x40000
	v_lshl_add_u64 v[224:225], s[22:23], 0, v[128:129]
	s_addc_u32 s65, s23, 0
	s_add_i32 s66, s45, s28
	global_load_lds_dwordx4 v[224:225], off
	v_lshl_add_u64 v[226:227], s[64:65], 0, v[132:133]
	s_mov_b32 m0, s66
	v_lshl_add_u64 v[228:229], s[24:25], 0, v[130:131]
	global_load_lds_dwordx4 v[226:227], off
	v_lshl_add_u64 v[226:227], s[64:65], 0, v[128:129]
	s_add_i32 m0, s66, 0x2000
	s_nop 0
	global_load_lds_dwordx4 v[226:227], off
	v_lshl_add_u64 v[226:227], s[24:25], 0, v[134:135]
	s_mov_b32 m0, s38
	s_nop 0
	global_load_lds_dwordx4 v[226:227], off
	s_mov_b32 m0, s39
	s_nop 0
	global_load_lds_dwordx4 v[228:229], off
	s_waitcnt vmcnt(8)
	s_waitcnt lgkmcnt(0)
	s_barrier
	s_setprio 1
	v_mfma_f32_16x16x32_bf16 v[60:63], v[142:145], v[188:191], v[60:63]
	v_mfma_f32_16x16x32_bf16 v[56:59], v[164:167], v[188:191], v[56:59]
	v_mfma_f32_16x16x32_bf16 v[44:47], v[142:145], v[200:203], v[44:47]
	v_mfma_f32_16x16x32_bf16 v[40:43], v[164:167], v[200:203], v[40:43]
	v_mfma_f32_16x16x32_bf16 v[28:31], v[142:145], v[208:211], v[28:31]
	v_mfma_f32_16x16x32_bf16 v[24:27], v[164:167], v[208:211], v[24:27]
	v_mfma_f32_16x16x32_bf16 v[12:15], v[142:145], v[216:219], v[12:15]
	v_mfma_f32_16x16x32_bf16 v[8:11], v[164:167], v[216:219], v[8:11]
	v_mfma_f32_16x16x32_bf16 v[60:63], v[146:149], v[192:195], v[60:63]
	v_mfma_f32_16x16x32_bf16 v[56:59], v[168:171], v[192:195], v[56:59]
	v_mfma_f32_16x16x32_bf16 v[44:47], v[146:149], v[204:207], v[44:47]
	v_mfma_f32_16x16x32_bf16 v[40:43], v[168:171], v[204:207], v[40:43]
	v_mfma_f32_16x16x32_bf16 v[28:31], v[146:149], v[212:215], v[28:31]
	v_mfma_f32_16x16x32_bf16 v[24:27], v[168:171], v[212:215], v[24:27]
	v_mfma_f32_16x16x32_bf16 v[12:15], v[146:149], v[220:223], v[12:15]
	v_mfma_f32_16x16x32_bf16 v[8:11], v[168:171], v[220:223], v[8:11]
	v_mfma_f32_16x16x32_bf16 v[52:55], v[172:175], v[188:191], v[52:55]
	v_mfma_f32_16x16x32_bf16 v[48:51], v[180:183], v[188:191], v[48:51]
	v_mfma_f32_16x16x32_bf16 v[36:39], v[172:175], v[200:203], v[36:39]
	v_mfma_f32_16x16x32_bf16 v[32:35], v[180:183], v[200:203], v[32:35]
	v_mfma_f32_16x16x32_bf16 v[20:23], v[172:175], v[208:211], v[20:23]
	v_mfma_f32_16x16x32_bf16 v[16:19], v[180:183], v[208:211], v[16:19]
	v_mfma_f32_16x16x32_bf16 v[4:7], v[172:175], v[216:219], v[4:7]
	v_mfma_f32_16x16x32_bf16 v[0:3], v[180:183], v[216:219], v[0:3]
	v_mfma_f32_16x16x32_bf16 v[52:55], v[176:179], v[192:195], v[52:55]
	v_mfma_f32_16x16x32_bf16 v[48:51], v[184:187], v[192:195], v[48:51]
	v_mfma_f32_16x16x32_bf16 v[36:39], v[176:179], v[204:207], v[36:39]
	v_mfma_f32_16x16x32_bf16 v[32:35], v[184:187], v[204:207], v[32:35]
	v_mfma_f32_16x16x32_bf16 v[20:23], v[176:179], v[212:215], v[20:23]
	v_mfma_f32_16x16x32_bf16 v[16:19], v[184:187], v[212:215], v[16:19]
	v_mfma_f32_16x16x32_bf16 v[4:7], v[176:179], v[220:223], v[4:7]
	v_mfma_f32_16x16x32_bf16 v[0:3], v[184:187], v[220:223], v[0:3]
	s_setprio 0
	s_barrier
	s_add_i32 s64, 0, 0x18000
	v_add_u32_e32 v136, s64, v159
	s_add_i32 s65, 0, 0x1c000
	ds_read_b128 v[142:145], v136
	ds_read_b128 v[146:149], v136 offset:1024
	ds_read_b128 v[164:167], v136 offset:2048
	ds_read_b128 v[168:171], v136 offset:3072
	v_add_u32_e32 v136, s65, v159
	ds_read_b128 v[172:175], v136
	ds_read_b128 v[176:179], v136 offset:1024
	ds_read_b128 v[180:183], v136 offset:2048
	ds_read_b128 v[184:187], v136 offset:3072
	s_add_u32 s24, s24, 0x40000
	s_addc_u32 s25, s25, 0
	s_mov_b32 m0, s40
	v_lshl_add_u64 v[230:231], s[24:25], 0, v[134:135]
	ds_read_b128 v[188:191], v163 offset:32768
	ds_read_b128 v[192:195], v163 offset:33792
	ds_read_b128 v[200:203], v163 offset:34816
	ds_read_b128 v[204:207], v163 offset:35840
	ds_read_b128 v[208:211], v163 offset:36864
	ds_read_b128 v[212:215], v163 offset:37888
	ds_read_b128 v[216:219], v163 offset:38912
	ds_read_b128 v[220:223], v163 offset:39936
	global_load_lds_dwordx4 v[230:231], off
	v_lshl_add_u64 v[230:231], s[24:25], 0, v[130:131]
	s_mov_b32 m0, s41
	s_nop 0
	global_load_lds_dwordx4 v[230:231], off
	s_waitcnt vmcnt(8)
	s_waitcnt lgkmcnt(0)
	s_barrier
	s_setprio 1
	v_mfma_f32_16x16x32_bf16 v[124:127], v[142:145], v[188:191], v[124:127]
	v_mfma_f32_16x16x32_bf16 v[120:123], v[164:167], v[188:191], v[120:123]
	v_mfma_f32_16x16x32_bf16 v[108:111], v[142:145], v[200:203], v[108:111]
	v_mfma_f32_16x16x32_bf16 v[104:107], v[164:167], v[200:203], v[104:107]
	v_mfma_f32_16x16x32_bf16 v[92:95], v[142:145], v[208:211], v[92:95]
	v_mfma_f32_16x16x32_bf16 v[88:91], v[164:167], v[208:211], v[88:91]
	v_mfma_f32_16x16x32_bf16 v[76:79], v[142:145], v[216:219], v[76:79]
	v_mfma_f32_16x16x32_bf16 v[72:75], v[164:167], v[216:219], v[72:75]
	v_mfma_f32_16x16x32_bf16 v[124:127], v[146:149], v[192:195], v[124:127]
	v_mfma_f32_16x16x32_bf16 v[120:123], v[168:171], v[192:195], v[120:123]
	v_mfma_f32_16x16x32_bf16 v[108:111], v[146:149], v[204:207], v[108:111]
	v_mfma_f32_16x16x32_bf16 v[104:107], v[168:171], v[204:207], v[104:107]
	v_mfma_f32_16x16x32_bf16 v[92:95], v[146:149], v[212:215], v[92:95]
	v_mfma_f32_16x16x32_bf16 v[88:91], v[168:171], v[212:215], v[88:91]
	v_mfma_f32_16x16x32_bf16 v[76:79], v[146:149], v[220:223], v[76:79]
	v_mfma_f32_16x16x32_bf16 v[72:75], v[168:171], v[220:223], v[72:75]
	v_mfma_f32_16x16x32_bf16 v[116:119], v[172:175], v[188:191], v[116:119]
	v_mfma_f32_16x16x32_bf16 v[112:115], v[180:183], v[188:191], v[112:115]
	v_mfma_f32_16x16x32_bf16 v[100:103], v[172:175], v[200:203], v[100:103]
	v_mfma_f32_16x16x32_bf16 v[96:99], v[180:183], v[200:203], v[96:99]
	v_mfma_f32_16x16x32_bf16 v[84:87], v[172:175], v[208:211], v[84:87]
	v_mfma_f32_16x16x32_bf16 v[80:83], v[180:183], v[208:211], v[80:83]
	v_mfma_f32_16x16x32_bf16 v[68:71], v[172:175], v[216:219], v[68:71]
	v_mfma_f32_16x16x32_bf16 v[64:67], v[180:183], v[216:219], v[64:67]
	v_mfma_f32_16x16x32_bf16 v[116:119], v[176:179], v[192:195], v[116:119]
	v_mfma_f32_16x16x32_bf16 v[112:115], v[184:187], v[192:195], v[112:115]
	v_mfma_f32_16x16x32_bf16 v[100:103], v[176:179], v[204:207], v[100:103]
	v_mfma_f32_16x16x32_bf16 v[96:99], v[184:187], v[204:207], v[96:99]
	v_mfma_f32_16x16x32_bf16 v[84:87], v[176:179], v[212:215], v[84:87]
	v_mfma_f32_16x16x32_bf16 v[80:83], v[184:187], v[212:215], v[80:83]
	v_mfma_f32_16x16x32_bf16 v[68:71], v[176:179], v[220:223], v[68:71]
	v_mfma_f32_16x16x32_bf16 v[64:67], v[184:187], v[220:223], v[64:67]
	s_setprio 0
	s_barrier
	s_add_i32 s24, s64, s28
	v_lshl_add_u64 v[196:197], v[196:197], 0, s[8:9]
	s_mov_b32 m0, s24
	ds_read_b128 v[188:191], v163 offset:49152
	ds_read_b128 v[192:195], v163 offset:50176
	ds_read_b128 v[200:203], v163 offset:51200
	ds_read_b128 v[204:207], v163 offset:52224
	ds_read_b128 v[208:211], v163 offset:53248
	ds_read_b128 v[212:215], v163 offset:54272
	ds_read_b128 v[216:219], v163 offset:55296
	ds_read_b128 v[220:223], v163 offset:56320
	global_load_lds_dwordx4 v[196:197], off
	s_add_i32 m0, s24, 0x2000
	s_add_u32 s22, s22, 0x40080
	v_lshl_add_u64 v[196:197], v[224:225], 0, s[8:9]
	s_addc_u32 s23, s23, 0
	s_add_i32 s24, s65, s28
	global_load_lds_dwordx4 v[196:197], off
	v_lshl_add_u64 v[196:197], s[22:23], 0, v[132:133]
	s_mov_b32 m0, s24
	s_nop 0
	global_load_lds_dwordx4 v[196:197], off
	v_lshl_add_u64 v[196:197], s[22:23], 0, v[128:129]
	s_add_i32 m0, s24, 0x2000
	s_nop 0
	global_load_lds_dwordx4 v[196:197], off
	v_lshl_add_u64 v[196:197], v[226:227], 0, s[8:9]
	s_mov_b32 m0, s43
	s_nop 0
	global_load_lds_dwordx4 v[196:197], off
	v_lshl_add_u64 v[196:197], v[228:229], 0, s[8:9]
	s_mov_b32 m0, s44
	s_nop 0
	global_load_lds_dwordx4 v[196:197], off
	s_waitcnt vmcnt(8)
	s_waitcnt lgkmcnt(0)
	s_barrier
	s_setprio 1
	v_mfma_f32_16x16x32_bf16 v[60:63], v[142:145], v[188:191], v[60:63]
	v_mfma_f32_16x16x32_bf16 v[56:59], v[164:167], v[188:191], v[56:59]
	v_mfma_f32_16x16x32_bf16 v[44:47], v[142:145], v[200:203], v[44:47]
	v_mfma_f32_16x16x32_bf16 v[40:43], v[164:167], v[200:203], v[40:43]
	v_mfma_f32_16x16x32_bf16 v[28:31], v[142:145], v[208:211], v[28:31]
	v_mfma_f32_16x16x32_bf16 v[24:27], v[164:167], v[208:211], v[24:27]
	v_mfma_f32_16x16x32_bf16 v[12:15], v[142:145], v[216:219], v[12:15]
	v_mfma_f32_16x16x32_bf16 v[8:11], v[164:167], v[216:219], v[8:11]
	v_mfma_f32_16x16x32_bf16 v[60:63], v[146:149], v[192:195], v[60:63]
	v_mfma_f32_16x16x32_bf16 v[56:59], v[168:171], v[192:195], v[56:59]
	v_mfma_f32_16x16x32_bf16 v[44:47], v[146:149], v[204:207], v[44:47]
	v_mfma_f32_16x16x32_bf16 v[40:43], v[168:171], v[204:207], v[40:43]
	v_mfma_f32_16x16x32_bf16 v[28:31], v[146:149], v[212:215], v[28:31]
	v_mfma_f32_16x16x32_bf16 v[24:27], v[168:171], v[212:215], v[24:27]
	v_mfma_f32_16x16x32_bf16 v[12:15], v[146:149], v[220:223], v[12:15]
	v_mfma_f32_16x16x32_bf16 v[8:11], v[168:171], v[220:223], v[8:11]
	v_mfma_f32_16x16x32_bf16 v[52:55], v[172:175], v[188:191], v[52:55]
	v_mfma_f32_16x16x32_bf16 v[48:51], v[180:183], v[188:191], v[48:51]
	v_mfma_f32_16x16x32_bf16 v[36:39], v[172:175], v[200:203], v[36:39]
	v_mfma_f32_16x16x32_bf16 v[32:35], v[180:183], v[200:203], v[32:35]
	v_mfma_f32_16x16x32_bf16 v[20:23], v[172:175], v[208:211], v[20:23]
	v_mfma_f32_16x16x32_bf16 v[16:19], v[180:183], v[208:211], v[16:19]
	v_mfma_f32_16x16x32_bf16 v[4:7], v[172:175], v[216:219], v[4:7]
	v_mfma_f32_16x16x32_bf16 v[0:3], v[180:183], v[216:219], v[0:3]
	v_mfma_f32_16x16x32_bf16 v[52:55], v[176:179], v[192:195], v[52:55]
	v_mfma_f32_16x16x32_bf16 v[48:51], v[184:187], v[192:195], v[48:51]
	v_mfma_f32_16x16x32_bf16 v[36:39], v[176:179], v[204:207], v[36:39]
	v_mfma_f32_16x16x32_bf16 v[32:35], v[184:187], v[204:207], v[32:35]
	v_mfma_f32_16x16x32_bf16 v[20:23], v[176:179], v[212:215], v[20:23]
	v_mfma_f32_16x16x32_bf16 v[16:19], v[184:187], v[212:215], v[16:19]
	v_mfma_f32_16x16x32_bf16 v[4:7], v[176:179], v[220:223], v[4:7]
	v_mfma_f32_16x16x32_bf16 v[0:3], v[184:187], v[220:223], v[0:3]
	s_setprio 0
	s_barrier
	s_add_i32 s63, s63, 2
	s_add_u32 s20, s20, 0x100
	s_addc_u32 s21, s21, 0
	s_add_u32 s61, s61, 0x100
	s_addc_u32 s62, s62, 0
	s_cmp_gt_u32 s63, 13
	s_cbranch_scc0 .LBB11_221
	s_and_b64 vcc, exec, s[10:11]
	s_cbranch_vccz .LBB11_224
	s_barrier

.LBB11_926:
	s_add_u32 s0, s22, 0xfffc0080
	s_addc_u32 s1, s23, -1
	s_add_i32 s48, 0, 0x10000
	s_cmp_eq_u32 s57, 12
	s_cselect_b32 s27, s8, s1
	s_cselect_b32 s26, s9, s0
	s_cselect_b32 s25, s40, s56
	s_cselect_b32 s24, s46, s47
	s_add_i32 s49, 0, 0x14000
	v_add_u32_e32 v152, s48, v159
	v_add_u32_e32 v156, s49, v159
	ds_read_b128 v[130:133], v152
	ds_read_b128 v[134:137], v152 offset:1024
	ds_read_b128 v[148:151], v152 offset:2048
	ds_read_b128 v[152:155], v152 offset:3072
	ds_read_b128 v[162:165], v156
	ds_read_b128 v[166:169], v156 offset:1024
	ds_read_b128 v[170:173], v156 offset:2048
	ds_read_b128 v[174:177], v156 offset:3072
	v_lshl_add_u64 v[156:157], s[22:23], 0, v[144:145]
	s_add_i32 m0, s35, 0xc000
	ds_read_b128 v[178:181], v161
	ds_read_b128 v[190:193], v161 offset:1024
	ds_read_b128 v[194:197], v161 offset:2048
	ds_read_b128 v[214:217], v161 offset:3072
	ds_read_b128 v[218:221], v161 offset:4096
	ds_read_b128 v[222:225], v161 offset:5120
	ds_read_b128 v[226:229], v161 offset:6144
	ds_read_b128 v[230:233], v161 offset:7168
	global_load_lds_dwordx4 v[156:157], off
	v_lshl_add_u64 v[156:157], s[22:23], 0, v[146:147]
	s_add_i32 m0, s35, 0xe000
	s_nop 0
	global_load_lds_dwordx4 v[156:157], off
	s_waitcnt vmcnt(8)
	s_waitcnt lgkmcnt(0)
	s_barrier
	s_setprio 1
	v_mfma_f32_16x16x32_bf16 v[126:129], v[130:133], v[178:181], v[126:129]
	v_mfma_f32_16x16x32_bf16 v[114:117], v[148:151], v[178:181], v[114:117]
	v_mfma_f32_16x16x32_bf16 v[110:113], v[130:133], v[194:197], v[110:113]
	v_mfma_f32_16x16x32_bf16 v[98:101], v[148:151], v[194:197], v[98:101]
	v_mfma_f32_16x16x32_bf16 v[94:97], v[130:133], v[218:221], v[94:97]
	v_mfma_f32_16x16x32_bf16 v[82:85], v[148:151], v[218:221], v[82:85]
	v_mfma_f32_16x16x32_bf16 v[78:81], v[130:133], v[226:229], v[78:81]
	v_mfma_f32_16x16x32_bf16 v[66:69], v[148:151], v[226:229], v[66:69]
	v_mfma_f32_16x16x32_bf16 v[126:129], v[134:137], v[190:193], v[126:129]
	v_mfma_f32_16x16x32_bf16 v[114:117], v[152:155], v[190:193], v[114:117]
	v_mfma_f32_16x16x32_bf16 v[110:113], v[134:137], v[214:217], v[110:113]
	v_mfma_f32_16x16x32_bf16 v[98:101], v[152:155], v[214:217], v[98:101]
	v_mfma_f32_16x16x32_bf16 v[94:97], v[134:137], v[222:225], v[94:97]
	v_mfma_f32_16x16x32_bf16 v[82:85], v[152:155], v[222:225], v[82:85]
	v_mfma_f32_16x16x32_bf16 v[78:81], v[134:137], v[230:233], v[78:81]
	v_mfma_f32_16x16x32_bf16 v[66:69], v[152:155], v[230:233], v[66:69]
	v_mfma_f32_16x16x32_bf16 v[122:125], v[162:165], v[178:181], v[122:125]
	v_mfma_f32_16x16x32_bf16 v[118:121], v[170:173], v[178:181], v[118:121]
	v_mfma_f32_16x16x32_bf16 v[106:109], v[162:165], v[194:197], v[106:109]
	v_mfma_f32_16x16x32_bf16 v[102:105], v[170:173], v[194:197], v[102:105]
	v_mfma_f32_16x16x32_bf16 v[90:93], v[162:165], v[218:221], v[90:93]
	v_mfma_f32_16x16x32_bf16 v[86:89], v[170:173], v[218:221], v[86:89]
	v_mfma_f32_16x16x32_bf16 v[74:77], v[162:165], v[226:229], v[74:77]
	v_mfma_f32_16x16x32_bf16 v[70:73], v[170:173], v[226:229], v[70:73]
	v_mfma_f32_16x16x32_bf16 v[122:125], v[166:169], v[190:193], v[122:125]
	v_mfma_f32_16x16x32_bf16 v[118:121], v[174:177], v[190:193], v[118:121]
	v_mfma_f32_16x16x32_bf16 v[106:109], v[166:169], v[214:217], v[106:109]
	v_mfma_f32_16x16x32_bf16 v[102:105], v[174:177], v[214:217], v[102:105]
	v_mfma_f32_16x16x32_bf16 v[90:93], v[166:169], v[222:225], v[90:93]
	v_mfma_f32_16x16x32_bf16 v[86:89], v[174:177], v[222:225], v[86:89]
	v_mfma_f32_16x16x32_bf16 v[74:77], v[166:169], v[230:233], v[74:77]
	v_mfma_f32_16x16x32_bf16 v[70:73], v[174:177], v[230:233], v[70:73]
	s_setprio 0
	s_barrier
	s_add_i32 s0, s48, s34
	v_lshl_add_u64 v[156:157], s[24:25], 0, v[0:1]
	s_mov_b32 m0, s0
	ds_read_b128 v[178:181], v161 offset:16384
	ds_read_b128 v[190:193], v161 offset:17408
	ds_read_b128 v[194:197], v161 offset:18432
	ds_read_b128 v[214:217], v161 offset:19456
	ds_read_b128 v[218:221], v161 offset:20480
	ds_read_b128 v[222:225], v161 offset:21504
	ds_read_b128 v[226:229], v161 offset:22528
	ds_read_b128 v[230:233], v161 offset:23552
	global_load_lds_dwordx4 v[156:157], off
	s_add_i32 m0, s0, 0x2000
	s_add_u32 s0, s24, 0x40000
	v_lshl_add_u64 v[182:183], s[24:25], 0, v[138:139]
	s_addc_u32 s1, s25, 0
	s_add_i32 s48, s49, s34
	global_load_lds_dwordx4 v[182:183], off
	v_lshl_add_u64 v[234:235], s[0:1], 0, v[0:1]
	s_mov_b32 m0, s48
	v_lshl_add_u64 v[236:237], s[26:27], 0, v[140:141]
	global_load_lds_dwordx4 v[234:235], off
	v_lshl_add_u64 v[234:235], s[0:1], 0, v[138:139]
	s_add_i32 m0, s48, 0x2000
	s_nop 0
	global_load_lds_dwordx4 v[234:235], off
	v_lshl_add_u64 v[234:235], s[26:27], 0, v[142:143]
	s_mov_b32 m0, s35
	s_nop 0
	global_load_lds_dwordx4 v[234:235], off
	s_mov_b32 m0, s36
	s_nop 0
	global_load_lds_dwordx4 v[236:237], off
	s_waitcnt vmcnt(8)
	s_waitcnt lgkmcnt(0)
	s_barrier
	s_setprio 1
	v_mfma_f32_16x16x32_bf16 v[62:65], v[130:133], v[178:181], v[62:65]
	v_mfma_f32_16x16x32_bf16 v[50:53], v[148:151], v[178:181], v[50:53]
	v_mfma_f32_16x16x32_bf16 v[46:49], v[130:133], v[194:197], v[46:49]
	v_mfma_f32_16x16x32_bf16 v[38:41], v[148:151], v[194:197], v[38:41]
	v_mfma_f32_16x16x32_bf16 v[30:33], v[130:133], v[218:221], v[30:33]
	v_mfma_f32_16x16x32_bf16 v[22:25], v[148:151], v[218:221], v[22:25]
	v_mfma_f32_16x16x32_bf16 v[14:17], v[130:133], v[226:229], v[14:17]
	v_mfma_f32_16x16x32_bf16 v[6:9], v[148:151], v[226:229], v[6:9]
	v_mfma_f32_16x16x32_bf16 v[62:65], v[134:137], v[190:193], v[62:65]
	v_mfma_f32_16x16x32_bf16 v[50:53], v[152:155], v[190:193], v[50:53]
	v_mfma_f32_16x16x32_bf16 v[46:49], v[134:137], v[214:217], v[46:49]
	v_mfma_f32_16x16x32_bf16 v[38:41], v[152:155], v[214:217], v[38:41]
	v_mfma_f32_16x16x32_bf16 v[30:33], v[134:137], v[222:225], v[30:33]
	v_mfma_f32_16x16x32_bf16 v[22:25], v[152:155], v[222:225], v[22:25]
	v_mfma_f32_16x16x32_bf16 v[14:17], v[134:137], v[230:233], v[14:17]
	v_mfma_f32_16x16x32_bf16 v[6:9], v[152:155], v[230:233], v[6:9]
	v_mfma_f32_16x16x32_bf16 v[58:61], v[162:165], v[178:181], v[58:61]
	v_mfma_f32_16x16x32_bf16 v[54:57], v[170:173], v[178:181], v[54:57]
	v_mfma_f32_16x16x32_bf16 v[42:45], v[162:165], v[194:197], v[42:45]
	v_mfma_f32_16x16x32_bf16 v[34:37], v[170:173], v[194:197], v[34:37]
	v_mfma_f32_16x16x32_bf16 v[26:29], v[162:165], v[218:221], v[26:29]
	v_mfma_f32_16x16x32_bf16 v[18:21], v[170:173], v[218:221], v[18:21]
	v_mfma_f32_16x16x32_bf16 v[10:13], v[162:165], v[226:229], v[10:13]
	v_mfma_f32_16x16x32_bf16 v[2:5], v[170:173], v[226:229], v[2:5]
	v_mfma_f32_16x16x32_bf16 v[58:61], v[166:169], v[190:193], v[58:61]
	v_mfma_f32_16x16x32_bf16 v[54:57], v[174:177], v[190:193], v[54:57]
	v_mfma_f32_16x16x32_bf16 v[42:45], v[166:169], v[214:217], v[42:45]
	v_mfma_f32_16x16x32_bf16 v[34:37], v[174:177], v[214:217], v[34:37]
	v_mfma_f32_16x16x32_bf16 v[26:29], v[166:169], v[222:225], v[26:29]
	v_mfma_f32_16x16x32_bf16 v[18:21], v[174:177], v[222:225], v[18:21]
	v_mfma_f32_16x16x32_bf16 v[10:13], v[166:169], v[230:233], v[10:13]
	v_mfma_f32_16x16x32_bf16 v[2:5], v[174:177], v[230:233], v[2:5]
	s_setprio 0
	s_barrier
	s_add_i32 s48, 0, 0x18000
	s_add_i32 s49, 0, 0x1c000
	v_add_u32_e32 v152, s48, v159
	v_add_u32_e32 v174, s49, v159
	ds_read_b128 v[130:133], v152
	ds_read_b128 v[134:137], v152 offset:1024
	ds_read_b128 v[148:151], v152 offset:2048
	ds_read_b128 v[152:155], v152 offset:3072
	ds_read_b128 v[162:165], v174
	ds_read_b128 v[166:169], v174 offset:1024
	ds_read_b128 v[170:173], v174 offset:2048
	ds_read_b128 v[174:177], v174 offset:3072
	s_add_u32 s0, s26, 0x40000
	s_addc_u32 s1, s27, 0
	s_mov_b32 m0, s37
	v_lshl_add_u64 v[238:239], s[0:1], 0, v[142:143]
	ds_read_b128 v[178:181], v161 offset:32768
	ds_read_b128 v[190:193], v161 offset:33792
	ds_read_b128 v[194:197], v161 offset:34816
	ds_read_b128 v[214:217], v161 offset:35840
	ds_read_b128 v[218:221], v161 offset:36864
	ds_read_b128 v[222:225], v161 offset:37888
	ds_read_b128 v[226:229], v161 offset:38912
	ds_read_b128 v[230:233], v161 offset:39936
	global_load_lds_dwordx4 v[238:239], off
	v_lshl_add_u64 v[238:239], s[0:1], 0, v[140:141]
	s_mov_b32 m0, s38
	s_nop 0
	global_load_lds_dwordx4 v[238:239], off
	s_waitcnt vmcnt(8)
	s_waitcnt lgkmcnt(0)
	s_barrier
	s_setprio 1
	v_mfma_f32_16x16x32_bf16 v[126:129], v[130:133], v[178:181], v[126:129]
	v_mfma_f32_16x16x32_bf16 v[114:117], v[148:151], v[178:181], v[114:117]
	v_mfma_f32_16x16x32_bf16 v[110:113], v[130:133], v[194:197], v[110:113]
	v_mfma_f32_16x16x32_bf16 v[98:101], v[148:151], v[194:197], v[98:101]
	v_mfma_f32_16x16x32_bf16 v[94:97], v[130:133], v[218:221], v[94:97]
	v_mfma_f32_16x16x32_bf16 v[82:85], v[148:151], v[218:221], v[82:85]
	v_mfma_f32_16x16x32_bf16 v[78:81], v[130:133], v[226:229], v[78:81]
	v_mfma_f32_16x16x32_bf16 v[66:69], v[148:151], v[226:229], v[66:69]
	v_mfma_f32_16x16x32_bf16 v[126:129], v[134:137], v[190:193], v[126:129]
	v_mfma_f32_16x16x32_bf16 v[114:117], v[152:155], v[190:193], v[114:117]
	v_mfma_f32_16x16x32_bf16 v[110:113], v[134:137], v[214:217], v[110:113]
	v_mfma_f32_16x16x32_bf16 v[98:101], v[152:155], v[214:217], v[98:101]
	v_mfma_f32_16x16x32_bf16 v[94:97], v[134:137], v[222:225], v[94:97]
	v_mfma_f32_16x16x32_bf16 v[82:85], v[152:155], v[222:225], v[82:85]
	v_mfma_f32_16x16x32_bf16 v[78:81], v[134:137], v[230:233], v[78:81]
	v_mfma_f32_16x16x32_bf16 v[66:69], v[152:155], v[230:233], v[66:69]
	v_mfma_f32_16x16x32_bf16 v[122:125], v[162:165], v[178:181], v[122:125]
	v_mfma_f32_16x16x32_bf16 v[118:121], v[170:173], v[178:181], v[118:121]
	v_mfma_f32_16x16x32_bf16 v[106:109], v[162:165], v[194:197], v[106:109]
	v_mfma_f32_16x16x32_bf16 v[102:105], v[170:173], v[194:197], v[102:105]
	v_mfma_f32_16x16x32_bf16 v[90:93], v[162:165], v[218:221], v[90:93]
	v_mfma_f32_16x16x32_bf16 v[86:89], v[170:173], v[218:221], v[86:89]
	v_mfma_f32_16x16x32_bf16 v[74:77], v[162:165], v[226:229], v[74:77]
	v_mfma_f32_16x16x32_bf16 v[70:73], v[170:173], v[226:229], v[70:73]
	v_mfma_f32_16x16x32_bf16 v[122:125], v[166:169], v[190:193], v[122:125]
	v_mfma_f32_16x16x32_bf16 v[118:121], v[174:177], v[190:193], v[118:121]
	v_mfma_f32_16x16x32_bf16 v[106:109], v[166:169], v[214:217], v[106:109]
	v_mfma_f32_16x16x32_bf16 v[102:105], v[174:177], v[214:217], v[102:105]
	v_mfma_f32_16x16x32_bf16 v[90:93], v[166:169], v[222:225], v[90:93]
	v_mfma_f32_16x16x32_bf16 v[86:89], v[174:177], v[222:225], v[86:89]
	v_mfma_f32_16x16x32_bf16 v[74:77], v[166:169], v[230:233], v[74:77]
	v_mfma_f32_16x16x32_bf16 v[70:73], v[174:177], v[230:233], v[70:73]
	s_setprio 0
	s_barrier
	s_add_i32 s0, s48, s34
	v_lshl_add_u64 v[156:157], v[156:157], 0, s[96:97]
	s_mov_b32 m0, s0
	ds_read_b128 v[178:181], v161 offset:49152
	ds_read_b128 v[190:193], v161 offset:50176
	ds_read_b128 v[194:197], v161 offset:51200
	ds_read_b128 v[214:217], v161 offset:52224
	ds_read_b128 v[218:221], v161 offset:53248
	ds_read_b128 v[222:225], v161 offset:54272
	ds_read_b128 v[226:229], v161 offset:55296
	ds_read_b128 v[230:233], v161 offset:56320
	global_load_lds_dwordx4 v[156:157], off
	s_add_i32 m0, s0, 0x2000
	s_add_u32 s0, s24, 0x40080
	v_lshl_add_u64 v[156:157], v[182:183], 0, s[96:97]
	s_addc_u32 s1, s25, 0
	s_add_i32 s24, s49, s34
	global_load_lds_dwordx4 v[156:157], off
	v_lshl_add_u64 v[156:157], s[0:1], 0, v[0:1]
	s_mov_b32 m0, s24
	s_nop 0
	global_load_lds_dwordx4 v[156:157], off
	v_lshl_add_u64 v[156:157], s[0:1], 0, v[138:139]
	s_add_i32 m0, s24, 0x2000
	s_nop 0
	global_load_lds_dwordx4 v[156:157], off
	v_lshl_add_u64 v[156:157], v[234:235], 0, s[96:97]
	s_mov_b32 m0, s39
	s_nop 0
	global_load_lds_dwordx4 v[156:157], off
	v_lshl_add_u64 v[156:157], v[236:237], 0, s[96:97]
	s_mov_b32 m0, s41
	s_nop 0
	global_load_lds_dwordx4 v[156:157], off
	s_waitcnt vmcnt(8)
	s_waitcnt lgkmcnt(0)
	s_barrier
	s_setprio 1
	v_mfma_f32_16x16x32_bf16 v[62:65], v[130:133], v[178:181], v[62:65]
	v_mfma_f32_16x16x32_bf16 v[50:53], v[148:151], v[178:181], v[50:53]
	v_mfma_f32_16x16x32_bf16 v[46:49], v[130:133], v[194:197], v[46:49]
	v_mfma_f32_16x16x32_bf16 v[38:41], v[148:151], v[194:197], v[38:41]
	v_mfma_f32_16x16x32_bf16 v[30:33], v[130:133], v[218:221], v[30:33]
	v_mfma_f32_16x16x32_bf16 v[22:25], v[148:151], v[218:221], v[22:25]
	v_mfma_f32_16x16x32_bf16 v[14:17], v[130:133], v[226:229], v[14:17]
	v_mfma_f32_16x16x32_bf16 v[6:9], v[148:151], v[226:229], v[6:9]
	v_mfma_f32_16x16x32_bf16 v[62:65], v[134:137], v[190:193], v[62:65]
	v_mfma_f32_16x16x32_bf16 v[50:53], v[152:155], v[190:193], v[50:53]
	v_mfma_f32_16x16x32_bf16 v[46:49], v[134:137], v[214:217], v[46:49]
	v_mfma_f32_16x16x32_bf16 v[38:41], v[152:155], v[214:217], v[38:41]
	v_mfma_f32_16x16x32_bf16 v[30:33], v[134:137], v[222:225], v[30:33]
	v_mfma_f32_16x16x32_bf16 v[22:25], v[152:155], v[222:225], v[22:25]
	v_mfma_f32_16x16x32_bf16 v[14:17], v[134:137], v[230:233], v[14:17]
	v_mfma_f32_16x16x32_bf16 v[6:9], v[152:155], v[230:233], v[6:9]
	v_mfma_f32_16x16x32_bf16 v[58:61], v[162:165], v[178:181], v[58:61]
	v_mfma_f32_16x16x32_bf16 v[54:57], v[170:173], v[178:181], v[54:57]
	v_mfma_f32_16x16x32_bf16 v[42:45], v[162:165], v[194:197], v[42:45]
	v_mfma_f32_16x16x32_bf16 v[34:37], v[170:173], v[194:197], v[34:37]
	v_mfma_f32_16x16x32_bf16 v[26:29], v[162:165], v[218:221], v[26:29]
	v_mfma_f32_16x16x32_bf16 v[18:21], v[170:173], v[218:221], v[18:21]
	v_mfma_f32_16x16x32_bf16 v[10:13], v[162:165], v[226:229], v[10:13]
	v_mfma_f32_16x16x32_bf16 v[2:5], v[170:173], v[226:229], v[2:5]
	v_mfma_f32_16x16x32_bf16 v[58:61], v[166:169], v[190:193], v[58:61]
	v_mfma_f32_16x16x32_bf16 v[54:57], v[174:177], v[190:193], v[54:57]
	v_mfma_f32_16x16x32_bf16 v[42:45], v[166:169], v[214:217], v[42:45]
	v_mfma_f32_16x16x32_bf16 v[34:37], v[174:177], v[214:217], v[34:37]
	v_mfma_f32_16x16x32_bf16 v[26:29], v[166:169], v[222:225], v[26:29]
	v_mfma_f32_16x16x32_bf16 v[18:21], v[174:177], v[222:225], v[18:21]
	v_mfma_f32_16x16x32_bf16 v[10:13], v[166:169], v[230:233], v[10:13]
	v_mfma_f32_16x16x32_bf16 v[2:5], v[174:177], v[230:233], v[2:5]
	s_setprio 0
	s_barrier
	s_add_i32 s57, s57, 2
	s_add_u32 s22, s22, 0x100
	s_addc_u32 s23, s23, 0
	s_add_u32 s47, s47, 0x100
	s_addc_u32 s56, s56, 0
	s_cmp_gt_u32 s57, 13
	s_cbranch_scc0 .LBB11_926
	s_and_b64 vcc, exec, s[14:15]
	s_cbranch_vccz .LBB11_929
	s_barrier

.LBB11_1172:
	s_add_u32 s0, s16, 0xfffc0080
	s_addc_u32 s1, s17, -1
	s_add_i32 s48, 0, 0x10000
	s_cmp_eq_u32 vcc_hi, 12
	s_cselect_b32 s39, s9, s1
	s_cselect_b32 s38, s68, s0
	s_cselect_b32 s29, s69, vcc_lo
	s_cselect_b32 s28, s70, s71
	s_add_i32 s49, 0, 0x14000
	v_add_u32_e32 v158, s48, v146
	v_add_u32_e32 v174, s49, v146
	ds_read_b128 v[140:143], v158
	ds_read_b128 v[150:153], v158 offset:1024
	ds_read_b128 v[154:157], v158 offset:2048
	ds_read_b128 v[158:161], v158 offset:3072
	ds_read_b128 v[162:165], v174
	ds_read_b128 v[166:169], v174 offset:1024
	ds_read_b128 v[170:173], v174 offset:2048
	ds_read_b128 v[174:177], v174 offset:3072
	v_lshl_add_u64 v[182:183], s[16:17], 0, v[136:137]
	s_add_i32 m0, s46, 0xc000
	ds_read_b128 v[178:181], v149
	ds_read_b128 v[190:193], v149 offset:1024
	ds_read_b128 v[194:197], v149 offset:2048
	ds_read_b128 v[214:217], v149 offset:3072
	ds_read_b128 v[218:221], v149 offset:4096
	ds_read_b128 v[222:225], v149 offset:5120
	ds_read_b128 v[226:229], v149 offset:6144
	ds_read_b128 v[230:233], v149 offset:7168
	global_load_lds_dwordx4 v[182:183], off
	v_lshl_add_u64 v[182:183], s[16:17], 0, v[138:139]
	s_add_i32 m0, s46, 0xe000
	s_nop 0
	global_load_lds_dwordx4 v[182:183], off
	s_waitcnt vmcnt(8)
	s_waitcnt lgkmcnt(0)
	s_barrier
	s_setprio 1
	v_mfma_f32_16x16x32_bf16 v[126:129], v[140:143], v[178:181], v[126:129]
	v_mfma_f32_16x16x32_bf16 v[122:125], v[154:157], v[178:181], v[122:125]
	v_mfma_f32_16x16x32_bf16 v[110:113], v[140:143], v[194:197], v[110:113]
	v_mfma_f32_16x16x32_bf16 v[106:109], v[154:157], v[194:197], v[106:109]
	v_mfma_f32_16x16x32_bf16 v[94:97], v[140:143], v[218:221], v[94:97]
	v_mfma_f32_16x16x32_bf16 v[90:93], v[154:157], v[218:221], v[90:93]
	v_mfma_f32_16x16x32_bf16 v[78:81], v[140:143], v[226:229], v[78:81]
	v_mfma_f32_16x16x32_bf16 v[74:77], v[154:157], v[226:229], v[74:77]
	v_mfma_f32_16x16x32_bf16 v[126:129], v[150:153], v[190:193], v[126:129]
	v_mfma_f32_16x16x32_bf16 v[122:125], v[158:161], v[190:193], v[122:125]
	v_mfma_f32_16x16x32_bf16 v[110:113], v[150:153], v[214:217], v[110:113]
	v_mfma_f32_16x16x32_bf16 v[106:109], v[158:161], v[214:217], v[106:109]
	v_mfma_f32_16x16x32_bf16 v[94:97], v[150:153], v[222:225], v[94:97]
	v_mfma_f32_16x16x32_bf16 v[90:93], v[158:161], v[222:225], v[90:93]
	v_mfma_f32_16x16x32_bf16 v[78:81], v[150:153], v[230:233], v[78:81]
	v_mfma_f32_16x16x32_bf16 v[74:77], v[158:161], v[230:233], v[74:77]
	v_mfma_f32_16x16x32_bf16 v[118:121], v[162:165], v[178:181], v[118:121]
	v_mfma_f32_16x16x32_bf16 v[114:117], v[170:173], v[178:181], v[114:117]
	v_mfma_f32_16x16x32_bf16 v[102:105], v[162:165], v[194:197], v[102:105]
	v_mfma_f32_16x16x32_bf16 v[98:101], v[170:173], v[194:197], v[98:101]
	v_mfma_f32_16x16x32_bf16 v[86:89], v[162:165], v[218:221], v[86:89]
	v_mfma_f32_16x16x32_bf16 v[82:85], v[170:173], v[218:221], v[82:85]
	v_mfma_f32_16x16x32_bf16 v[70:73], v[162:165], v[226:229], v[70:73]
	v_mfma_f32_16x16x32_bf16 v[66:69], v[170:173], v[226:229], v[66:69]
	v_mfma_f32_16x16x32_bf16 v[118:121], v[166:169], v[190:193], v[118:121]
	v_mfma_f32_16x16x32_bf16 v[114:117], v[174:177], v[190:193], v[114:117]
	v_mfma_f32_16x16x32_bf16 v[102:105], v[166:169], v[214:217], v[102:105]
	v_mfma_f32_16x16x32_bf16 v[98:101], v[174:177], v[214:217], v[98:101]
	v_mfma_f32_16x16x32_bf16 v[86:89], v[166:169], v[222:225], v[86:89]
	v_mfma_f32_16x16x32_bf16 v[82:85], v[174:177], v[222:225], v[82:85]
	v_mfma_f32_16x16x32_bf16 v[70:73], v[166:169], v[230:233], v[70:73]
	v_mfma_f32_16x16x32_bf16 v[66:69], v[174:177], v[230:233], v[66:69]
	s_setprio 0
	s_barrier
	s_add_i32 s0, s48, s45
	v_lshl_add_u64 v[182:183], s[28:29], 0, v[0:1]
	s_mov_b32 m0, s0
	ds_read_b128 v[178:181], v149 offset:16384
	ds_read_b128 v[190:193], v149 offset:17408
	ds_read_b128 v[194:197], v149 offset:18432
	ds_read_b128 v[214:217], v149 offset:19456
	ds_read_b128 v[218:221], v149 offset:20480
	ds_read_b128 v[222:225], v149 offset:21504
	ds_read_b128 v[226:229], v149 offset:22528
	ds_read_b128 v[230:233], v149 offset:23552
	global_load_lds_dwordx4 v[182:183], off
	s_add_i32 m0, s0, 0x2000
	s_add_u32 s0, s28, 0x40000
	v_lshl_add_u64 v[234:235], s[28:29], 0, v[134:135]
	s_addc_u32 s1, s29, 0
	s_add_i32 s48, s49, s45
	global_load_lds_dwordx4 v[234:235], off
	v_lshl_add_u64 v[236:237], s[0:1], 0, v[0:1]
	s_mov_b32 m0, s48
	v_lshl_add_u64 v[238:239], s[38:39], 0, v[132:133]
	global_load_lds_dwordx4 v[236:237], off
	v_lshl_add_u64 v[236:237], s[0:1], 0, v[134:135]
	s_add_i32 m0, s48, 0x2000
	s_nop 0
	global_load_lds_dwordx4 v[236:237], off
	v_lshl_add_u64 v[236:237], s[38:39], 0, v[130:131]
	s_mov_b32 m0, s46
	s_nop 0
	global_load_lds_dwordx4 v[236:237], off
	s_mov_b32 m0, s47
	s_nop 0
	global_load_lds_dwordx4 v[238:239], off
	s_waitcnt vmcnt(8)
	s_waitcnt lgkmcnt(0)
	s_barrier
	s_setprio 1
	v_mfma_f32_16x16x32_bf16 v[62:65], v[140:143], v[178:181], v[62:65]
	v_mfma_f32_16x16x32_bf16 v[58:61], v[154:157], v[178:181], v[58:61]
	v_mfma_f32_16x16x32_bf16 v[46:49], v[140:143], v[194:197], v[46:49]
	v_mfma_f32_16x16x32_bf16 v[42:45], v[154:157], v[194:197], v[42:45]
	v_mfma_f32_16x16x32_bf16 v[30:33], v[140:143], v[218:221], v[30:33]
	v_mfma_f32_16x16x32_bf16 v[26:29], v[154:157], v[218:221], v[26:29]
	v_mfma_f32_16x16x32_bf16 v[14:17], v[140:143], v[226:229], v[14:17]
	v_mfma_f32_16x16x32_bf16 v[10:13], v[154:157], v[226:229], v[10:13]
	v_mfma_f32_16x16x32_bf16 v[62:65], v[150:153], v[190:193], v[62:65]
	v_mfma_f32_16x16x32_bf16 v[58:61], v[158:161], v[190:193], v[58:61]
	v_mfma_f32_16x16x32_bf16 v[46:49], v[150:153], v[214:217], v[46:49]
	v_mfma_f32_16x16x32_bf16 v[42:45], v[158:161], v[214:217], v[42:45]
	v_mfma_f32_16x16x32_bf16 v[30:33], v[150:153], v[222:225], v[30:33]
	v_mfma_f32_16x16x32_bf16 v[26:29], v[158:161], v[222:225], v[26:29]
	v_mfma_f32_16x16x32_bf16 v[14:17], v[150:153], v[230:233], v[14:17]
	v_mfma_f32_16x16x32_bf16 v[10:13], v[158:161], v[230:233], v[10:13]
	v_mfma_f32_16x16x32_bf16 v[54:57], v[162:165], v[178:181], v[54:57]
	v_mfma_f32_16x16x32_bf16 v[50:53], v[170:173], v[178:181], v[50:53]
	v_mfma_f32_16x16x32_bf16 v[38:41], v[162:165], v[194:197], v[38:41]
	v_mfma_f32_16x16x32_bf16 v[34:37], v[170:173], v[194:197], v[34:37]
	v_mfma_f32_16x16x32_bf16 v[22:25], v[162:165], v[218:221], v[22:25]
	v_mfma_f32_16x16x32_bf16 v[18:21], v[170:173], v[218:221], v[18:21]
	v_mfma_f32_16x16x32_bf16 v[6:9], v[162:165], v[226:229], v[6:9]
	v_mfma_f32_16x16x32_bf16 v[2:5], v[170:173], v[226:229], v[2:5]
	v_mfma_f32_16x16x32_bf16 v[54:57], v[166:169], v[190:193], v[54:57]
	v_mfma_f32_16x16x32_bf16 v[50:53], v[174:177], v[190:193], v[50:53]
	v_mfma_f32_16x16x32_bf16 v[38:41], v[166:169], v[214:217], v[38:41]
	v_mfma_f32_16x16x32_bf16 v[34:37], v[174:177], v[214:217], v[34:37]
	v_mfma_f32_16x16x32_bf16 v[22:25], v[166:169], v[222:225], v[22:25]
	v_mfma_f32_16x16x32_bf16 v[18:21], v[174:177], v[222:225], v[18:21]
	v_mfma_f32_16x16x32_bf16 v[6:9], v[166:169], v[230:233], v[6:9]
	v_mfma_f32_16x16x32_bf16 v[2:5], v[174:177], v[230:233], v[2:5]
	s_setprio 0
	s_barrier
	s_add_i32 s48, 0, 0x18000
	s_add_i32 s49, 0, 0x1c000
	v_add_u32_e32 v158, s48, v146
	v_add_u32_e32 v174, s49, v146
	ds_read_b128 v[140:143], v158
	ds_read_b128 v[150:153], v158 offset:1024
	ds_read_b128 v[154:157], v158 offset:2048
	ds_read_b128 v[158:161], v158 offset:3072
	ds_read_b128 v[162:165], v174
	ds_read_b128 v[166:169], v174 offset:1024
	ds_read_b128 v[170:173], v174 offset:2048
	ds_read_b128 v[174:177], v174 offset:3072
	s_add_u32 s0, s38, 0x40000
	s_addc_u32 s1, s39, 0
	s_mov_b32 m0, s56
	v_lshl_add_u64 v[240:241], s[0:1], 0, v[130:131]
	ds_read_b128 v[178:181], v149 offset:32768
	ds_read_b128 v[190:193], v149 offset:33792
	ds_read_b128 v[194:197], v149 offset:34816
	ds_read_b128 v[214:217], v149 offset:35840
	ds_read_b128 v[218:221], v149 offset:36864
	ds_read_b128 v[222:225], v149 offset:37888
	ds_read_b128 v[226:229], v149 offset:38912
	ds_read_b128 v[230:233], v149 offset:39936
	global_load_lds_dwordx4 v[240:241], off
	v_lshl_add_u64 v[240:241], s[0:1], 0, v[132:133]
	s_mov_b32 m0, s57
	s_nop 0
	global_load_lds_dwordx4 v[240:241], off
	s_waitcnt vmcnt(8)
	s_waitcnt lgkmcnt(0)
	s_barrier
	s_setprio 1
	v_mfma_f32_16x16x32_bf16 v[126:129], v[140:143], v[178:181], v[126:129]
	v_mfma_f32_16x16x32_bf16 v[122:125], v[154:157], v[178:181], v[122:125]
	v_mfma_f32_16x16x32_bf16 v[110:113], v[140:143], v[194:197], v[110:113]
	v_mfma_f32_16x16x32_bf16 v[106:109], v[154:157], v[194:197], v[106:109]
	v_mfma_f32_16x16x32_bf16 v[94:97], v[140:143], v[218:221], v[94:97]
	v_mfma_f32_16x16x32_bf16 v[90:93], v[154:157], v[218:221], v[90:93]
	v_mfma_f32_16x16x32_bf16 v[78:81], v[140:143], v[226:229], v[78:81]
	v_mfma_f32_16x16x32_bf16 v[74:77], v[154:157], v[226:229], v[74:77]
	v_mfma_f32_16x16x32_bf16 v[126:129], v[150:153], v[190:193], v[126:129]
	v_mfma_f32_16x16x32_bf16 v[122:125], v[158:161], v[190:193], v[122:125]
	v_mfma_f32_16x16x32_bf16 v[110:113], v[150:153], v[214:217], v[110:113]
	v_mfma_f32_16x16x32_bf16 v[106:109], v[158:161], v[214:217], v[106:109]
	v_mfma_f32_16x16x32_bf16 v[94:97], v[150:153], v[222:225], v[94:97]
	v_mfma_f32_16x16x32_bf16 v[90:93], v[158:161], v[222:225], v[90:93]
	v_mfma_f32_16x16x32_bf16 v[78:81], v[150:153], v[230:233], v[78:81]
	v_mfma_f32_16x16x32_bf16 v[74:77], v[158:161], v[230:233], v[74:77]
	v_mfma_f32_16x16x32_bf16 v[118:121], v[162:165], v[178:181], v[118:121]
	v_mfma_f32_16x16x32_bf16 v[114:117], v[170:173], v[178:181], v[114:117]
	v_mfma_f32_16x16x32_bf16 v[102:105], v[162:165], v[194:197], v[102:105]
	v_mfma_f32_16x16x32_bf16 v[98:101], v[170:173], v[194:197], v[98:101]
	v_mfma_f32_16x16x32_bf16 v[86:89], v[162:165], v[218:221], v[86:89]
	v_mfma_f32_16x16x32_bf16 v[82:85], v[170:173], v[218:221], v[82:85]
	v_mfma_f32_16x16x32_bf16 v[70:73], v[162:165], v[226:229], v[70:73]
	v_mfma_f32_16x16x32_bf16 v[66:69], v[170:173], v[226:229], v[66:69]
	v_mfma_f32_16x16x32_bf16 v[118:121], v[166:169], v[190:193], v[118:121]
	v_mfma_f32_16x16x32_bf16 v[114:117], v[174:177], v[190:193], v[114:117]
	v_mfma_f32_16x16x32_bf16 v[102:105], v[166:169], v[214:217], v[102:105]
	v_mfma_f32_16x16x32_bf16 v[98:101], v[174:177], v[214:217], v[98:101]
	v_mfma_f32_16x16x32_bf16 v[86:89], v[166:169], v[222:225], v[86:89]
	v_mfma_f32_16x16x32_bf16 v[82:85], v[174:177], v[222:225], v[82:85]
	v_mfma_f32_16x16x32_bf16 v[70:73], v[166:169], v[230:233], v[70:73]
	v_mfma_f32_16x16x32_bf16 v[66:69], v[174:177], v[230:233], v[66:69]
	s_setprio 0
	s_barrier
	s_add_i32 s0, s48, s45
	v_lshl_add_u64 v[182:183], v[182:183], 0, s[96:97]
	s_mov_b32 m0, s0
	ds_read_b128 v[178:181], v149 offset:49152
	ds_read_b128 v[190:193], v149 offset:50176
	ds_read_b128 v[194:197], v149 offset:51200
	ds_read_b128 v[214:217], v149 offset:52224
	ds_read_b128 v[218:221], v149 offset:53248
	ds_read_b128 v[222:225], v149 offset:54272
	ds_read_b128 v[226:229], v149 offset:55296
	ds_read_b128 v[230:233], v149 offset:56320
	global_load_lds_dwordx4 v[182:183], off
	s_add_i32 m0, s0, 0x2000
	s_add_u32 s0, s28, 0x40080
	v_lshl_add_u64 v[182:183], v[234:235], 0, s[96:97]
	s_addc_u32 s1, s29, 0
	s_add_i32 s28, s49, s45
	global_load_lds_dwordx4 v[182:183], off
	v_lshl_add_u64 v[182:183], s[0:1], 0, v[0:1]
	s_mov_b32 m0, s28
	s_nop 0
	global_load_lds_dwordx4 v[182:183], off
	v_lshl_add_u64 v[182:183], s[0:1], 0, v[134:135]
	s_add_i32 m0, s28, 0x2000
	s_nop 0
	global_load_lds_dwordx4 v[182:183], off
	v_lshl_add_u64 v[182:183], v[236:237], 0, s[96:97]
	s_mov_b32 m0, s58
	s_nop 0
	global_load_lds_dwordx4 v[182:183], off
	v_lshl_add_u64 v[182:183], v[238:239], 0, s[96:97]
	s_mov_b32 m0, s59
	s_nop 0
	global_load_lds_dwordx4 v[182:183], off
	s_waitcnt vmcnt(8)
	s_waitcnt lgkmcnt(0)
	s_barrier
	s_setprio 1
	v_mfma_f32_16x16x32_bf16 v[62:65], v[140:143], v[178:181], v[62:65]
	v_mfma_f32_16x16x32_bf16 v[58:61], v[154:157], v[178:181], v[58:61]
	v_mfma_f32_16x16x32_bf16 v[46:49], v[140:143], v[194:197], v[46:49]
	v_mfma_f32_16x16x32_bf16 v[42:45], v[154:157], v[194:197], v[42:45]
	v_mfma_f32_16x16x32_bf16 v[30:33], v[140:143], v[218:221], v[30:33]
	v_mfma_f32_16x16x32_bf16 v[26:29], v[154:157], v[218:221], v[26:29]
	v_mfma_f32_16x16x32_bf16 v[14:17], v[140:143], v[226:229], v[14:17]
	v_mfma_f32_16x16x32_bf16 v[10:13], v[154:157], v[226:229], v[10:13]
	v_mfma_f32_16x16x32_bf16 v[62:65], v[150:153], v[190:193], v[62:65]
	v_mfma_f32_16x16x32_bf16 v[58:61], v[158:161], v[190:193], v[58:61]
	v_mfma_f32_16x16x32_bf16 v[46:49], v[150:153], v[214:217], v[46:49]
	v_mfma_f32_16x16x32_bf16 v[42:45], v[158:161], v[214:217], v[42:45]
	v_mfma_f32_16x16x32_bf16 v[30:33], v[150:153], v[222:225], v[30:33]
	v_mfma_f32_16x16x32_bf16 v[26:29], v[158:161], v[222:225], v[26:29]
	v_mfma_f32_16x16x32_bf16 v[14:17], v[150:153], v[230:233], v[14:17]
	v_mfma_f32_16x16x32_bf16 v[10:13], v[158:161], v[230:233], v[10:13]
	v_mfma_f32_16x16x32_bf16 v[54:57], v[162:165], v[178:181], v[54:57]
	v_mfma_f32_16x16x32_bf16 v[50:53], v[170:173], v[178:181], v[50:53]
	v_mfma_f32_16x16x32_bf16 v[38:41], v[162:165], v[194:197], v[38:41]
	v_mfma_f32_16x16x32_bf16 v[34:37], v[170:173], v[194:197], v[34:37]
	v_mfma_f32_16x16x32_bf16 v[22:25], v[162:165], v[218:221], v[22:25]
	v_mfma_f32_16x16x32_bf16 v[18:21], v[170:173], v[218:221], v[18:21]
	v_mfma_f32_16x16x32_bf16 v[6:9], v[162:165], v[226:229], v[6:9]
	v_mfma_f32_16x16x32_bf16 v[2:5], v[170:173], v[226:229], v[2:5]
	v_mfma_f32_16x16x32_bf16 v[54:57], v[166:169], v[190:193], v[54:57]
	v_mfma_f32_16x16x32_bf16 v[50:53], v[174:177], v[190:193], v[50:53]
	v_mfma_f32_16x16x32_bf16 v[38:41], v[166:169], v[214:217], v[38:41]
	v_mfma_f32_16x16x32_bf16 v[34:37], v[174:177], v[214:217], v[34:37]
	v_mfma_f32_16x16x32_bf16 v[22:25], v[166:169], v[222:225], v[22:25]
	v_mfma_f32_16x16x32_bf16 v[18:21], v[174:177], v[222:225], v[18:21]
	v_mfma_f32_16x16x32_bf16 v[6:9], v[166:169], v[230:233], v[6:9]
	v_mfma_f32_16x16x32_bf16 v[2:5], v[174:177], v[230:233], v[2:5]
	s_setprio 0
	s_barrier
	s_add_i32 vcc_hi, vcc_hi, 2
	s_add_u32 s16, s16, 0x100
	s_addc_u32 s17, s17, 0
	s_add_u32 s71, s71, 0x100
	s_addc_u32 vcc_lo, vcc_lo, 0
	s_cmp_gt_u32 vcc_hi, 13
	s_cbranch_scc0 .LBB11_1172
	s_and_b64 vcc, exec, s[20:21]
	s_cbranch_vccz .LBB11_1175
	s_barrier

.LBB11_1629:
	s_add_u32 s0, s22, 0xfff80080
	s_addc_u32 s1, s23, -1
	s_add_i32 s48, 0, 0x10000
	s_cmp_eq_u32 s57, 28
	s_cselect_b32 s27, s8, s1
	s_cselect_b32 s26, s9, s0
	v_add_u32_e32 v148, s48, v151
	s_cselect_b32 s25, s40, s56
	s_cselect_b32 s24, s46, s47
	s_add_i32 s49, 0, 0x14000
	ds_read_b128 v[140:143], v148
	ds_read_b128 v[144:147], v148 offset:1024
	ds_read_b128 v[154:157], v148 offset:2048
	ds_read_b128 v[158:161], v148 offset:3072
	v_add_u32_e32 v148, s49, v151
	ds_read_b128 v[162:165], v148
	ds_read_b128 v[166:169], v148 offset:1024
	ds_read_b128 v[170:173], v148 offset:2048
	ds_read_b128 v[174:177], v148 offset:3072
	v_lshl_add_u64 v[148:149], s[22:23], 0, v[136:137]
	s_add_i32 m0, s35, 0xc000
	ds_read_b128 v[178:181], v153
	ds_read_b128 v[190:193], v153 offset:1024
	ds_read_b128 v[194:197], v153 offset:2048
	ds_read_b128 v[214:217], v153 offset:3072
	ds_read_b128 v[218:221], v153 offset:4096
	ds_read_b128 v[222:225], v153 offset:5120
	ds_read_b128 v[226:229], v153 offset:6144
	ds_read_b128 v[230:233], v153 offset:7168
	global_load_lds_dwordx4 v[148:149], off
	v_lshl_add_u64 v[148:149], s[22:23], 0, v[138:139]
	s_add_i32 m0, s35, 0xe000
	s_nop 0
	global_load_lds_dwordx4 v[148:149], off
	s_waitcnt vmcnt(8)
	s_waitcnt lgkmcnt(0)
	s_barrier
	s_setprio 1
	v_mfma_f32_16x16x32_bf16 v[126:129], v[140:143], v[178:181], v[126:129]
	v_mfma_f32_16x16x32_bf16 v[122:125], v[154:157], v[178:181], v[122:125]
	v_mfma_f32_16x16x32_bf16 v[110:113], v[140:143], v[194:197], v[110:113]
	v_mfma_f32_16x16x32_bf16 v[106:109], v[154:157], v[194:197], v[106:109]
	v_mfma_f32_16x16x32_bf16 v[94:97], v[140:143], v[218:221], v[94:97]
	v_mfma_f32_16x16x32_bf16 v[90:93], v[154:157], v[218:221], v[90:93]
	v_mfma_f32_16x16x32_bf16 v[78:81], v[140:143], v[226:229], v[78:81]
	v_mfma_f32_16x16x32_bf16 v[74:77], v[154:157], v[226:229], v[74:77]
	v_mfma_f32_16x16x32_bf16 v[126:129], v[144:147], v[190:193], v[126:129]
	v_mfma_f32_16x16x32_bf16 v[122:125], v[158:161], v[190:193], v[122:125]
	v_mfma_f32_16x16x32_bf16 v[110:113], v[144:147], v[214:217], v[110:113]
	v_mfma_f32_16x16x32_bf16 v[106:109], v[158:161], v[214:217], v[106:109]
	v_mfma_f32_16x16x32_bf16 v[94:97], v[144:147], v[222:225], v[94:97]
	v_mfma_f32_16x16x32_bf16 v[90:93], v[158:161], v[222:225], v[90:93]
	v_mfma_f32_16x16x32_bf16 v[78:81], v[144:147], v[230:233], v[78:81]
	v_mfma_f32_16x16x32_bf16 v[74:77], v[158:161], v[230:233], v[74:77]
	v_mfma_f32_16x16x32_bf16 v[118:121], v[162:165], v[178:181], v[118:121]
	v_mfma_f32_16x16x32_bf16 v[114:117], v[170:173], v[178:181], v[114:117]
	v_mfma_f32_16x16x32_bf16 v[102:105], v[162:165], v[194:197], v[102:105]
	v_mfma_f32_16x16x32_bf16 v[98:101], v[170:173], v[194:197], v[98:101]
	v_mfma_f32_16x16x32_bf16 v[86:89], v[162:165], v[218:221], v[86:89]
	v_mfma_f32_16x16x32_bf16 v[82:85], v[170:173], v[218:221], v[82:85]
	v_mfma_f32_16x16x32_bf16 v[70:73], v[162:165], v[226:229], v[70:73]
	v_mfma_f32_16x16x32_bf16 v[66:69], v[170:173], v[226:229], v[66:69]
	v_mfma_f32_16x16x32_bf16 v[118:121], v[166:169], v[190:193], v[118:121]
	v_mfma_f32_16x16x32_bf16 v[114:117], v[174:177], v[190:193], v[114:117]
	v_mfma_f32_16x16x32_bf16 v[102:105], v[166:169], v[214:217], v[102:105]
	v_mfma_f32_16x16x32_bf16 v[98:101], v[174:177], v[214:217], v[98:101]
	v_mfma_f32_16x16x32_bf16 v[86:89], v[166:169], v[222:225], v[86:89]
	v_mfma_f32_16x16x32_bf16 v[82:85], v[174:177], v[222:225], v[82:85]
	v_mfma_f32_16x16x32_bf16 v[70:73], v[166:169], v[230:233], v[70:73]
	v_mfma_f32_16x16x32_bf16 v[66:69], v[174:177], v[230:233], v[66:69]
	s_setprio 0
	s_barrier
	s_add_i32 s0, s48, s34
	v_lshl_add_u64 v[148:149], s[24:25], 0, v[0:1]
	s_mov_b32 m0, s0
	ds_read_b128 v[178:181], v153 offset:16384
	ds_read_b128 v[190:193], v153 offset:17408
	ds_read_b128 v[194:197], v153 offset:18432
	ds_read_b128 v[214:217], v153 offset:19456
	ds_read_b128 v[218:221], v153 offset:20480
	ds_read_b128 v[222:225], v153 offset:21504
	ds_read_b128 v[226:229], v153 offset:22528
	ds_read_b128 v[230:233], v153 offset:23552
	global_load_lds_dwordx4 v[148:149], off
	s_add_i32 m0, s0, 0x2000
	s_add_u32 s0, s24, 0x80000
	v_lshl_add_u64 v[182:183], s[24:25], 0, v[130:131]
	s_addc_u32 s1, s25, 0
	s_add_i32 s48, s49, s34
	global_load_lds_dwordx4 v[182:183], off
	v_lshl_add_u64 v[234:235], s[0:1], 0, v[0:1]
	s_mov_b32 m0, s48
	v_lshl_add_u64 v[236:237], s[26:27], 0, v[132:133]
	global_load_lds_dwordx4 v[234:235], off
	v_lshl_add_u64 v[234:235], s[0:1], 0, v[130:131]
	s_add_i32 m0, s48, 0x2000
	s_nop 0
	global_load_lds_dwordx4 v[234:235], off
	v_lshl_add_u64 v[234:235], s[26:27], 0, v[134:135]
	s_mov_b32 m0, s35
	s_nop 0
	global_load_lds_dwordx4 v[234:235], off
	s_mov_b32 m0, s36
	s_nop 0
	global_load_lds_dwordx4 v[236:237], off
	s_waitcnt vmcnt(8)
	s_waitcnt lgkmcnt(0)
	s_barrier
	s_setprio 1
	v_mfma_f32_16x16x32_bf16 v[62:65], v[140:143], v[178:181], v[62:65]
	v_mfma_f32_16x16x32_bf16 v[58:61], v[154:157], v[178:181], v[58:61]
	v_mfma_f32_16x16x32_bf16 v[46:49], v[140:143], v[194:197], v[46:49]
	v_mfma_f32_16x16x32_bf16 v[42:45], v[154:157], v[194:197], v[42:45]
	v_mfma_f32_16x16x32_bf16 v[30:33], v[140:143], v[218:221], v[30:33]
	v_mfma_f32_16x16x32_bf16 v[26:29], v[154:157], v[218:221], v[26:29]
	v_mfma_f32_16x16x32_bf16 v[14:17], v[140:143], v[226:229], v[14:17]
	v_mfma_f32_16x16x32_bf16 v[10:13], v[154:157], v[226:229], v[10:13]
	v_mfma_f32_16x16x32_bf16 v[62:65], v[144:147], v[190:193], v[62:65]
	v_mfma_f32_16x16x32_bf16 v[58:61], v[158:161], v[190:193], v[58:61]
	v_mfma_f32_16x16x32_bf16 v[46:49], v[144:147], v[214:217], v[46:49]
	v_mfma_f32_16x16x32_bf16 v[42:45], v[158:161], v[214:217], v[42:45]
	v_mfma_f32_16x16x32_bf16 v[30:33], v[144:147], v[222:225], v[30:33]
	v_mfma_f32_16x16x32_bf16 v[26:29], v[158:161], v[222:225], v[26:29]
	v_mfma_f32_16x16x32_bf16 v[14:17], v[144:147], v[230:233], v[14:17]
	v_mfma_f32_16x16x32_bf16 v[10:13], v[158:161], v[230:233], v[10:13]
	v_mfma_f32_16x16x32_bf16 v[54:57], v[162:165], v[178:181], v[54:57]
	v_mfma_f32_16x16x32_bf16 v[50:53], v[170:173], v[178:181], v[50:53]
	v_mfma_f32_16x16x32_bf16 v[38:41], v[162:165], v[194:197], v[38:41]
	v_mfma_f32_16x16x32_bf16 v[34:37], v[170:173], v[194:197], v[34:37]
	v_mfma_f32_16x16x32_bf16 v[22:25], v[162:165], v[218:221], v[22:25]
	v_mfma_f32_16x16x32_bf16 v[18:21], v[170:173], v[218:221], v[18:21]
	v_mfma_f32_16x16x32_bf16 v[6:9], v[162:165], v[226:229], v[6:9]
	v_mfma_f32_16x16x32_bf16 v[2:5], v[170:173], v[226:229], v[2:5]
	v_mfma_f32_16x16x32_bf16 v[54:57], v[166:169], v[190:193], v[54:57]
	v_mfma_f32_16x16x32_bf16 v[50:53], v[174:177], v[190:193], v[50:53]
	v_mfma_f32_16x16x32_bf16 v[38:41], v[166:169], v[214:217], v[38:41]
	v_mfma_f32_16x16x32_bf16 v[34:37], v[174:177], v[214:217], v[34:37]
	v_mfma_f32_16x16x32_bf16 v[22:25], v[166:169], v[222:225], v[22:25]
	v_mfma_f32_16x16x32_bf16 v[18:21], v[174:177], v[222:225], v[18:21]
	v_mfma_f32_16x16x32_bf16 v[6:9], v[166:169], v[230:233], v[6:9]
	v_mfma_f32_16x16x32_bf16 v[2:5], v[174:177], v[230:233], v[2:5]
	s_setprio 0
	s_barrier
	s_add_i32 s48, 0, 0x18000
	s_add_i32 s49, 0, 0x1c000
	v_add_u32_e32 v158, s48, v151
	v_add_u32_e32 v174, s49, v151
	ds_read_b128 v[140:143], v158
	ds_read_b128 v[144:147], v158 offset:1024
	ds_read_b128 v[154:157], v158 offset:2048
	ds_read_b128 v[158:161], v158 offset:3072
	ds_read_b128 v[162:165], v174
	ds_read_b128 v[166:169], v174 offset:1024
	ds_read_b128 v[170:173], v174 offset:2048
	ds_read_b128 v[174:177], v174 offset:3072
	s_add_u32 s0, s26, 0x80000
	s_addc_u32 s1, s27, 0
	s_mov_b32 m0, s37
	v_lshl_add_u64 v[238:239], s[0:1], 0, v[134:135]
	ds_read_b128 v[178:181], v153 offset:32768
	ds_read_b128 v[190:193], v153 offset:33792
	ds_read_b128 v[194:197], v153 offset:34816
	ds_read_b128 v[214:217], v153 offset:35840
	ds_read_b128 v[218:221], v153 offset:36864
	ds_read_b128 v[222:225], v153 offset:37888
	ds_read_b128 v[226:229], v153 offset:38912
	ds_read_b128 v[230:233], v153 offset:39936
	global_load_lds_dwordx4 v[238:239], off
	v_lshl_add_u64 v[238:239], s[0:1], 0, v[132:133]
	s_mov_b32 m0, s38
	s_nop 0
	global_load_lds_dwordx4 v[238:239], off
	s_waitcnt vmcnt(8)
	s_waitcnt lgkmcnt(0)
	s_barrier
	s_setprio 1
	v_mfma_f32_16x16x32_bf16 v[126:129], v[140:143], v[178:181], v[126:129]
	v_mfma_f32_16x16x32_bf16 v[122:125], v[154:157], v[178:181], v[122:125]
	v_mfma_f32_16x16x32_bf16 v[110:113], v[140:143], v[194:197], v[110:113]
	v_mfma_f32_16x16x32_bf16 v[106:109], v[154:157], v[194:197], v[106:109]
	v_mfma_f32_16x16x32_bf16 v[94:97], v[140:143], v[218:221], v[94:97]
	v_mfma_f32_16x16x32_bf16 v[90:93], v[154:157], v[218:221], v[90:93]
	v_mfma_f32_16x16x32_bf16 v[78:81], v[140:143], v[226:229], v[78:81]
	v_mfma_f32_16x16x32_bf16 v[74:77], v[154:157], v[226:229], v[74:77]
	v_mfma_f32_16x16x32_bf16 v[126:129], v[144:147], v[190:193], v[126:129]
	v_mfma_f32_16x16x32_bf16 v[122:125], v[158:161], v[190:193], v[122:125]
	v_mfma_f32_16x16x32_bf16 v[110:113], v[144:147], v[214:217], v[110:113]
	v_mfma_f32_16x16x32_bf16 v[106:109], v[158:161], v[214:217], v[106:109]
	v_mfma_f32_16x16x32_bf16 v[94:97], v[144:147], v[222:225], v[94:97]
	v_mfma_f32_16x16x32_bf16 v[90:93], v[158:161], v[222:225], v[90:93]
	v_mfma_f32_16x16x32_bf16 v[78:81], v[144:147], v[230:233], v[78:81]
	v_mfma_f32_16x16x32_bf16 v[74:77], v[158:161], v[230:233], v[74:77]
	v_mfma_f32_16x16x32_bf16 v[118:121], v[162:165], v[178:181], v[118:121]
	v_mfma_f32_16x16x32_bf16 v[114:117], v[170:173], v[178:181], v[114:117]
	v_mfma_f32_16x16x32_bf16 v[102:105], v[162:165], v[194:197], v[102:105]
	v_mfma_f32_16x16x32_bf16 v[98:101], v[170:173], v[194:197], v[98:101]
	v_mfma_f32_16x16x32_bf16 v[86:89], v[162:165], v[218:221], v[86:89]
	v_mfma_f32_16x16x32_bf16 v[82:85], v[170:173], v[218:221], v[82:85]
	v_mfma_f32_16x16x32_bf16 v[70:73], v[162:165], v[226:229], v[70:73]
	v_mfma_f32_16x16x32_bf16 v[66:69], v[170:173], v[226:229], v[66:69]
	v_mfma_f32_16x16x32_bf16 v[118:121], v[166:169], v[190:193], v[118:121]
	v_mfma_f32_16x16x32_bf16 v[114:117], v[174:177], v[190:193], v[114:117]
	v_mfma_f32_16x16x32_bf16 v[102:105], v[166:169], v[214:217], v[102:105]
	v_mfma_f32_16x16x32_bf16 v[98:101], v[174:177], v[214:217], v[98:101]
	v_mfma_f32_16x16x32_bf16 v[86:89], v[166:169], v[222:225], v[86:89]
	v_mfma_f32_16x16x32_bf16 v[82:85], v[174:177], v[222:225], v[82:85]
	v_mfma_f32_16x16x32_bf16 v[70:73], v[166:169], v[230:233], v[70:73]
	v_mfma_f32_16x16x32_bf16 v[66:69], v[174:177], v[230:233], v[66:69]
	s_setprio 0
	s_barrier
	s_add_i32 s0, s48, s34
	v_lshl_add_u64 v[148:149], v[148:149], 0, s[96:97]
	s_mov_b32 m0, s0
	ds_read_b128 v[178:181], v153 offset:49152
	ds_read_b128 v[190:193], v153 offset:50176
	ds_read_b128 v[194:197], v153 offset:51200
	ds_read_b128 v[214:217], v153 offset:52224
	ds_read_b128 v[218:221], v153 offset:53248
	ds_read_b128 v[222:225], v153 offset:54272
	ds_read_b128 v[226:229], v153 offset:55296
	ds_read_b128 v[230:233], v153 offset:56320
	global_load_lds_dwordx4 v[148:149], off
	s_add_i32 m0, s0, 0x2000
	s_add_u32 s0, s24, 0x80080
	v_lshl_add_u64 v[148:149], v[182:183], 0, s[96:97]
	s_addc_u32 s1, s25, 0
	s_add_i32 s24, s49, s34
	global_load_lds_dwordx4 v[148:149], off
	v_lshl_add_u64 v[148:149], s[0:1], 0, v[0:1]
	s_mov_b32 m0, s24
	s_nop 0
	global_load_lds_dwordx4 v[148:149], off
	v_lshl_add_u64 v[148:149], s[0:1], 0, v[130:131]
	s_add_i32 m0, s24, 0x2000
	s_nop 0
	global_load_lds_dwordx4 v[148:149], off
	v_lshl_add_u64 v[148:149], v[234:235], 0, s[96:97]
	s_mov_b32 m0, s39
	s_nop 0
	global_load_lds_dwordx4 v[148:149], off
	v_lshl_add_u64 v[148:149], v[236:237], 0, s[96:97]
	s_mov_b32 m0, s41
	s_nop 0
	global_load_lds_dwordx4 v[148:149], off
	s_waitcnt vmcnt(8)
	s_waitcnt lgkmcnt(0)
	s_barrier
	s_setprio 1
	v_mfma_f32_16x16x32_bf16 v[62:65], v[140:143], v[178:181], v[62:65]
	v_mfma_f32_16x16x32_bf16 v[58:61], v[154:157], v[178:181], v[58:61]
	v_mfma_f32_16x16x32_bf16 v[46:49], v[140:143], v[194:197], v[46:49]
	v_mfma_f32_16x16x32_bf16 v[42:45], v[154:157], v[194:197], v[42:45]
	v_mfma_f32_16x16x32_bf16 v[30:33], v[140:143], v[218:221], v[30:33]
	v_mfma_f32_16x16x32_bf16 v[26:29], v[154:157], v[218:221], v[26:29]
	v_mfma_f32_16x16x32_bf16 v[14:17], v[140:143], v[226:229], v[14:17]
	v_mfma_f32_16x16x32_bf16 v[10:13], v[154:157], v[226:229], v[10:13]
	v_mfma_f32_16x16x32_bf16 v[62:65], v[144:147], v[190:193], v[62:65]
	v_mfma_f32_16x16x32_bf16 v[58:61], v[158:161], v[190:193], v[58:61]
	v_mfma_f32_16x16x32_bf16 v[46:49], v[144:147], v[214:217], v[46:49]
	v_mfma_f32_16x16x32_bf16 v[42:45], v[158:161], v[214:217], v[42:45]
	v_mfma_f32_16x16x32_bf16 v[30:33], v[144:147], v[222:225], v[30:33]
	v_mfma_f32_16x16x32_bf16 v[26:29], v[158:161], v[222:225], v[26:29]
	v_mfma_f32_16x16x32_bf16 v[14:17], v[144:147], v[230:233], v[14:17]
	v_mfma_f32_16x16x32_bf16 v[10:13], v[158:161], v[230:233], v[10:13]
	v_mfma_f32_16x16x32_bf16 v[54:57], v[162:165], v[178:181], v[54:57]
	v_mfma_f32_16x16x32_bf16 v[50:53], v[170:173], v[178:181], v[50:53]
	v_mfma_f32_16x16x32_bf16 v[38:41], v[162:165], v[194:197], v[38:41]
	v_mfma_f32_16x16x32_bf16 v[34:37], v[170:173], v[194:197], v[34:37]
	v_mfma_f32_16x16x32_bf16 v[22:25], v[162:165], v[218:221], v[22:25]
	v_mfma_f32_16x16x32_bf16 v[18:21], v[170:173], v[218:221], v[18:21]
	v_mfma_f32_16x16x32_bf16 v[6:9], v[162:165], v[226:229], v[6:9]
	v_mfma_f32_16x16x32_bf16 v[2:5], v[170:173], v[226:229], v[2:5]
	v_mfma_f32_16x16x32_bf16 v[54:57], v[166:169], v[190:193], v[54:57]
	v_mfma_f32_16x16x32_bf16 v[50:53], v[174:177], v[190:193], v[50:53]
	v_mfma_f32_16x16x32_bf16 v[38:41], v[166:169], v[214:217], v[38:41]
	v_mfma_f32_16x16x32_bf16 v[34:37], v[174:177], v[214:217], v[34:37]
	v_mfma_f32_16x16x32_bf16 v[22:25], v[166:169], v[222:225], v[22:25]
	v_mfma_f32_16x16x32_bf16 v[18:21], v[174:177], v[222:225], v[18:21]
	v_mfma_f32_16x16x32_bf16 v[6:9], v[166:169], v[230:233], v[6:9]
	v_mfma_f32_16x16x32_bf16 v[2:5], v[174:177], v[230:233], v[2:5]
	s_setprio 0
	s_barrier
	s_add_i32 s57, s57, 2
	s_add_u32 s22, s22, 0x100
	s_addc_u32 s23, s23, 0
	s_add_u32 s47, s47, 0x100
	s_addc_u32 s56, s56, 0
	s_cmp_gt_u32 s57, 29
	s_cbranch_scc0 .LBB11_1629
	s_and_b64 vcc, exec, s[14:15]
	s_cbranch_vccz .LBB11_1632
	s_barrier

.LBB11_1869:
	s_add_u32 s0, s24, 0xfffc0080
	s_addc_u32 s1, s25, -1
	s_add_i32 s48, 0, 0x10000
	s_cmp_eq_u32 s57, 12
	s_cselect_b32 s27, s43, s1
	s_cselect_b32 s26, s44, s0
	s_cselect_b32 s11, s45, s56
	s_cselect_b32 s10, s46, s47
	s_add_i32 s49, 0, 0x14000
	v_add_u32_e32 v158, s48, v146
	v_add_u32_e32 v174, s49, v146
	ds_read_b128 v[140:143], v158
	ds_read_b128 v[150:153], v158 offset:1024
	ds_read_b128 v[154:157], v158 offset:2048
	ds_read_b128 v[158:161], v158 offset:3072
	ds_read_b128 v[162:165], v174
	ds_read_b128 v[166:169], v174 offset:1024
	ds_read_b128 v[170:173], v174 offset:2048
	ds_read_b128 v[174:177], v174 offset:3072
	v_lshl_add_u64 v[182:183], s[24:25], 0, v[136:137]
	s_add_i32 m0, s7, 0xc000
	ds_read_b128 v[178:181], v149
	ds_read_b128 v[190:193], v149 offset:1024
	ds_read_b128 v[194:197], v149 offset:2048
	ds_read_b128 v[214:217], v149 offset:3072
	ds_read_b128 v[218:221], v149 offset:4096
	ds_read_b128 v[222:225], v149 offset:5120
	ds_read_b128 v[226:229], v149 offset:6144
	ds_read_b128 v[230:233], v149 offset:7168
	global_load_lds_dwordx4 v[182:183], off
	v_lshl_add_u64 v[182:183], s[24:25], 0, v[138:139]
	s_add_i32 m0, s7, 0xe000
	s_nop 0
	global_load_lds_dwordx4 v[182:183], off
	s_waitcnt vmcnt(8)
	s_waitcnt lgkmcnt(0)
	s_barrier
	s_setprio 1
	v_mfma_f32_16x16x32_bf16 v[126:129], v[140:143], v[178:181], v[126:129]
	v_mfma_f32_16x16x32_bf16 v[122:125], v[154:157], v[178:181], v[122:125]
	v_mfma_f32_16x16x32_bf16 v[110:113], v[140:143], v[194:197], v[110:113]
	v_mfma_f32_16x16x32_bf16 v[106:109], v[154:157], v[194:197], v[106:109]
	v_mfma_f32_16x16x32_bf16 v[94:97], v[140:143], v[218:221], v[94:97]
	v_mfma_f32_16x16x32_bf16 v[90:93], v[154:157], v[218:221], v[90:93]
	v_mfma_f32_16x16x32_bf16 v[78:81], v[140:143], v[226:229], v[78:81]
	v_mfma_f32_16x16x32_bf16 v[74:77], v[154:157], v[226:229], v[74:77]
	v_mfma_f32_16x16x32_bf16 v[126:129], v[150:153], v[190:193], v[126:129]
	v_mfma_f32_16x16x32_bf16 v[122:125], v[158:161], v[190:193], v[122:125]
	v_mfma_f32_16x16x32_bf16 v[110:113], v[150:153], v[214:217], v[110:113]
	v_mfma_f32_16x16x32_bf16 v[106:109], v[158:161], v[214:217], v[106:109]
	v_mfma_f32_16x16x32_bf16 v[94:97], v[150:153], v[222:225], v[94:97]
	v_mfma_f32_16x16x32_bf16 v[90:93], v[158:161], v[222:225], v[90:93]
	v_mfma_f32_16x16x32_bf16 v[78:81], v[150:153], v[230:233], v[78:81]
	v_mfma_f32_16x16x32_bf16 v[74:77], v[158:161], v[230:233], v[74:77]
	v_mfma_f32_16x16x32_bf16 v[118:121], v[162:165], v[178:181], v[118:121]
	v_mfma_f32_16x16x32_bf16 v[114:117], v[170:173], v[178:181], v[114:117]
	v_mfma_f32_16x16x32_bf16 v[102:105], v[162:165], v[194:197], v[102:105]
	v_mfma_f32_16x16x32_bf16 v[98:101], v[170:173], v[194:197], v[98:101]
	v_mfma_f32_16x16x32_bf16 v[86:89], v[162:165], v[218:221], v[86:89]
	v_mfma_f32_16x16x32_bf16 v[82:85], v[170:173], v[218:221], v[82:85]
	v_mfma_f32_16x16x32_bf16 v[70:73], v[162:165], v[226:229], v[70:73]
	v_mfma_f32_16x16x32_bf16 v[66:69], v[170:173], v[226:229], v[66:69]
	v_mfma_f32_16x16x32_bf16 v[118:121], v[166:169], v[190:193], v[118:121]
	v_mfma_f32_16x16x32_bf16 v[114:117], v[174:177], v[190:193], v[114:117]
	v_mfma_f32_16x16x32_bf16 v[102:105], v[166:169], v[214:217], v[102:105]
	v_mfma_f32_16x16x32_bf16 v[98:101], v[174:177], v[214:217], v[98:101]
	v_mfma_f32_16x16x32_bf16 v[86:89], v[166:169], v[222:225], v[86:89]
	v_mfma_f32_16x16x32_bf16 v[82:85], v[174:177], v[222:225], v[82:85]
	v_mfma_f32_16x16x32_bf16 v[70:73], v[166:169], v[230:233], v[70:73]
	v_mfma_f32_16x16x32_bf16 v[66:69], v[174:177], v[230:233], v[66:69]
	s_setprio 0
	s_barrier
	s_add_i32 s0, s48, s6
	v_lshl_add_u64 v[182:183], s[10:11], 0, v[0:1]
	s_mov_b32 m0, s0
	ds_read_b128 v[178:181], v149 offset:16384
	ds_read_b128 v[190:193], v149 offset:17408
	ds_read_b128 v[194:197], v149 offset:18432
	ds_read_b128 v[214:217], v149 offset:19456
	ds_read_b128 v[218:221], v149 offset:20480
	ds_read_b128 v[222:225], v149 offset:21504
	ds_read_b128 v[226:229], v149 offset:22528
	ds_read_b128 v[230:233], v149 offset:23552
	global_load_lds_dwordx4 v[182:183], off
	s_add_i32 m0, s0, 0x2000
	s_add_u32 s0, s10, 0x40000
	v_lshl_add_u64 v[234:235], s[10:11], 0, v[134:135]
	s_addc_u32 s1, s11, 0
	s_add_i32 s48, s49, s6
	global_load_lds_dwordx4 v[234:235], off
	v_lshl_add_u64 v[236:237], s[0:1], 0, v[0:1]
	s_mov_b32 m0, s48
	v_lshl_add_u64 v[238:239], s[26:27], 0, v[132:133]
	global_load_lds_dwordx4 v[236:237], off
	v_lshl_add_u64 v[236:237], s[0:1], 0, v[134:135]
	s_add_i32 m0, s48, 0x2000
	s_nop 0
	global_load_lds_dwordx4 v[236:237], off
	v_lshl_add_u64 v[236:237], s[26:27], 0, v[130:131]
	s_mov_b32 m0, s7
	s_nop 0
	global_load_lds_dwordx4 v[236:237], off
	s_mov_b32 m0, s28
	s_nop 0
	global_load_lds_dwordx4 v[238:239], off
	s_waitcnt vmcnt(8)
	s_waitcnt lgkmcnt(0)
	s_barrier
	s_setprio 1
	v_mfma_f32_16x16x32_bf16 v[62:65], v[140:143], v[178:181], v[62:65]
	v_mfma_f32_16x16x32_bf16 v[58:61], v[154:157], v[178:181], v[58:61]
	v_mfma_f32_16x16x32_bf16 v[46:49], v[140:143], v[194:197], v[46:49]
	v_mfma_f32_16x16x32_bf16 v[42:45], v[154:157], v[194:197], v[42:45]
	v_mfma_f32_16x16x32_bf16 v[30:33], v[140:143], v[218:221], v[30:33]
	v_mfma_f32_16x16x32_bf16 v[26:29], v[154:157], v[218:221], v[26:29]
	v_mfma_f32_16x16x32_bf16 v[14:17], v[140:143], v[226:229], v[14:17]
	v_mfma_f32_16x16x32_bf16 v[10:13], v[154:157], v[226:229], v[10:13]
	v_mfma_f32_16x16x32_bf16 v[62:65], v[150:153], v[190:193], v[62:65]
	v_mfma_f32_16x16x32_bf16 v[58:61], v[158:161], v[190:193], v[58:61]
	v_mfma_f32_16x16x32_bf16 v[46:49], v[150:153], v[214:217], v[46:49]
	v_mfma_f32_16x16x32_bf16 v[42:45], v[158:161], v[214:217], v[42:45]
	v_mfma_f32_16x16x32_bf16 v[30:33], v[150:153], v[222:225], v[30:33]
	v_mfma_f32_16x16x32_bf16 v[26:29], v[158:161], v[222:225], v[26:29]
	v_mfma_f32_16x16x32_bf16 v[14:17], v[150:153], v[230:233], v[14:17]
	v_mfma_f32_16x16x32_bf16 v[10:13], v[158:161], v[230:233], v[10:13]
	v_mfma_f32_16x16x32_bf16 v[54:57], v[162:165], v[178:181], v[54:57]
	v_mfma_f32_16x16x32_bf16 v[50:53], v[170:173], v[178:181], v[50:53]
	v_mfma_f32_16x16x32_bf16 v[38:41], v[162:165], v[194:197], v[38:41]
	v_mfma_f32_16x16x32_bf16 v[34:37], v[170:173], v[194:197], v[34:37]
	v_mfma_f32_16x16x32_bf16 v[22:25], v[162:165], v[218:221], v[22:25]
	v_mfma_f32_16x16x32_bf16 v[18:21], v[170:173], v[218:221], v[18:21]
	v_mfma_f32_16x16x32_bf16 v[6:9], v[162:165], v[226:229], v[6:9]
	v_mfma_f32_16x16x32_bf16 v[2:5], v[170:173], v[226:229], v[2:5]
	v_mfma_f32_16x16x32_bf16 v[54:57], v[166:169], v[190:193], v[54:57]
	v_mfma_f32_16x16x32_bf16 v[50:53], v[174:177], v[190:193], v[50:53]
	v_mfma_f32_16x16x32_bf16 v[38:41], v[166:169], v[214:217], v[38:41]
	v_mfma_f32_16x16x32_bf16 v[34:37], v[174:177], v[214:217], v[34:37]
	v_mfma_f32_16x16x32_bf16 v[22:25], v[166:169], v[222:225], v[22:25]
	v_mfma_f32_16x16x32_bf16 v[18:21], v[174:177], v[222:225], v[18:21]
	v_mfma_f32_16x16x32_bf16 v[6:9], v[166:169], v[230:233], v[6:9]
	v_mfma_f32_16x16x32_bf16 v[2:5], v[174:177], v[230:233], v[2:5]
	s_setprio 0
	s_barrier
	s_add_i32 s48, 0, 0x18000
	s_add_i32 s49, 0, 0x1c000
	v_add_u32_e32 v158, s48, v146
	v_add_u32_e32 v174, s49, v146
	ds_read_b128 v[140:143], v158
	ds_read_b128 v[150:153], v158 offset:1024
	ds_read_b128 v[154:157], v158 offset:2048
	ds_read_b128 v[158:161], v158 offset:3072
	ds_read_b128 v[162:165], v174
	ds_read_b128 v[166:169], v174 offset:1024
	ds_read_b128 v[170:173], v174 offset:2048
	ds_read_b128 v[174:177], v174 offset:3072
	s_add_u32 s0, s26, 0x40000
	s_addc_u32 s1, s27, 0
	s_mov_b32 m0, s29
	v_lshl_add_u64 v[240:241], s[0:1], 0, v[130:131]
	ds_read_b128 v[178:181], v149 offset:32768
	ds_read_b128 v[190:193], v149 offset:33792
	ds_read_b128 v[194:197], v149 offset:34816
	ds_read_b128 v[214:217], v149 offset:35840
	ds_read_b128 v[218:221], v149 offset:36864
	ds_read_b128 v[222:225], v149 offset:37888
	ds_read_b128 v[226:229], v149 offset:38912
	ds_read_b128 v[230:233], v149 offset:39936
	global_load_lds_dwordx4 v[240:241], off
	v_lshl_add_u64 v[240:241], s[0:1], 0, v[132:133]
	s_mov_b32 m0, s36
	s_nop 0
	global_load_lds_dwordx4 v[240:241], off
	s_waitcnt vmcnt(8)
	s_waitcnt lgkmcnt(0)
	s_barrier
	s_setprio 1
	v_mfma_f32_16x16x32_bf16 v[126:129], v[140:143], v[178:181], v[126:129]
	v_mfma_f32_16x16x32_bf16 v[122:125], v[154:157], v[178:181], v[122:125]
	v_mfma_f32_16x16x32_bf16 v[110:113], v[140:143], v[194:197], v[110:113]
	v_mfma_f32_16x16x32_bf16 v[106:109], v[154:157], v[194:197], v[106:109]
	v_mfma_f32_16x16x32_bf16 v[94:97], v[140:143], v[218:221], v[94:97]
	v_mfma_f32_16x16x32_bf16 v[90:93], v[154:157], v[218:221], v[90:93]
	v_mfma_f32_16x16x32_bf16 v[78:81], v[140:143], v[226:229], v[78:81]
	v_mfma_f32_16x16x32_bf16 v[74:77], v[154:157], v[226:229], v[74:77]
	v_mfma_f32_16x16x32_bf16 v[126:129], v[150:153], v[190:193], v[126:129]
	v_mfma_f32_16x16x32_bf16 v[122:125], v[158:161], v[190:193], v[122:125]
	v_mfma_f32_16x16x32_bf16 v[110:113], v[150:153], v[214:217], v[110:113]
	v_mfma_f32_16x16x32_bf16 v[106:109], v[158:161], v[214:217], v[106:109]
	v_mfma_f32_16x16x32_bf16 v[94:97], v[150:153], v[222:225], v[94:97]
	v_mfma_f32_16x16x32_bf16 v[90:93], v[158:161], v[222:225], v[90:93]
	v_mfma_f32_16x16x32_bf16 v[78:81], v[150:153], v[230:233], v[78:81]
	v_mfma_f32_16x16x32_bf16 v[74:77], v[158:161], v[230:233], v[74:77]
	v_mfma_f32_16x16x32_bf16 v[118:121], v[162:165], v[178:181], v[118:121]
	v_mfma_f32_16x16x32_bf16 v[114:117], v[170:173], v[178:181], v[114:117]
	v_mfma_f32_16x16x32_bf16 v[102:105], v[162:165], v[194:197], v[102:105]
	v_mfma_f32_16x16x32_bf16 v[98:101], v[170:173], v[194:197], v[98:101]
	v_mfma_f32_16x16x32_bf16 v[86:89], v[162:165], v[218:221], v[86:89]
	v_mfma_f32_16x16x32_bf16 v[82:85], v[170:173], v[218:221], v[82:85]
	v_mfma_f32_16x16x32_bf16 v[70:73], v[162:165], v[226:229], v[70:73]
	v_mfma_f32_16x16x32_bf16 v[66:69], v[170:173], v[226:229], v[66:69]
	v_mfma_f32_16x16x32_bf16 v[118:121], v[166:169], v[190:193], v[118:121]
	v_mfma_f32_16x16x32_bf16 v[114:117], v[174:177], v[190:193], v[114:117]
	v_mfma_f32_16x16x32_bf16 v[102:105], v[166:169], v[214:217], v[102:105]
	v_mfma_f32_16x16x32_bf16 v[98:101], v[174:177], v[214:217], v[98:101]
	v_mfma_f32_16x16x32_bf16 v[86:89], v[166:169], v[222:225], v[86:89]
	v_mfma_f32_16x16x32_bf16 v[82:85], v[174:177], v[222:225], v[82:85]
	v_mfma_f32_16x16x32_bf16 v[70:73], v[166:169], v[230:233], v[70:73]
	v_mfma_f32_16x16x32_bf16 v[66:69], v[174:177], v[230:233], v[66:69]
	s_setprio 0
	s_barrier
	s_add_i32 s0, s48, s6
	v_lshl_add_u64 v[182:183], v[182:183], 0, s[96:97]
	s_mov_b32 m0, s0
	ds_read_b128 v[178:181], v149 offset:49152
	ds_read_b128 v[190:193], v149 offset:50176
	ds_read_b128 v[194:197], v149 offset:51200
	ds_read_b128 v[214:217], v149 offset:52224
	ds_read_b128 v[218:221], v149 offset:53248
	ds_read_b128 v[222:225], v149 offset:54272
	ds_read_b128 v[226:229], v149 offset:55296
	ds_read_b128 v[230:233], v149 offset:56320
	global_load_lds_dwordx4 v[182:183], off
	s_add_i32 m0, s0, 0x2000
	s_add_u32 s0, s10, 0x40080
	v_lshl_add_u64 v[182:183], v[234:235], 0, s[96:97]
	s_addc_u32 s1, s11, 0
	s_add_i32 s10, s49, s6
	global_load_lds_dwordx4 v[182:183], off
	v_lshl_add_u64 v[182:183], s[0:1], 0, v[0:1]
	s_mov_b32 m0, s10
	s_nop 0
	global_load_lds_dwordx4 v[182:183], off
	v_lshl_add_u64 v[182:183], s[0:1], 0, v[134:135]
	s_add_i32 m0, s10, 0x2000
	s_nop 0
	global_load_lds_dwordx4 v[182:183], off
	v_lshl_add_u64 v[182:183], v[236:237], 0, s[96:97]
	s_mov_b32 m0, s37
	s_nop 0
	global_load_lds_dwordx4 v[182:183], off
	v_lshl_add_u64 v[182:183], v[238:239], 0, s[96:97]
	s_mov_b32 m0, s38
	s_nop 0
	global_load_lds_dwordx4 v[182:183], off
	s_waitcnt vmcnt(8)
	s_waitcnt lgkmcnt(0)
	s_barrier
	s_setprio 1
	v_mfma_f32_16x16x32_bf16 v[62:65], v[140:143], v[178:181], v[62:65]
	v_mfma_f32_16x16x32_bf16 v[58:61], v[154:157], v[178:181], v[58:61]
	v_mfma_f32_16x16x32_bf16 v[46:49], v[140:143], v[194:197], v[46:49]
	v_mfma_f32_16x16x32_bf16 v[42:45], v[154:157], v[194:197], v[42:45]
	v_mfma_f32_16x16x32_bf16 v[30:33], v[140:143], v[218:221], v[30:33]
	v_mfma_f32_16x16x32_bf16 v[26:29], v[154:157], v[218:221], v[26:29]
	v_mfma_f32_16x16x32_bf16 v[14:17], v[140:143], v[226:229], v[14:17]
	v_mfma_f32_16x16x32_bf16 v[10:13], v[154:157], v[226:229], v[10:13]
	v_mfma_f32_16x16x32_bf16 v[62:65], v[150:153], v[190:193], v[62:65]
	v_mfma_f32_16x16x32_bf16 v[58:61], v[158:161], v[190:193], v[58:61]
	v_mfma_f32_16x16x32_bf16 v[46:49], v[150:153], v[214:217], v[46:49]
	v_mfma_f32_16x16x32_bf16 v[42:45], v[158:161], v[214:217], v[42:45]
	v_mfma_f32_16x16x32_bf16 v[30:33], v[150:153], v[222:225], v[30:33]
	v_mfma_f32_16x16x32_bf16 v[26:29], v[158:161], v[222:225], v[26:29]
	v_mfma_f32_16x16x32_bf16 v[14:17], v[150:153], v[230:233], v[14:17]
	v_mfma_f32_16x16x32_bf16 v[10:13], v[158:161], v[230:233], v[10:13]
	v_mfma_f32_16x16x32_bf16 v[54:57], v[162:165], v[178:181], v[54:57]
	v_mfma_f32_16x16x32_bf16 v[50:53], v[170:173], v[178:181], v[50:53]
	v_mfma_f32_16x16x32_bf16 v[38:41], v[162:165], v[194:197], v[38:41]
	v_mfma_f32_16x16x32_bf16 v[34:37], v[170:173], v[194:197], v[34:37]
	v_mfma_f32_16x16x32_bf16 v[22:25], v[162:165], v[218:221], v[22:25]
	v_mfma_f32_16x16x32_bf16 v[18:21], v[170:173], v[218:221], v[18:21]
	v_mfma_f32_16x16x32_bf16 v[6:9], v[162:165], v[226:229], v[6:9]
	v_mfma_f32_16x16x32_bf16 v[2:5], v[170:173], v[226:229], v[2:5]
	v_mfma_f32_16x16x32_bf16 v[54:57], v[166:169], v[190:193], v[54:57]
	v_mfma_f32_16x16x32_bf16 v[50:53], v[174:177], v[190:193], v[50:53]
	v_mfma_f32_16x16x32_bf16 v[38:41], v[166:169], v[214:217], v[38:41]
	v_mfma_f32_16x16x32_bf16 v[34:37], v[174:177], v[214:217], v[34:37]
	v_mfma_f32_16x16x32_bf16 v[22:25], v[166:169], v[222:225], v[22:25]
	v_mfma_f32_16x16x32_bf16 v[18:21], v[174:177], v[222:225], v[18:21]
	v_mfma_f32_16x16x32_bf16 v[6:9], v[166:169], v[230:233], v[6:9]
	v_mfma_f32_16x16x32_bf16 v[2:5], v[174:177], v[230:233], v[2:5]
	s_setprio 0
	s_barrier
	s_add_i32 s57, s57, 2
	s_add_u32 s24, s24, 0x100
	s_addc_u32 s25, s25, 0
	s_add_u32 s47, s47, 0x100
	s_addc_u32 s56, s56, 0
	s_cmp_gt_u32 s57, 13
	s_cbranch_scc0 .LBB11_1869
	s_and_b64 vcc, exec, s[16:17]
	s_cbranch_vccz .LBB11_1872
	s_barrier

.LBB11_2045:
	s_add_u32 s40, s26, s34
	s_addc_u32 s41, s27, s35
	s_add_u32 s36, s40, 0x100
	s_addc_u32 s37, s41, 0
	s_and_b64 s[0:1], s[10:11], exec
	s_cselect_b32 s37, s7, s37
	s_cselect_b32 s36, s8, s36
	s_add_u32 s0, s24, s34
	s_addc_u32 s1, s25, s35
	s_add_u32 s34, s0, 0x100
	s_addc_u32 s35, s1, 0
	s_add_i32 s51, 0, 0x10000
	s_and_b64 s[0:1], s[10:11], exec
	s_cselect_b32 s39, s9, s35
	s_cselect_b32 s38, s68, s34
	s_add_i32 s0, 0, 0x14000
	s_add_u32 s42, s40, 0x40080
	s_addc_u32 s43, s41, 0
	s_add_i32 vcc_hi, s51, s46
	s_add_i32 m0, s47, 0xc000
	s_add_i32 s1, s47, 0xe000
	s_add_i32 s50, vcc_hi, 0x2000
	v_add_u32_e32 v136, s51, v139
	s_add_u32 s40, s38, 0x40000
	ds_read_b128 v[142:145], v136
	ds_read_b128 v[146:149], v136 offset:1024
	ds_read_b128 v[150:153], v136 offset:2048
	ds_read_b128 v[154:157], v136 offset:3072
	v_add_u32_e32 v136, s0, v139
	s_addc_u32 s41, s39, 0
	s_add_i32 s49, s0, s46
	ds_read_b128 v[158:161], v136
	ds_read_b128 v[162:165], v136 offset:1024
	ds_read_b128 v[166:169], v136 offset:2048
	ds_read_b128 v[170:173], v136 offset:3072
	s_add_i32 s48, s49, 0x2000
	s_add_i32 vcc_lo, 0, 0x18000
	s_add_i32 s71, 0, 0x1c000
	s_add_u32 s34, s36, 0x40000
	s_addc_u32 s35, s37, 0
	s_add_i32 s70, vcc_lo, s46
	s_add_i32 s69, s70, 0x2000
	s_add_u32 s10, s38, 0x40080
	s_addc_u32 s11, s39, 0
	s_add_i32 s51, s71, s46
	s_add_i32 s0, s51, 0x2000
	v_lshl_add_u64 v[136:137], s[42:43], 0, v[134:135]
	ds_read_b128 v[174:177], v141
	ds_read_b128 v[178:181], v141 offset:1024
	ds_read_b128 v[190:193], v141 offset:2048
	ds_read_b128 v[194:197], v141 offset:3072
	ds_read_b128 v[214:217], v141 offset:4096
	ds_read_b128 v[218:221], v141 offset:5120
	ds_read_b128 v[222:225], v141 offset:6144
	ds_read_b128 v[226:229], v141 offset:7168
	global_load_lds_dwordx4 v[136:137], off
	v_lshl_add_u64 v[136:137], s[42:43], 0, v[132:133]
	s_mov_b32 m0, s1
	s_nop 0
	global_load_lds_dwordx4 v[136:137], off
	s_waitcnt vmcnt(8)
	s_waitcnt lgkmcnt(0)
	s_barrier
	s_setprio 1
	v_mfma_f32_16x16x32_bf16 v[126:129], v[142:145], v[174:177], v[126:129]
	v_mfma_f32_16x16x32_bf16 v[122:125], v[150:153], v[174:177], v[122:125]
	v_mfma_f32_16x16x32_bf16 v[110:113], v[142:145], v[190:193], v[110:113]
	v_mfma_f32_16x16x32_bf16 v[106:109], v[150:153], v[190:193], v[106:109]
	v_mfma_f32_16x16x32_bf16 v[94:97], v[142:145], v[214:217], v[94:97]
	v_mfma_f32_16x16x32_bf16 v[90:93], v[150:153], v[214:217], v[90:93]
	v_mfma_f32_16x16x32_bf16 v[78:81], v[142:145], v[222:225], v[78:81]
	v_mfma_f32_16x16x32_bf16 v[74:77], v[150:153], v[222:225], v[74:77]
	v_mfma_f32_16x16x32_bf16 v[126:129], v[146:149], v[178:181], v[126:129]
	v_mfma_f32_16x16x32_bf16 v[122:125], v[154:157], v[178:181], v[122:125]
	v_mfma_f32_16x16x32_bf16 v[110:113], v[146:149], v[194:197], v[110:113]
	v_mfma_f32_16x16x32_bf16 v[106:109], v[154:157], v[194:197], v[106:109]
	v_mfma_f32_16x16x32_bf16 v[94:97], v[146:149], v[218:221], v[94:97]
	v_mfma_f32_16x16x32_bf16 v[90:93], v[154:157], v[218:221], v[90:93]
	v_mfma_f32_16x16x32_bf16 v[78:81], v[146:149], v[226:229], v[78:81]
	v_mfma_f32_16x16x32_bf16 v[74:77], v[154:157], v[226:229], v[74:77]
	v_mfma_f32_16x16x32_bf16 v[118:121], v[158:161], v[174:177], v[118:121]
	v_mfma_f32_16x16x32_bf16 v[114:117], v[166:169], v[174:177], v[114:117]
	v_mfma_f32_16x16x32_bf16 v[102:105], v[158:161], v[190:193], v[102:105]
	v_mfma_f32_16x16x32_bf16 v[98:101], v[166:169], v[190:193], v[98:101]
	v_mfma_f32_16x16x32_bf16 v[86:89], v[158:161], v[214:217], v[86:89]
	v_mfma_f32_16x16x32_bf16 v[82:85], v[166:169], v[214:217], v[82:85]
	v_mfma_f32_16x16x32_bf16 v[70:73], v[158:161], v[222:225], v[70:73]
	v_mfma_f32_16x16x32_bf16 v[66:69], v[166:169], v[222:225], v[66:69]
	v_mfma_f32_16x16x32_bf16 v[118:121], v[162:165], v[178:181], v[118:121]
	v_mfma_f32_16x16x32_bf16 v[114:117], v[170:173], v[178:181], v[114:117]
	v_mfma_f32_16x16x32_bf16 v[102:105], v[162:165], v[194:197], v[102:105]
	v_mfma_f32_16x16x32_bf16 v[98:101], v[170:173], v[194:197], v[98:101]
	v_mfma_f32_16x16x32_bf16 v[86:89], v[162:165], v[218:221], v[86:89]
	v_mfma_f32_16x16x32_bf16 v[82:85], v[170:173], v[218:221], v[82:85]
	v_mfma_f32_16x16x32_bf16 v[70:73], v[162:165], v[226:229], v[70:73]
	v_mfma_f32_16x16x32_bf16 v[66:69], v[170:173], v[226:229], v[66:69]
	s_setprio 0
	s_barrier
	s_mov_b32 m0, vcc_hi
	v_lshl_add_u64 v[136:137], s[38:39], 0, v[0:1]
	ds_read_b128 v[174:177], v141 offset:16384
	ds_read_b128 v[178:181], v141 offset:17408
	ds_read_b128 v[190:193], v141 offset:18432
	ds_read_b128 v[194:197], v141 offset:19456
	ds_read_b128 v[214:217], v141 offset:20480
	ds_read_b128 v[218:221], v141 offset:21504
	ds_read_b128 v[222:225], v141 offset:22528
	ds_read_b128 v[226:229], v141 offset:23552
	global_load_lds_dwordx4 v[136:137], off
	v_lshl_add_u64 v[182:183], s[38:39], 0, v[130:131]
	s_mov_b32 m0, s50
	v_lshl_add_u64 v[230:231], s[40:41], 0, v[0:1]
	global_load_lds_dwordx4 v[182:183], off
	s_mov_b32 m0, s49
	v_lshl_add_u64 v[232:233], s[36:37], 0, v[132:133]
	global_load_lds_dwordx4 v[230:231], off
	v_lshl_add_u64 v[230:231], s[40:41], 0, v[130:131]
	s_mov_b32 m0, s48
	s_nop 0
	global_load_lds_dwordx4 v[230:231], off
	v_lshl_add_u64 v[230:231], s[36:37], 0, v[134:135]
	s_mov_b32 m0, s47
	s_nop 0
	global_load_lds_dwordx4 v[230:231], off
	s_mov_b32 m0, s56
	s_nop 0
	global_load_lds_dwordx4 v[232:233], off
	s_waitcnt vmcnt(8)
	s_waitcnt lgkmcnt(0)
	s_barrier
	s_setprio 1
	v_mfma_f32_16x16x32_bf16 v[62:65], v[142:145], v[174:177], v[62:65]
	v_mfma_f32_16x16x32_bf16 v[58:61], v[150:153], v[174:177], v[58:61]
	v_mfma_f32_16x16x32_bf16 v[46:49], v[142:145], v[190:193], v[46:49]
	v_mfma_f32_16x16x32_bf16 v[42:45], v[150:153], v[190:193], v[42:45]
	v_mfma_f32_16x16x32_bf16 v[30:33], v[142:145], v[214:217], v[30:33]
	v_mfma_f32_16x16x32_bf16 v[26:29], v[150:153], v[214:217], v[26:29]
	v_mfma_f32_16x16x32_bf16 v[14:17], v[142:145], v[222:225], v[14:17]
	v_mfma_f32_16x16x32_bf16 v[10:13], v[150:153], v[222:225], v[10:13]
	v_mfma_f32_16x16x32_bf16 v[62:65], v[146:149], v[178:181], v[62:65]
	v_mfma_f32_16x16x32_bf16 v[58:61], v[154:157], v[178:181], v[58:61]
	v_mfma_f32_16x16x32_bf16 v[46:49], v[146:149], v[194:197], v[46:49]
	v_mfma_f32_16x16x32_bf16 v[42:45], v[154:157], v[194:197], v[42:45]
	v_mfma_f32_16x16x32_bf16 v[30:33], v[146:149], v[218:221], v[30:33]
	v_mfma_f32_16x16x32_bf16 v[26:29], v[154:157], v[218:221], v[26:29]
	v_mfma_f32_16x16x32_bf16 v[14:17], v[146:149], v[226:229], v[14:17]
	v_mfma_f32_16x16x32_bf16 v[10:13], v[154:157], v[226:229], v[10:13]
	v_mfma_f32_16x16x32_bf16 v[54:57], v[158:161], v[174:177], v[54:57]
	v_mfma_f32_16x16x32_bf16 v[50:53], v[166:169], v[174:177], v[50:53]
	v_mfma_f32_16x16x32_bf16 v[38:41], v[158:161], v[190:193], v[38:41]
	v_mfma_f32_16x16x32_bf16 v[34:37], v[166:169], v[190:193], v[34:37]
	v_mfma_f32_16x16x32_bf16 v[22:25], v[158:161], v[214:217], v[22:25]
	v_mfma_f32_16x16x32_bf16 v[18:21], v[166:169], v[214:217], v[18:21]
	v_mfma_f32_16x16x32_bf16 v[6:9], v[158:161], v[222:225], v[6:9]
	v_mfma_f32_16x16x32_bf16 v[2:5], v[166:169], v[222:225], v[2:5]
	v_mfma_f32_16x16x32_bf16 v[54:57], v[162:165], v[178:181], v[54:57]
	v_mfma_f32_16x16x32_bf16 v[50:53], v[170:173], v[178:181], v[50:53]
	v_mfma_f32_16x16x32_bf16 v[38:41], v[162:165], v[194:197], v[38:41]
	v_mfma_f32_16x16x32_bf16 v[34:37], v[170:173], v[194:197], v[34:37]
	v_mfma_f32_16x16x32_bf16 v[22:25], v[162:165], v[218:221], v[22:25]
	v_mfma_f32_16x16x32_bf16 v[18:21], v[170:173], v[218:221], v[18:21]
	v_mfma_f32_16x16x32_bf16 v[6:9], v[162:165], v[226:229], v[6:9]
	v_mfma_f32_16x16x32_bf16 v[2:5], v[170:173], v[226:229], v[2:5]
	s_setprio 0
	s_barrier
	v_add_u32_e32 v154, vcc_lo, v139
	v_add_u32_e32 v170, s71, v139
	ds_read_b128 v[142:145], v154
	ds_read_b128 v[146:149], v154 offset:1024
	ds_read_b128 v[150:153], v154 offset:2048
	ds_read_b128 v[154:157], v154 offset:3072
	ds_read_b128 v[158:161], v170
	ds_read_b128 v[162:165], v170 offset:1024
	ds_read_b128 v[166:169], v170 offset:2048
	ds_read_b128 v[170:173], v170 offset:3072
	s_mov_b32 m0, s57
	v_lshl_add_u64 v[234:235], s[34:35], 0, v[134:135]
	ds_read_b128 v[174:177], v141 offset:32768
	ds_read_b128 v[178:181], v141 offset:33792
	ds_read_b128 v[190:193], v141 offset:34816
	ds_read_b128 v[194:197], v141 offset:35840
	ds_read_b128 v[214:217], v141 offset:36864
	ds_read_b128 v[218:221], v141 offset:37888
	ds_read_b128 v[222:225], v141 offset:38912
	ds_read_b128 v[226:229], v141 offset:39936
	global_load_lds_dwordx4 v[234:235], off
	v_lshl_add_u64 v[234:235], s[34:35], 0, v[132:133]
	s_mov_b32 m0, s58
	s_nop 0
	global_load_lds_dwordx4 v[234:235], off
	s_waitcnt vmcnt(8)
	s_waitcnt lgkmcnt(0)
	s_barrier
	s_setprio 1
	v_mfma_f32_16x16x32_bf16 v[126:129], v[142:145], v[174:177], v[126:129]
	v_mfma_f32_16x16x32_bf16 v[122:125], v[150:153], v[174:177], v[122:125]
	v_mfma_f32_16x16x32_bf16 v[110:113], v[142:145], v[190:193], v[110:113]
	v_mfma_f32_16x16x32_bf16 v[106:109], v[150:153], v[190:193], v[106:109]
	v_mfma_f32_16x16x32_bf16 v[94:97], v[142:145], v[214:217], v[94:97]
	v_mfma_f32_16x16x32_bf16 v[90:93], v[150:153], v[214:217], v[90:93]
	v_mfma_f32_16x16x32_bf16 v[78:81], v[142:145], v[222:225], v[78:81]
	v_mfma_f32_16x16x32_bf16 v[74:77], v[150:153], v[222:225], v[74:77]
	v_mfma_f32_16x16x32_bf16 v[126:129], v[146:149], v[178:181], v[126:129]
	v_mfma_f32_16x16x32_bf16 v[122:125], v[154:157], v[178:181], v[122:125]
	v_mfma_f32_16x16x32_bf16 v[110:113], v[146:149], v[194:197], v[110:113]
	v_mfma_f32_16x16x32_bf16 v[106:109], v[154:157], v[194:197], v[106:109]
	v_mfma_f32_16x16x32_bf16 v[94:97], v[146:149], v[218:221], v[94:97]
	v_mfma_f32_16x16x32_bf16 v[90:93], v[154:157], v[218:221], v[90:93]
	v_mfma_f32_16x16x32_bf16 v[78:81], v[146:149], v[226:229], v[78:81]
	v_mfma_f32_16x16x32_bf16 v[74:77], v[154:157], v[226:229], v[74:77]
	v_mfma_f32_16x16x32_bf16 v[118:121], v[158:161], v[174:177], v[118:121]
	v_mfma_f32_16x16x32_bf16 v[114:117], v[166:169], v[174:177], v[114:117]
	v_mfma_f32_16x16x32_bf16 v[102:105], v[158:161], v[190:193], v[102:105]
	v_mfma_f32_16x16x32_bf16 v[98:101], v[166:169], v[190:193], v[98:101]
	v_mfma_f32_16x16x32_bf16 v[86:89], v[158:161], v[214:217], v[86:89]
	v_mfma_f32_16x16x32_bf16 v[82:85], v[166:169], v[214:217], v[82:85]
	v_mfma_f32_16x16x32_bf16 v[70:73], v[158:161], v[222:225], v[70:73]
	v_mfma_f32_16x16x32_bf16 v[66:69], v[166:169], v[222:225], v[66:69]
	v_mfma_f32_16x16x32_bf16 v[118:121], v[162:165], v[178:181], v[118:121]
	v_mfma_f32_16x16x32_bf16 v[114:117], v[170:173], v[178:181], v[114:117]
	v_mfma_f32_16x16x32_bf16 v[102:105], v[162:165], v[194:197], v[102:105]
	v_mfma_f32_16x16x32_bf16 v[98:101], v[170:173], v[194:197], v[98:101]
	v_mfma_f32_16x16x32_bf16 v[86:89], v[162:165], v[218:221], v[86:89]
	v_mfma_f32_16x16x32_bf16 v[82:85], v[170:173], v[218:221], v[82:85]
	v_mfma_f32_16x16x32_bf16 v[70:73], v[162:165], v[226:229], v[70:73]
	v_mfma_f32_16x16x32_bf16 v[66:69], v[170:173], v[226:229], v[66:69]
	s_setprio 0
	s_barrier
	s_mov_b32 m0, s70
	v_lshl_add_u64 v[136:137], v[136:137], 0, s[96:97]
	ds_read_b128 v[174:177], v141 offset:49152
	ds_read_b128 v[178:181], v141 offset:50176
	ds_read_b128 v[190:193], v141 offset:51200
	ds_read_b128 v[194:197], v141 offset:52224
	ds_read_b128 v[214:217], v141 offset:53248
	ds_read_b128 v[218:221], v141 offset:54272
	ds_read_b128 v[222:225], v141 offset:55296
	ds_read_b128 v[226:229], v141 offset:56320
	global_load_lds_dwordx4 v[136:137], off
	v_lshl_add_u64 v[136:137], v[182:183], 0, s[96:97]
	s_mov_b32 m0, s69
	s_nop 0
	global_load_lds_dwordx4 v[136:137], off
	v_lshl_add_u64 v[136:137], s[10:11], 0, v[0:1]
	s_mov_b32 m0, s51
	s_nop 0
	global_load_lds_dwordx4 v[136:137], off
	v_lshl_add_u64 v[136:137], s[10:11], 0, v[130:131]
	s_mov_b32 m0, s0
	s_nop 0
	global_load_lds_dwordx4 v[136:137], off
	v_lshl_add_u64 v[136:137], v[230:231], 0, s[96:97]
	s_mov_b32 m0, s59
	s_nop 0
	global_load_lds_dwordx4 v[136:137], off
	v_lshl_add_u64 v[136:137], v[232:233], 0, s[96:97]
	s_mov_b32 m0, s60
	s_nop 0
	global_load_lds_dwordx4 v[136:137], off
	s_waitcnt vmcnt(8)
	s_waitcnt lgkmcnt(0)
	s_barrier
	s_setprio 1
	v_mfma_f32_16x16x32_bf16 v[62:65], v[142:145], v[174:177], v[62:65]
	v_mfma_f32_16x16x32_bf16 v[58:61], v[150:153], v[174:177], v[58:61]
	v_mfma_f32_16x16x32_bf16 v[46:49], v[142:145], v[190:193], v[46:49]
	v_mfma_f32_16x16x32_bf16 v[42:45], v[150:153], v[190:193], v[42:45]
	v_mfma_f32_16x16x32_bf16 v[30:33], v[142:145], v[214:217], v[30:33]
	v_mfma_f32_16x16x32_bf16 v[26:29], v[150:153], v[214:217], v[26:29]
	v_mfma_f32_16x16x32_bf16 v[14:17], v[142:145], v[222:225], v[14:17]
	v_mfma_f32_16x16x32_bf16 v[10:13], v[150:153], v[222:225], v[10:13]
	v_mfma_f32_16x16x32_bf16 v[62:65], v[146:149], v[178:181], v[62:65]
	v_mfma_f32_16x16x32_bf16 v[58:61], v[154:157], v[178:181], v[58:61]
	v_mfma_f32_16x16x32_bf16 v[46:49], v[146:149], v[194:197], v[46:49]
	v_mfma_f32_16x16x32_bf16 v[42:45], v[154:157], v[194:197], v[42:45]
	v_mfma_f32_16x16x32_bf16 v[30:33], v[146:149], v[218:221], v[30:33]
	v_mfma_f32_16x16x32_bf16 v[26:29], v[154:157], v[218:221], v[26:29]
	v_mfma_f32_16x16x32_bf16 v[14:17], v[146:149], v[226:229], v[14:17]
	v_mfma_f32_16x16x32_bf16 v[10:13], v[154:157], v[226:229], v[10:13]
	v_mfma_f32_16x16x32_bf16 v[54:57], v[158:161], v[174:177], v[54:57]
	v_mfma_f32_16x16x32_bf16 v[50:53], v[166:169], v[174:177], v[50:53]
	v_mfma_f32_16x16x32_bf16 v[38:41], v[158:161], v[190:193], v[38:41]
	v_mfma_f32_16x16x32_bf16 v[34:37], v[166:169], v[190:193], v[34:37]
	v_mfma_f32_16x16x32_bf16 v[22:25], v[158:161], v[214:217], v[22:25]
	v_mfma_f32_16x16x32_bf16 v[18:21], v[166:169], v[214:217], v[18:21]
	v_mfma_f32_16x16x32_bf16 v[6:9], v[158:161], v[222:225], v[6:9]
	v_mfma_f32_16x16x32_bf16 v[2:5], v[166:169], v[222:225], v[2:5]
	v_mfma_f32_16x16x32_bf16 v[54:57], v[162:165], v[178:181], v[54:57]
	v_mfma_f32_16x16x32_bf16 v[50:53], v[170:173], v[178:181], v[50:53]
	v_mfma_f32_16x16x32_bf16 v[38:41], v[162:165], v[194:197], v[38:41]
	v_mfma_f32_16x16x32_bf16 v[34:37], v[170:173], v[194:197], v[34:37]
	v_mfma_f32_16x16x32_bf16 v[22:25], v[162:165], v[218:221], v[22:25]
	v_mfma_f32_16x16x32_bf16 v[18:21], v[170:173], v[218:221], v[18:21]
	v_mfma_f32_16x16x32_bf16 v[6:9], v[162:165], v[226:229], v[6:9]
	v_mfma_f32_16x16x32_bf16 v[2:5], v[170:173], v[226:229], v[2:5]
	s_setprio 0
	s_barrier
	s_andn2_b64 vcc, exec, s[30:31]
	s_mov_b64 s[10:11], -1
	s_mov_b64 s[30:31], 0
	s_mov_b64 s[34:35], 0x100
	s_cbranch_vccz .LBB11_2045
	s_and_b64 vcc, exec, s[16:17]
	s_cbranch_vccz .LBB11_2048
	s_barrier

.LBB11_2093:
	s_add_u32 s36, s24, s28
	s_addc_u32 s37, s25, s29
	s_add_u32 s30, s36, 0x100
	s_addc_u32 s31, s37, 0
	s_and_b64 s[0:1], s[10:11], exec
	s_cselect_b32 s31, s58, s31
	s_cselect_b32 s30, s59, s30
	s_add_u32 s0, s22, s28
	s_addc_u32 s1, s23, s29
	s_add_u32 s28, s0, 0x100
	s_addc_u32 s29, s1, 0
	s_add_i32 s51, 0, 0x10000
	s_and_b64 s[0:1], s[10:11], exec
	s_cselect_b32 s35, s60, s29
	s_cselect_b32 s34, s68, s28
	s_add_i32 s0, 0, 0x14000
	s_add_u32 s38, s36, 0x40080
	s_addc_u32 s39, s37, 0
	s_add_i32 s50, s51, s40
	s_add_i32 m0, s41, 0xc000
	s_add_i32 s1, s41, 0xe000
	s_add_i32 s48, s50, 0x2000
	s_add_u32 s36, s34, 0x10000
	v_add_u32_e32 v152, s51, v141
	v_add_u32_e32 v168, s0, v141
	s_addc_u32 s37, s35, 0
	s_add_i32 s89, s0, s40
	ds_read_b128 v[136:139], v152
	ds_read_b128 v[144:147], v152 offset:1024
	ds_read_b128 v[148:151], v152 offset:2048
	ds_read_b128 v[152:155], v152 offset:3072
	ds_read_b128 v[156:159], v168
	ds_read_b128 v[160:163], v168 offset:1024
	ds_read_b128 v[164:167], v168 offset:2048
	ds_read_b128 v[168:171], v168 offset:3072
	s_add_i32 s49, s89, 0x2000
	s_add_i32 s88, 0, 0x18000
	s_add_i32 s71, 0, 0x1c000
	s_add_u32 s28, s30, 0x40000
	s_addc_u32 s29, s31, 0
	s_add_i32 s70, s88, s40
	s_add_i32 s69, s70, 0x2000
	s_add_u32 s10, s34, 0x10080
	s_addc_u32 s11, s35, 0
	s_add_i32 s0, s71, s40
	s_add_i32 s51, s0, 0x2000
	v_lshl_add_u64 v[226:227], s[38:39], 0, v[134:135]
	ds_read_b128 v[172:175], v143
	ds_read_b128 v[176:179], v143 offset:1024
	ds_read_b128 v[180:183], v143 offset:2048
	ds_read_b128 v[190:193], v143 offset:3072
	ds_read_b128 v[194:197], v143 offset:4096
	ds_read_b128 v[214:217], v143 offset:5120
	ds_read_b128 v[218:221], v143 offset:6144
	ds_read_b128 v[222:225], v143 offset:7168
	global_load_lds_dwordx4 v[226:227], off
	v_lshl_add_u64 v[226:227], s[38:39], 0, v[132:133]
	s_mov_b32 m0, s1
	s_nop 0
	global_load_lds_dwordx4 v[226:227], off
	s_waitcnt vmcnt(8)
	s_waitcnt lgkmcnt(0)
	s_barrier
	s_setprio 1
	v_mfma_f32_16x16x32_bf16 v[126:129], v[136:139], v[172:175], v[126:129]
	v_mfma_f32_16x16x32_bf16 v[122:125], v[148:151], v[172:175], v[122:125]
	v_mfma_f32_16x16x32_bf16 v[114:117], v[136:139], v[180:183], v[114:117]
	v_mfma_f32_16x16x32_bf16 v[106:109], v[148:151], v[180:183], v[106:109]
	v_mfma_f32_16x16x32_bf16 v[98:101], v[136:139], v[194:197], v[98:101]
	v_mfma_f32_16x16x32_bf16 v[90:93], v[148:151], v[194:197], v[90:93]
	v_mfma_f32_16x16x32_bf16 v[82:85], v[136:139], v[218:221], v[82:85]
	v_mfma_f32_16x16x32_bf16 v[74:77], v[148:151], v[218:221], v[74:77]
	v_mfma_f32_16x16x32_bf16 v[126:129], v[144:147], v[176:179], v[126:129]
	v_mfma_f32_16x16x32_bf16 v[122:125], v[152:155], v[176:179], v[122:125]
	v_mfma_f32_16x16x32_bf16 v[114:117], v[144:147], v[190:193], v[114:117]
	v_mfma_f32_16x16x32_bf16 v[106:109], v[152:155], v[190:193], v[106:109]
	v_mfma_f32_16x16x32_bf16 v[98:101], v[144:147], v[214:217], v[98:101]
	v_mfma_f32_16x16x32_bf16 v[90:93], v[152:155], v[214:217], v[90:93]
	v_mfma_f32_16x16x32_bf16 v[82:85], v[144:147], v[222:225], v[82:85]
	v_mfma_f32_16x16x32_bf16 v[74:77], v[152:155], v[222:225], v[74:77]
	v_mfma_f32_16x16x32_bf16 v[118:121], v[156:159], v[172:175], v[118:121]
	v_mfma_f32_16x16x32_bf16 v[110:113], v[164:167], v[172:175], v[110:113]
	v_mfma_f32_16x16x32_bf16 v[102:105], v[156:159], v[180:183], v[102:105]
	v_mfma_f32_16x16x32_bf16 v[94:97], v[164:167], v[180:183], v[94:97]
	v_mfma_f32_16x16x32_bf16 v[86:89], v[156:159], v[194:197], v[86:89]
	v_mfma_f32_16x16x32_bf16 v[78:81], v[164:167], v[194:197], v[78:81]
	v_mfma_f32_16x16x32_bf16 v[70:73], v[156:159], v[218:221], v[70:73]
	v_mfma_f32_16x16x32_bf16 v[66:69], v[164:167], v[218:221], v[66:69]
	v_mfma_f32_16x16x32_bf16 v[118:121], v[160:163], v[176:179], v[118:121]
	v_mfma_f32_16x16x32_bf16 v[110:113], v[168:171], v[176:179], v[110:113]
	v_mfma_f32_16x16x32_bf16 v[102:105], v[160:163], v[190:193], v[102:105]
	v_mfma_f32_16x16x32_bf16 v[94:97], v[168:171], v[190:193], v[94:97]
	v_mfma_f32_16x16x32_bf16 v[86:89], v[160:163], v[214:217], v[86:89]
	v_mfma_f32_16x16x32_bf16 v[78:81], v[168:171], v[214:217], v[78:81]
	v_mfma_f32_16x16x32_bf16 v[70:73], v[160:163], v[222:225], v[70:73]
	v_mfma_f32_16x16x32_bf16 v[66:69], v[168:171], v[222:225], v[66:69]
	s_setprio 0
	s_barrier
	s_mov_b32 m0, s50
	v_lshl_add_u64 v[226:227], s[34:35], 0, v[0:1]
	ds_read_b128 v[172:175], v143 offset:16384
	ds_read_b128 v[176:179], v143 offset:17408
	ds_read_b128 v[180:183], v143 offset:18432
	ds_read_b128 v[190:193], v143 offset:19456
	ds_read_b128 v[194:197], v143 offset:20480
	ds_read_b128 v[214:217], v143 offset:21504
	ds_read_b128 v[218:221], v143 offset:22528
	ds_read_b128 v[222:225], v143 offset:23552
	global_load_lds_dwordx4 v[226:227], off
	v_lshl_add_u64 v[228:229], s[34:35], 0, v[130:131]
	s_mov_b32 m0, s48
	v_lshl_add_u64 v[230:231], s[36:37], 0, v[0:1]
	global_load_lds_dwordx4 v[228:229], off
	s_mov_b32 m0, s89
	v_lshl_add_u64 v[232:233], s[30:31], 0, v[132:133]
	global_load_lds_dwordx4 v[230:231], off
	v_lshl_add_u64 v[230:231], s[36:37], 0, v[130:131]
	s_mov_b32 m0, s49
	s_nop 0
	global_load_lds_dwordx4 v[230:231], off
	v_lshl_add_u64 v[230:231], s[30:31], 0, v[134:135]
	s_mov_b32 m0, s41
	s_nop 0
	global_load_lds_dwordx4 v[230:231], off
	s_mov_b32 m0, s42
	s_nop 0
	global_load_lds_dwordx4 v[232:233], off
	s_waitcnt vmcnt(8)
	s_waitcnt lgkmcnt(0)
	s_barrier
	s_setprio 1
	v_mfma_f32_16x16x32_bf16 v[62:65], v[136:139], v[172:175], v[62:65]
	v_mfma_f32_16x16x32_bf16 v[58:61], v[148:151], v[172:175], v[58:61]
	v_mfma_f32_16x16x32_bf16 v[50:53], v[136:139], v[180:183], v[50:53]
	v_mfma_f32_16x16x32_bf16 v[42:45], v[148:151], v[180:183], v[42:45]
	v_mfma_f32_16x16x32_bf16 v[34:37], v[136:139], v[194:197], v[34:37]
	v_mfma_f32_16x16x32_bf16 v[26:29], v[148:151], v[194:197], v[26:29]
	v_mfma_f32_16x16x32_bf16 v[18:21], v[136:139], v[218:221], v[18:21]
	v_mfma_f32_16x16x32_bf16 v[10:13], v[148:151], v[218:221], v[10:13]
	v_mfma_f32_16x16x32_bf16 v[62:65], v[144:147], v[176:179], v[62:65]
	v_mfma_f32_16x16x32_bf16 v[58:61], v[152:155], v[176:179], v[58:61]
	v_mfma_f32_16x16x32_bf16 v[50:53], v[144:147], v[190:193], v[50:53]
	v_mfma_f32_16x16x32_bf16 v[42:45], v[152:155], v[190:193], v[42:45]
	v_mfma_f32_16x16x32_bf16 v[34:37], v[144:147], v[214:217], v[34:37]
	v_mfma_f32_16x16x32_bf16 v[26:29], v[152:155], v[214:217], v[26:29]
	v_mfma_f32_16x16x32_bf16 v[18:21], v[144:147], v[222:225], v[18:21]
	v_mfma_f32_16x16x32_bf16 v[10:13], v[152:155], v[222:225], v[10:13]
	v_mfma_f32_16x16x32_bf16 v[54:57], v[156:159], v[172:175], v[54:57]
	v_mfma_f32_16x16x32_bf16 v[46:49], v[164:167], v[172:175], v[46:49]
	v_mfma_f32_16x16x32_bf16 v[38:41], v[156:159], v[180:183], v[38:41]
	v_mfma_f32_16x16x32_bf16 v[30:33], v[164:167], v[180:183], v[30:33]
	v_mfma_f32_16x16x32_bf16 v[22:25], v[156:159], v[194:197], v[22:25]
	v_mfma_f32_16x16x32_bf16 v[14:17], v[164:167], v[194:197], v[14:17]
	v_mfma_f32_16x16x32_bf16 v[6:9], v[156:159], v[218:221], v[6:9]
	v_mfma_f32_16x16x32_bf16 v[2:5], v[164:167], v[218:221], v[2:5]
	v_mfma_f32_16x16x32_bf16 v[54:57], v[160:163], v[176:179], v[54:57]
	v_mfma_f32_16x16x32_bf16 v[46:49], v[168:171], v[176:179], v[46:49]
	v_mfma_f32_16x16x32_bf16 v[38:41], v[160:163], v[190:193], v[38:41]
	v_mfma_f32_16x16x32_bf16 v[30:33], v[168:171], v[190:193], v[30:33]
	v_mfma_f32_16x16x32_bf16 v[22:25], v[160:163], v[214:217], v[22:25]
	v_mfma_f32_16x16x32_bf16 v[14:17], v[168:171], v[214:217], v[14:17]
	v_mfma_f32_16x16x32_bf16 v[6:9], v[160:163], v[222:225], v[6:9]
	v_mfma_f32_16x16x32_bf16 v[2:5], v[168:171], v[222:225], v[2:5]
	s_setprio 0
	s_barrier
	v_add_u32_e32 v152, s88, v141
	v_add_u32_e32 v168, s71, v141
	ds_read_b128 v[136:139], v152
	ds_read_b128 v[144:147], v152 offset:1024
	ds_read_b128 v[148:151], v152 offset:2048
	ds_read_b128 v[152:155], v152 offset:3072
	ds_read_b128 v[156:159], v168
	ds_read_b128 v[160:163], v168 offset:1024
	ds_read_b128 v[164:167], v168 offset:2048
	ds_read_b128 v[168:171], v168 offset:3072
	s_mov_b32 m0, s43
	v_lshl_add_u64 v[234:235], s[28:29], 0, v[134:135]
	ds_read_b128 v[172:175], v143 offset:32768
	ds_read_b128 v[176:179], v143 offset:33792
	ds_read_b128 v[180:183], v143 offset:34816
	ds_read_b128 v[190:193], v143 offset:35840
	ds_read_b128 v[194:197], v143 offset:36864
	ds_read_b128 v[214:217], v143 offset:37888
	ds_read_b128 v[218:221], v143 offset:38912
	ds_read_b128 v[222:225], v143 offset:39936
	global_load_lds_dwordx4 v[234:235], off
	v_lshl_add_u64 v[234:235], s[28:29], 0, v[132:133]
	s_mov_b32 m0, s44
	s_nop 0
	global_load_lds_dwordx4 v[234:235], off
	s_waitcnt vmcnt(8)
	s_waitcnt lgkmcnt(0)
	s_barrier
	s_setprio 1
	v_mfma_f32_16x16x32_bf16 v[126:129], v[136:139], v[172:175], v[126:129]
	v_mfma_f32_16x16x32_bf16 v[122:125], v[148:151], v[172:175], v[122:125]
	v_mfma_f32_16x16x32_bf16 v[114:117], v[136:139], v[180:183], v[114:117]
	v_mfma_f32_16x16x32_bf16 v[106:109], v[148:151], v[180:183], v[106:109]
	v_mfma_f32_16x16x32_bf16 v[98:101], v[136:139], v[194:197], v[98:101]
	v_mfma_f32_16x16x32_bf16 v[90:93], v[148:151], v[194:197], v[90:93]
	v_mfma_f32_16x16x32_bf16 v[82:85], v[136:139], v[218:221], v[82:85]
	v_mfma_f32_16x16x32_bf16 v[74:77], v[148:151], v[218:221], v[74:77]
	v_mfma_f32_16x16x32_bf16 v[126:129], v[144:147], v[176:179], v[126:129]
	v_mfma_f32_16x16x32_bf16 v[122:125], v[152:155], v[176:179], v[122:125]
	v_mfma_f32_16x16x32_bf16 v[114:117], v[144:147], v[190:193], v[114:117]
	v_mfma_f32_16x16x32_bf16 v[106:109], v[152:155], v[190:193], v[106:109]
	v_mfma_f32_16x16x32_bf16 v[98:101], v[144:147], v[214:217], v[98:101]
	v_mfma_f32_16x16x32_bf16 v[90:93], v[152:155], v[214:217], v[90:93]
	v_mfma_f32_16x16x32_bf16 v[82:85], v[144:147], v[222:225], v[82:85]
	v_mfma_f32_16x16x32_bf16 v[74:77], v[152:155], v[222:225], v[74:77]
	v_mfma_f32_16x16x32_bf16 v[118:121], v[156:159], v[172:175], v[118:121]
	v_mfma_f32_16x16x32_bf16 v[110:113], v[164:167], v[172:175], v[110:113]
	v_mfma_f32_16x16x32_bf16 v[102:105], v[156:159], v[180:183], v[102:105]
	v_mfma_f32_16x16x32_bf16 v[94:97], v[164:167], v[180:183], v[94:97]
	v_mfma_f32_16x16x32_bf16 v[86:89], v[156:159], v[194:197], v[86:89]
	v_mfma_f32_16x16x32_bf16 v[78:81], v[164:167], v[194:197], v[78:81]
	v_mfma_f32_16x16x32_bf16 v[70:73], v[156:159], v[218:221], v[70:73]
	v_mfma_f32_16x16x32_bf16 v[66:69], v[164:167], v[218:221], v[66:69]
	v_mfma_f32_16x16x32_bf16 v[118:121], v[160:163], v[176:179], v[118:121]
	v_mfma_f32_16x16x32_bf16 v[110:113], v[168:171], v[176:179], v[110:113]
	v_mfma_f32_16x16x32_bf16 v[102:105], v[160:163], v[190:193], v[102:105]
	v_mfma_f32_16x16x32_bf16 v[94:97], v[168:171], v[190:193], v[94:97]
	v_mfma_f32_16x16x32_bf16 v[86:89], v[160:163], v[214:217], v[86:89]
	v_mfma_f32_16x16x32_bf16 v[78:81], v[168:171], v[214:217], v[78:81]
	v_mfma_f32_16x16x32_bf16 v[70:73], v[160:163], v[222:225], v[70:73]
	v_mfma_f32_16x16x32_bf16 v[66:69], v[168:171], v[222:225], v[66:69]
	s_setprio 0
	s_barrier
	s_mov_b32 m0, s70
	v_lshl_add_u64 v[226:227], v[226:227], 0, s[96:97]
	ds_read_b128 v[172:175], v143 offset:49152
	ds_read_b128 v[176:179], v143 offset:50176
	ds_read_b128 v[180:183], v143 offset:51200
	ds_read_b128 v[190:193], v143 offset:52224
	ds_read_b128 v[194:197], v143 offset:53248
	ds_read_b128 v[214:217], v143 offset:54272
	ds_read_b128 v[218:221], v143 offset:55296
	ds_read_b128 v[222:225], v143 offset:56320
	global_load_lds_dwordx4 v[226:227], off
	v_lshl_add_u64 v[226:227], v[228:229], 0, s[96:97]
	s_mov_b32 m0, s69
	s_nop 0
	global_load_lds_dwordx4 v[226:227], off
	v_lshl_add_u64 v[226:227], s[10:11], 0, v[0:1]
	s_mov_b32 m0, s0
	s_nop 0
	global_load_lds_dwordx4 v[226:227], off
	v_lshl_add_u64 v[226:227], s[10:11], 0, v[130:131]
	s_mov_b32 m0, s51
	s_nop 0
	global_load_lds_dwordx4 v[226:227], off
	v_lshl_add_u64 v[226:227], v[230:231], 0, s[96:97]
	s_mov_b32 m0, s45
	s_nop 0
	global_load_lds_dwordx4 v[226:227], off
	v_lshl_add_u64 v[226:227], v[232:233], 0, s[96:97]
	s_mov_b32 m0, s46
	s_nop 0
	global_load_lds_dwordx4 v[226:227], off
	s_waitcnt vmcnt(8)
	s_waitcnt lgkmcnt(0)
	s_barrier
	s_setprio 1
	v_mfma_f32_16x16x32_bf16 v[62:65], v[136:139], v[172:175], v[62:65]
	v_mfma_f32_16x16x32_bf16 v[58:61], v[148:151], v[172:175], v[58:61]
	v_mfma_f32_16x16x32_bf16 v[50:53], v[136:139], v[180:183], v[50:53]
	v_mfma_f32_16x16x32_bf16 v[42:45], v[148:151], v[180:183], v[42:45]
	v_mfma_f32_16x16x32_bf16 v[34:37], v[136:139], v[194:197], v[34:37]
	v_mfma_f32_16x16x32_bf16 v[26:29], v[148:151], v[194:197], v[26:29]
	v_mfma_f32_16x16x32_bf16 v[18:21], v[136:139], v[218:221], v[18:21]
	v_mfma_f32_16x16x32_bf16 v[10:13], v[148:151], v[218:221], v[10:13]
	v_mfma_f32_16x16x32_bf16 v[62:65], v[144:147], v[176:179], v[62:65]
	v_mfma_f32_16x16x32_bf16 v[58:61], v[152:155], v[176:179], v[58:61]
	v_mfma_f32_16x16x32_bf16 v[50:53], v[144:147], v[190:193], v[50:53]
	v_mfma_f32_16x16x32_bf16 v[42:45], v[152:155], v[190:193], v[42:45]
	v_mfma_f32_16x16x32_bf16 v[34:37], v[144:147], v[214:217], v[34:37]
	v_mfma_f32_16x16x32_bf16 v[26:29], v[152:155], v[214:217], v[26:29]
	v_mfma_f32_16x16x32_bf16 v[18:21], v[144:147], v[222:225], v[18:21]
	v_mfma_f32_16x16x32_bf16 v[10:13], v[152:155], v[222:225], v[10:13]
	v_mfma_f32_16x16x32_bf16 v[54:57], v[156:159], v[172:175], v[54:57]
	v_mfma_f32_16x16x32_bf16 v[46:49], v[164:167], v[172:175], v[46:49]
	v_mfma_f32_16x16x32_bf16 v[38:41], v[156:159], v[180:183], v[38:41]
	v_mfma_f32_16x16x32_bf16 v[30:33], v[164:167], v[180:183], v[30:33]
	v_mfma_f32_16x16x32_bf16 v[22:25], v[156:159], v[194:197], v[22:25]
	v_mfma_f32_16x16x32_bf16 v[14:17], v[164:167], v[194:197], v[14:17]
	v_mfma_f32_16x16x32_bf16 v[6:9], v[156:159], v[218:221], v[6:9]
	v_mfma_f32_16x16x32_bf16 v[2:5], v[164:167], v[218:221], v[2:5]
	v_mfma_f32_16x16x32_bf16 v[54:57], v[160:163], v[176:179], v[54:57]
	v_mfma_f32_16x16x32_bf16 v[46:49], v[168:171], v[176:179], v[46:49]
	v_mfma_f32_16x16x32_bf16 v[38:41], v[160:163], v[190:193], v[38:41]
	v_mfma_f32_16x16x32_bf16 v[30:33], v[168:171], v[190:193], v[30:33]
	v_mfma_f32_16x16x32_bf16 v[22:25], v[160:163], v[214:217], v[22:25]
	v_mfma_f32_16x16x32_bf16 v[14:17], v[168:171], v[214:217], v[14:17]
	v_mfma_f32_16x16x32_bf16 v[6:9], v[160:163], v[222:225], v[6:9]
	v_mfma_f32_16x16x32_bf16 v[2:5], v[168:171], v[222:225], v[2:5]
	s_setprio 0
	s_barrier
	s_andn2_b64 vcc, exec, s[26:27]
	s_mov_b64 s[10:11], -1
	s_mov_b64 s[26:27], 0
	s_mov_b64 s[28:29], 0x100
	s_cbranch_vccz .LBB11_2093
	s_and_b64 vcc, exec, s[14:15]
	s_cbranch_vccz .LBB11_2096
	s_barrier

.LBB11_2329:
	s_add_u32 s0, s22, 0xfffc0080
	s_addc_u32 s1, s23, -1
	s_add_i32 s48, 0, 0x10000
	s_cmp_eq_u32 s57, 12
	s_cselect_b32 s27, s8, s1
	s_cselect_b32 s26, s9, s0
	v_add_u32_e32 v148, s48, v151
	s_cselect_b32 s25, s45, s56
	s_cselect_b32 s24, s46, s47
	s_add_i32 s49, 0, 0x14000
	ds_read_b128 v[140:143], v148
	ds_read_b128 v[144:147], v148 offset:1024
	ds_read_b128 v[154:157], v148 offset:2048
	ds_read_b128 v[158:161], v148 offset:3072
	v_add_u32_e32 v148, s49, v151
	ds_read_b128 v[162:165], v148
	ds_read_b128 v[166:169], v148 offset:1024
	ds_read_b128 v[170:173], v148 offset:2048
	ds_read_b128 v[174:177], v148 offset:3072
	v_lshl_add_u64 v[148:149], s[22:23], 0, v[136:137]
	s_add_i32 m0, s35, 0xc000
	ds_read_b128 v[178:181], v153
	ds_read_b128 v[190:193], v153 offset:1024
	ds_read_b128 v[194:197], v153 offset:2048
	ds_read_b128 v[214:217], v153 offset:3072
	ds_read_b128 v[218:221], v153 offset:4096
	ds_read_b128 v[222:225], v153 offset:5120
	ds_read_b128 v[226:229], v153 offset:6144
	ds_read_b128 v[230:233], v153 offset:7168
	global_load_lds_dwordx4 v[148:149], off
	v_lshl_add_u64 v[148:149], s[22:23], 0, v[138:139]
	s_add_i32 m0, s35, 0xe000
	s_nop 0
	global_load_lds_dwordx4 v[148:149], off
	s_waitcnt vmcnt(8)
	s_waitcnt lgkmcnt(0)
	s_barrier
	s_setprio 1
	v_mfma_f32_16x16x32_bf16 v[126:129], v[140:143], v[178:181], v[126:129]
	v_mfma_f32_16x16x32_bf16 v[122:125], v[154:157], v[178:181], v[122:125]
	v_mfma_f32_16x16x32_bf16 v[110:113], v[140:143], v[194:197], v[110:113]
	v_mfma_f32_16x16x32_bf16 v[106:109], v[154:157], v[194:197], v[106:109]
	v_mfma_f32_16x16x32_bf16 v[94:97], v[140:143], v[218:221], v[94:97]
	v_mfma_f32_16x16x32_bf16 v[90:93], v[154:157], v[218:221], v[90:93]
	v_mfma_f32_16x16x32_bf16 v[78:81], v[140:143], v[226:229], v[78:81]
	v_mfma_f32_16x16x32_bf16 v[74:77], v[154:157], v[226:229], v[74:77]
	v_mfma_f32_16x16x32_bf16 v[126:129], v[144:147], v[190:193], v[126:129]
	v_mfma_f32_16x16x32_bf16 v[122:125], v[158:161], v[190:193], v[122:125]
	v_mfma_f32_16x16x32_bf16 v[110:113], v[144:147], v[214:217], v[110:113]
	v_mfma_f32_16x16x32_bf16 v[106:109], v[158:161], v[214:217], v[106:109]
	v_mfma_f32_16x16x32_bf16 v[94:97], v[144:147], v[222:225], v[94:97]
	v_mfma_f32_16x16x32_bf16 v[90:93], v[158:161], v[222:225], v[90:93]
	v_mfma_f32_16x16x32_bf16 v[78:81], v[144:147], v[230:233], v[78:81]
	v_mfma_f32_16x16x32_bf16 v[74:77], v[158:161], v[230:233], v[74:77]
	v_mfma_f32_16x16x32_bf16 v[118:121], v[162:165], v[178:181], v[118:121]
	v_mfma_f32_16x16x32_bf16 v[114:117], v[170:173], v[178:181], v[114:117]
	v_mfma_f32_16x16x32_bf16 v[102:105], v[162:165], v[194:197], v[102:105]
	v_mfma_f32_16x16x32_bf16 v[98:101], v[170:173], v[194:197], v[98:101]
	v_mfma_f32_16x16x32_bf16 v[86:89], v[162:165], v[218:221], v[86:89]
	v_mfma_f32_16x16x32_bf16 v[82:85], v[170:173], v[218:221], v[82:85]
	v_mfma_f32_16x16x32_bf16 v[70:73], v[162:165], v[226:229], v[70:73]
	v_mfma_f32_16x16x32_bf16 v[66:69], v[170:173], v[226:229], v[66:69]
	v_mfma_f32_16x16x32_bf16 v[118:121], v[166:169], v[190:193], v[118:121]
	v_mfma_f32_16x16x32_bf16 v[114:117], v[174:177], v[190:193], v[114:117]
	v_mfma_f32_16x16x32_bf16 v[102:105], v[166:169], v[214:217], v[102:105]
	v_mfma_f32_16x16x32_bf16 v[98:101], v[174:177], v[214:217], v[98:101]
	v_mfma_f32_16x16x32_bf16 v[86:89], v[166:169], v[222:225], v[86:89]
	v_mfma_f32_16x16x32_bf16 v[82:85], v[174:177], v[222:225], v[82:85]
	v_mfma_f32_16x16x32_bf16 v[70:73], v[166:169], v[230:233], v[70:73]
	v_mfma_f32_16x16x32_bf16 v[66:69], v[174:177], v[230:233], v[66:69]
	s_setprio 0
	s_barrier
	s_add_i32 s0, s48, s34
	v_lshl_add_u64 v[148:149], s[24:25], 0, v[0:1]
	s_mov_b32 m0, s0
	ds_read_b128 v[178:181], v153 offset:16384
	ds_read_b128 v[190:193], v153 offset:17408
	ds_read_b128 v[194:197], v153 offset:18432
	ds_read_b128 v[214:217], v153 offset:19456
	ds_read_b128 v[218:221], v153 offset:20480
	ds_read_b128 v[222:225], v153 offset:21504
	ds_read_b128 v[226:229], v153 offset:22528
	ds_read_b128 v[230:233], v153 offset:23552
	global_load_lds_dwordx4 v[148:149], off
	s_add_i32 m0, s0, 0x2000
	s_add_u32 s0, s24, 0x40000
	v_lshl_add_u64 v[182:183], s[24:25], 0, v[130:131]
	s_addc_u32 s1, s25, 0
	s_add_i32 s48, s49, s34
	global_load_lds_dwordx4 v[182:183], off
	v_lshl_add_u64 v[234:235], s[0:1], 0, v[0:1]
	s_mov_b32 m0, s48
	v_lshl_add_u64 v[236:237], s[26:27], 0, v[132:133]
	global_load_lds_dwordx4 v[234:235], off
	v_lshl_add_u64 v[234:235], s[0:1], 0, v[130:131]
	s_add_i32 m0, s48, 0x2000
	s_nop 0
	global_load_lds_dwordx4 v[234:235], off
	v_lshl_add_u64 v[234:235], s[26:27], 0, v[134:135]
	s_mov_b32 m0, s35
	s_nop 0
	global_load_lds_dwordx4 v[234:235], off
	s_mov_b32 m0, s36
	s_nop 0
	global_load_lds_dwordx4 v[236:237], off
	s_waitcnt vmcnt(8)
	s_waitcnt lgkmcnt(0)
	s_barrier
	s_setprio 1
	v_mfma_f32_16x16x32_bf16 v[62:65], v[140:143], v[178:181], v[62:65]
	v_mfma_f32_16x16x32_bf16 v[58:61], v[154:157], v[178:181], v[58:61]
	v_mfma_f32_16x16x32_bf16 v[46:49], v[140:143], v[194:197], v[46:49]
	v_mfma_f32_16x16x32_bf16 v[42:45], v[154:157], v[194:197], v[42:45]
	v_mfma_f32_16x16x32_bf16 v[30:33], v[140:143], v[218:221], v[30:33]
	v_mfma_f32_16x16x32_bf16 v[26:29], v[154:157], v[218:221], v[26:29]
	v_mfma_f32_16x16x32_bf16 v[14:17], v[140:143], v[226:229], v[14:17]
	v_mfma_f32_16x16x32_bf16 v[10:13], v[154:157], v[226:229], v[10:13]
	v_mfma_f32_16x16x32_bf16 v[62:65], v[144:147], v[190:193], v[62:65]
	v_mfma_f32_16x16x32_bf16 v[58:61], v[158:161], v[190:193], v[58:61]
	v_mfma_f32_16x16x32_bf16 v[46:49], v[144:147], v[214:217], v[46:49]
	v_mfma_f32_16x16x32_bf16 v[42:45], v[158:161], v[214:217], v[42:45]
	v_mfma_f32_16x16x32_bf16 v[30:33], v[144:147], v[222:225], v[30:33]
	v_mfma_f32_16x16x32_bf16 v[26:29], v[158:161], v[222:225], v[26:29]
	v_mfma_f32_16x16x32_bf16 v[14:17], v[144:147], v[230:233], v[14:17]
	v_mfma_f32_16x16x32_bf16 v[10:13], v[158:161], v[230:233], v[10:13]
	v_mfma_f32_16x16x32_bf16 v[54:57], v[162:165], v[178:181], v[54:57]
	v_mfma_f32_16x16x32_bf16 v[50:53], v[170:173], v[178:181], v[50:53]
	v_mfma_f32_16x16x32_bf16 v[38:41], v[162:165], v[194:197], v[38:41]
	v_mfma_f32_16x16x32_bf16 v[34:37], v[170:173], v[194:197], v[34:37]
	v_mfma_f32_16x16x32_bf16 v[22:25], v[162:165], v[218:221], v[22:25]
	v_mfma_f32_16x16x32_bf16 v[18:21], v[170:173], v[218:221], v[18:21]
	v_mfma_f32_16x16x32_bf16 v[6:9], v[162:165], v[226:229], v[6:9]
	v_mfma_f32_16x16x32_bf16 v[2:5], v[170:173], v[226:229], v[2:5]
	v_mfma_f32_16x16x32_bf16 v[54:57], v[166:169], v[190:193], v[54:57]
	v_mfma_f32_16x16x32_bf16 v[50:53], v[174:177], v[190:193], v[50:53]
	v_mfma_f32_16x16x32_bf16 v[38:41], v[166:169], v[214:217], v[38:41]
	v_mfma_f32_16x16x32_bf16 v[34:37], v[174:177], v[214:217], v[34:37]
	v_mfma_f32_16x16x32_bf16 v[22:25], v[166:169], v[222:225], v[22:25]
	v_mfma_f32_16x16x32_bf16 v[18:21], v[174:177], v[222:225], v[18:21]
	v_mfma_f32_16x16x32_bf16 v[6:9], v[166:169], v[230:233], v[6:9]
	v_mfma_f32_16x16x32_bf16 v[2:5], v[174:177], v[230:233], v[2:5]
	s_setprio 0
	s_barrier
	s_add_i32 s48, 0, 0x18000
	s_add_i32 s49, 0, 0x1c000
	v_add_u32_e32 v158, s48, v151
	v_add_u32_e32 v174, s49, v151
	ds_read_b128 v[140:143], v158
	ds_read_b128 v[144:147], v158 offset:1024
	ds_read_b128 v[154:157], v158 offset:2048
	ds_read_b128 v[158:161], v158 offset:3072
	ds_read_b128 v[162:165], v174
	ds_read_b128 v[166:169], v174 offset:1024
	ds_read_b128 v[170:173], v174 offset:2048
	ds_read_b128 v[174:177], v174 offset:3072
	s_add_u32 s0, s26, 0x40000
	s_addc_u32 s1, s27, 0
	s_mov_b32 m0, s37
	v_lshl_add_u64 v[238:239], s[0:1], 0, v[134:135]
	ds_read_b128 v[178:181], v153 offset:32768
	ds_read_b128 v[190:193], v153 offset:33792
	ds_read_b128 v[194:197], v153 offset:34816
	ds_read_b128 v[214:217], v153 offset:35840
	ds_read_b128 v[218:221], v153 offset:36864
	ds_read_b128 v[222:225], v153 offset:37888
	ds_read_b128 v[226:229], v153 offset:38912
	ds_read_b128 v[230:233], v153 offset:39936
	global_load_lds_dwordx4 v[238:239], off
	v_lshl_add_u64 v[238:239], s[0:1], 0, v[132:133]
	s_mov_b32 m0, s38
	s_nop 0
	global_load_lds_dwordx4 v[238:239], off
	s_waitcnt vmcnt(8)
	s_waitcnt lgkmcnt(0)
	s_barrier
	s_setprio 1
	v_mfma_f32_16x16x32_bf16 v[126:129], v[140:143], v[178:181], v[126:129]
	v_mfma_f32_16x16x32_bf16 v[122:125], v[154:157], v[178:181], v[122:125]
	v_mfma_f32_16x16x32_bf16 v[110:113], v[140:143], v[194:197], v[110:113]
	v_mfma_f32_16x16x32_bf16 v[106:109], v[154:157], v[194:197], v[106:109]
	v_mfma_f32_16x16x32_bf16 v[94:97], v[140:143], v[218:221], v[94:97]
	v_mfma_f32_16x16x32_bf16 v[90:93], v[154:157], v[218:221], v[90:93]
	v_mfma_f32_16x16x32_bf16 v[78:81], v[140:143], v[226:229], v[78:81]
	v_mfma_f32_16x16x32_bf16 v[74:77], v[154:157], v[226:229], v[74:77]
	v_mfma_f32_16x16x32_bf16 v[126:129], v[144:147], v[190:193], v[126:129]
	v_mfma_f32_16x16x32_bf16 v[122:125], v[158:161], v[190:193], v[122:125]
	v_mfma_f32_16x16x32_bf16 v[110:113], v[144:147], v[214:217], v[110:113]
	v_mfma_f32_16x16x32_bf16 v[106:109], v[158:161], v[214:217], v[106:109]
	v_mfma_f32_16x16x32_bf16 v[94:97], v[144:147], v[222:225], v[94:97]
	v_mfma_f32_16x16x32_bf16 v[90:93], v[158:161], v[222:225], v[90:93]
	v_mfma_f32_16x16x32_bf16 v[78:81], v[144:147], v[230:233], v[78:81]
	v_mfma_f32_16x16x32_bf16 v[74:77], v[158:161], v[230:233], v[74:77]
	v_mfma_f32_16x16x32_bf16 v[118:121], v[162:165], v[178:181], v[118:121]
	v_mfma_f32_16x16x32_bf16 v[114:117], v[170:173], v[178:181], v[114:117]
	v_mfma_f32_16x16x32_bf16 v[102:105], v[162:165], v[194:197], v[102:105]
	v_mfma_f32_16x16x32_bf16 v[98:101], v[170:173], v[194:197], v[98:101]
	v_mfma_f32_16x16x32_bf16 v[86:89], v[162:165], v[218:221], v[86:89]
	v_mfma_f32_16x16x32_bf16 v[82:85], v[170:173], v[218:221], v[82:85]
	v_mfma_f32_16x16x32_bf16 v[70:73], v[162:165], v[226:229], v[70:73]
	v_mfma_f32_16x16x32_bf16 v[66:69], v[170:173], v[226:229], v[66:69]
	v_mfma_f32_16x16x32_bf16 v[118:121], v[166:169], v[190:193], v[118:121]
	v_mfma_f32_16x16x32_bf16 v[114:117], v[174:177], v[190:193], v[114:117]
	v_mfma_f32_16x16x32_bf16 v[102:105], v[166:169], v[214:217], v[102:105]
	v_mfma_f32_16x16x32_bf16 v[98:101], v[174:177], v[214:217], v[98:101]
	v_mfma_f32_16x16x32_bf16 v[86:89], v[166:169], v[222:225], v[86:89]
	v_mfma_f32_16x16x32_bf16 v[82:85], v[174:177], v[222:225], v[82:85]
	v_mfma_f32_16x16x32_bf16 v[70:73], v[166:169], v[230:233], v[70:73]
	v_mfma_f32_16x16x32_bf16 v[66:69], v[174:177], v[230:233], v[66:69]
	s_setprio 0
	s_barrier
	s_add_i32 s0, s48, s34
	v_lshl_add_u64 v[148:149], v[148:149], 0, s[96:97]
	s_mov_b32 m0, s0
	ds_read_b128 v[178:181], v153 offset:49152
	ds_read_b128 v[190:193], v153 offset:50176
	ds_read_b128 v[194:197], v153 offset:51200
	ds_read_b128 v[214:217], v153 offset:52224
	ds_read_b128 v[218:221], v153 offset:53248
	ds_read_b128 v[222:225], v153 offset:54272
	ds_read_b128 v[226:229], v153 offset:55296
	ds_read_b128 v[230:233], v153 offset:56320
	global_load_lds_dwordx4 v[148:149], off
	s_add_i32 m0, s0, 0x2000
	s_add_u32 s0, s24, 0x40080
	v_lshl_add_u64 v[148:149], v[182:183], 0, s[96:97]
	s_addc_u32 s1, s25, 0
	s_add_i32 s24, s49, s34
	global_load_lds_dwordx4 v[148:149], off
	v_lshl_add_u64 v[148:149], s[0:1], 0, v[0:1]
	s_mov_b32 m0, s24
	s_nop 0
	global_load_lds_dwordx4 v[148:149], off
	v_lshl_add_u64 v[148:149], s[0:1], 0, v[130:131]
	s_add_i32 m0, s24, 0x2000
	s_nop 0
	global_load_lds_dwordx4 v[148:149], off
	v_lshl_add_u64 v[148:149], v[234:235], 0, s[96:97]
	s_mov_b32 m0, s39
	s_nop 0
	global_load_lds_dwordx4 v[148:149], off
	v_lshl_add_u64 v[148:149], v[236:237], 0, s[96:97]
	s_mov_b32 m0, s40
	s_nop 0
	global_load_lds_dwordx4 v[148:149], off
	s_waitcnt vmcnt(8)
	s_waitcnt lgkmcnt(0)
	s_barrier
	s_setprio 1
	v_mfma_f32_16x16x32_bf16 v[62:65], v[140:143], v[178:181], v[62:65]
	v_mfma_f32_16x16x32_bf16 v[58:61], v[154:157], v[178:181], v[58:61]
	v_mfma_f32_16x16x32_bf16 v[46:49], v[140:143], v[194:197], v[46:49]
	v_mfma_f32_16x16x32_bf16 v[42:45], v[154:157], v[194:197], v[42:45]
	v_mfma_f32_16x16x32_bf16 v[30:33], v[140:143], v[218:221], v[30:33]
	v_mfma_f32_16x16x32_bf16 v[26:29], v[154:157], v[218:221], v[26:29]
	v_mfma_f32_16x16x32_bf16 v[14:17], v[140:143], v[226:229], v[14:17]
	v_mfma_f32_16x16x32_bf16 v[10:13], v[154:157], v[226:229], v[10:13]
	v_mfma_f32_16x16x32_bf16 v[62:65], v[144:147], v[190:193], v[62:65]
	v_mfma_f32_16x16x32_bf16 v[58:61], v[158:161], v[190:193], v[58:61]
	v_mfma_f32_16x16x32_bf16 v[46:49], v[144:147], v[214:217], v[46:49]
	v_mfma_f32_16x16x32_bf16 v[42:45], v[158:161], v[214:217], v[42:45]
	v_mfma_f32_16x16x32_bf16 v[30:33], v[144:147], v[222:225], v[30:33]
	v_mfma_f32_16x16x32_bf16 v[26:29], v[158:161], v[222:225], v[26:29]
	v_mfma_f32_16x16x32_bf16 v[14:17], v[144:147], v[230:233], v[14:17]
	v_mfma_f32_16x16x32_bf16 v[10:13], v[158:161], v[230:233], v[10:13]
	v_mfma_f32_16x16x32_bf16 v[54:57], v[162:165], v[178:181], v[54:57]
	v_mfma_f32_16x16x32_bf16 v[50:53], v[170:173], v[178:181], v[50:53]
	v_mfma_f32_16x16x32_bf16 v[38:41], v[162:165], v[194:197], v[38:41]
	v_mfma_f32_16x16x32_bf16 v[34:37], v[170:173], v[194:197], v[34:37]
	v_mfma_f32_16x16x32_bf16 v[22:25], v[162:165], v[218:221], v[22:25]
	v_mfma_f32_16x16x32_bf16 v[18:21], v[170:173], v[218:221], v[18:21]
	v_mfma_f32_16x16x32_bf16 v[6:9], v[162:165], v[226:229], v[6:9]
	v_mfma_f32_16x16x32_bf16 v[2:5], v[170:173], v[226:229], v[2:5]
	v_mfma_f32_16x16x32_bf16 v[54:57], v[166:169], v[190:193], v[54:57]
	v_mfma_f32_16x16x32_bf16 v[50:53], v[174:177], v[190:193], v[50:53]
	v_mfma_f32_16x16x32_bf16 v[38:41], v[166:169], v[214:217], v[38:41]
	v_mfma_f32_16x16x32_bf16 v[34:37], v[174:177], v[214:217], v[34:37]
	v_mfma_f32_16x16x32_bf16 v[22:25], v[166:169], v[222:225], v[22:25]
	v_mfma_f32_16x16x32_bf16 v[18:21], v[174:177], v[222:225], v[18:21]
	v_mfma_f32_16x16x32_bf16 v[6:9], v[166:169], v[230:233], v[6:9]
	v_mfma_f32_16x16x32_bf16 v[2:5], v[174:177], v[230:233], v[2:5]
	s_setprio 0
	s_barrier
	s_add_i32 s57, s57, 2
	s_add_u32 s22, s22, 0x100
	s_addc_u32 s23, s23, 0
	s_add_u32 s47, s47, 0x100
	s_addc_u32 s56, s56, 0
	s_cmp_gt_u32 s57, 13
	s_cbranch_scc0 .LBB11_2329
	s_and_b64 vcc, exec, s[14:15]
	s_cbranch_vccz .LBB11_2332
	s_barrier

.LBB11_2567:
	s_add_u32 s0, s26, 0xfffc0080
	s_addc_u32 s1, s27, -1
	s_add_i32 s48, 0, 0x10000
	s_cmp_eq_u32 s68, 12
	s_cselect_b32 s31, s9, s1
	s_cselect_b32 s30, s47, s0
	s_cselect_b32 s29, s56, s59
	s_cselect_b32 s28, s57, s58
	s_add_i32 s49, 0, 0x14000
	v_add_u32_e32 v158, s48, v142
	v_add_u32_e32 v174, s49, v142
	ds_read_b128 v[146:149], v158
	ds_read_b128 v[150:153], v158 offset:1024
	ds_read_b128 v[154:157], v158 offset:2048
	ds_read_b128 v[158:161], v158 offset:3072
	ds_read_b128 v[162:165], v174
	ds_read_b128 v[166:169], v174 offset:1024
	ds_read_b128 v[170:173], v174 offset:2048
	ds_read_b128 v[174:177], v174 offset:3072
	v_lshl_add_u64 v[182:183], s[26:27], 0, v[136:137]
	s_add_i32 m0, s36, 0xc000
	ds_read_b128 v[178:181], v145
	ds_read_b128 v[190:193], v145 offset:1024
	ds_read_b128 v[194:197], v145 offset:2048
	ds_read_b128 v[214:217], v145 offset:3072
	ds_read_b128 v[218:221], v145 offset:4096
	ds_read_b128 v[222:225], v145 offset:5120
	ds_read_b128 v[226:229], v145 offset:6144
	ds_read_b128 v[230:233], v145 offset:7168
	global_load_lds_dwordx4 v[182:183], off
	v_lshl_add_u64 v[182:183], s[26:27], 0, v[138:139]
	s_add_i32 m0, s36, 0xe000
	s_nop 0
	global_load_lds_dwordx4 v[182:183], off
	s_waitcnt vmcnt(8)
	s_waitcnt lgkmcnt(0)
	s_barrier
	s_setprio 1
	v_mfma_f32_16x16x32_bf16 v[126:129], v[146:149], v[178:181], v[126:129]
	v_mfma_f32_16x16x32_bf16 v[118:121], v[154:157], v[178:181], v[118:121]
	v_mfma_f32_16x16x32_bf16 v[110:113], v[146:149], v[194:197], v[110:113]
	v_mfma_f32_16x16x32_bf16 v[102:105], v[154:157], v[194:197], v[102:105]
	v_mfma_f32_16x16x32_bf16 v[94:97], v[146:149], v[218:221], v[94:97]
	v_mfma_f32_16x16x32_bf16 v[86:89], v[154:157], v[218:221], v[86:89]
	v_mfma_f32_16x16x32_bf16 v[78:81], v[146:149], v[226:229], v[78:81]
	v_mfma_f32_16x16x32_bf16 v[70:73], v[154:157], v[226:229], v[70:73]
	v_mfma_f32_16x16x32_bf16 v[126:129], v[150:153], v[190:193], v[126:129]
	v_mfma_f32_16x16x32_bf16 v[118:121], v[158:161], v[190:193], v[118:121]
	v_mfma_f32_16x16x32_bf16 v[110:113], v[150:153], v[214:217], v[110:113]
	v_mfma_f32_16x16x32_bf16 v[102:105], v[158:161], v[214:217], v[102:105]
	v_mfma_f32_16x16x32_bf16 v[94:97], v[150:153], v[222:225], v[94:97]
	v_mfma_f32_16x16x32_bf16 v[86:89], v[158:161], v[222:225], v[86:89]
	v_mfma_f32_16x16x32_bf16 v[78:81], v[150:153], v[230:233], v[78:81]
	v_mfma_f32_16x16x32_bf16 v[70:73], v[158:161], v[230:233], v[70:73]
	v_mfma_f32_16x16x32_bf16 v[122:125], v[162:165], v[178:181], v[122:125]
	v_mfma_f32_16x16x32_bf16 v[114:117], v[170:173], v[178:181], v[114:117]
	v_mfma_f32_16x16x32_bf16 v[106:109], v[162:165], v[194:197], v[106:109]
	v_mfma_f32_16x16x32_bf16 v[98:101], v[170:173], v[194:197], v[98:101]
	v_mfma_f32_16x16x32_bf16 v[90:93], v[162:165], v[218:221], v[90:93]
	v_mfma_f32_16x16x32_bf16 v[82:85], v[170:173], v[218:221], v[82:85]
	v_mfma_f32_16x16x32_bf16 v[74:77], v[162:165], v[226:229], v[74:77]
	v_mfma_f32_16x16x32_bf16 v[66:69], v[170:173], v[226:229], v[66:69]
	v_mfma_f32_16x16x32_bf16 v[122:125], v[166:169], v[190:193], v[122:125]
	v_mfma_f32_16x16x32_bf16 v[114:117], v[174:177], v[190:193], v[114:117]
	v_mfma_f32_16x16x32_bf16 v[106:109], v[166:169], v[214:217], v[106:109]
	v_mfma_f32_16x16x32_bf16 v[98:101], v[174:177], v[214:217], v[98:101]
	v_mfma_f32_16x16x32_bf16 v[90:93], v[166:169], v[222:225], v[90:93]
	v_mfma_f32_16x16x32_bf16 v[82:85], v[174:177], v[222:225], v[82:85]
	v_mfma_f32_16x16x32_bf16 v[74:77], v[166:169], v[230:233], v[74:77]
	v_mfma_f32_16x16x32_bf16 v[66:69], v[174:177], v[230:233], v[66:69]
	s_setprio 0
	s_barrier
	s_add_i32 s0, s48, s35
	v_lshl_add_u64 v[182:183], s[28:29], 0, v[0:1]
	s_mov_b32 m0, s0
	ds_read_b128 v[178:181], v145 offset:16384
	ds_read_b128 v[190:193], v145 offset:17408
	ds_read_b128 v[194:197], v145 offset:18432
	ds_read_b128 v[214:217], v145 offset:19456
	ds_read_b128 v[218:221], v145 offset:20480
	ds_read_b128 v[222:225], v145 offset:21504
	ds_read_b128 v[226:229], v145 offset:22528
	ds_read_b128 v[230:233], v145 offset:23552
	global_load_lds_dwordx4 v[182:183], off
	s_add_i32 m0, s0, 0x2000
	s_add_u32 s0, s28, 0x40000
	v_lshl_add_u64 v[234:235], s[28:29], 0, v[134:135]
	s_addc_u32 s1, s29, 0
	s_add_i32 s48, s49, s35
	global_load_lds_dwordx4 v[234:235], off
	v_lshl_add_u64 v[236:237], s[0:1], 0, v[0:1]
	s_mov_b32 m0, s48
	v_lshl_add_u64 v[238:239], s[30:31], 0, v[132:133]
	global_load_lds_dwordx4 v[236:237], off
	v_lshl_add_u64 v[236:237], s[0:1], 0, v[134:135]
	s_add_i32 m0, s48, 0x2000
	s_nop 0
	global_load_lds_dwordx4 v[236:237], off
	v_lshl_add_u64 v[236:237], s[30:31], 0, v[130:131]
	s_mov_b32 m0, s36
	s_nop 0
	global_load_lds_dwordx4 v[236:237], off
	s_mov_b32 m0, s37
	s_nop 0
	global_load_lds_dwordx4 v[238:239], off
	s_waitcnt vmcnt(8)
	s_waitcnt lgkmcnt(0)
	s_barrier
	s_setprio 1
	v_mfma_f32_16x16x32_bf16 v[62:65], v[146:149], v[178:181], v[62:65]
	v_mfma_f32_16x16x32_bf16 v[54:57], v[154:157], v[178:181], v[54:57]
	v_mfma_f32_16x16x32_bf16 v[46:49], v[146:149], v[194:197], v[46:49]
	v_mfma_f32_16x16x32_bf16 v[38:41], v[154:157], v[194:197], v[38:41]
	v_mfma_f32_16x16x32_bf16 v[30:33], v[146:149], v[218:221], v[30:33]
	v_mfma_f32_16x16x32_bf16 v[22:25], v[154:157], v[218:221], v[22:25]
	v_mfma_f32_16x16x32_bf16 v[14:17], v[146:149], v[226:229], v[14:17]
	v_mfma_f32_16x16x32_bf16 v[6:9], v[154:157], v[226:229], v[6:9]
	v_mfma_f32_16x16x32_bf16 v[62:65], v[150:153], v[190:193], v[62:65]
	v_mfma_f32_16x16x32_bf16 v[54:57], v[158:161], v[190:193], v[54:57]
	v_mfma_f32_16x16x32_bf16 v[46:49], v[150:153], v[214:217], v[46:49]
	v_mfma_f32_16x16x32_bf16 v[38:41], v[158:161], v[214:217], v[38:41]
	v_mfma_f32_16x16x32_bf16 v[30:33], v[150:153], v[222:225], v[30:33]
	v_mfma_f32_16x16x32_bf16 v[22:25], v[158:161], v[222:225], v[22:25]
	v_mfma_f32_16x16x32_bf16 v[14:17], v[150:153], v[230:233], v[14:17]
	v_mfma_f32_16x16x32_bf16 v[6:9], v[158:161], v[230:233], v[6:9]
	v_mfma_f32_16x16x32_bf16 v[58:61], v[162:165], v[178:181], v[58:61]
	v_mfma_f32_16x16x32_bf16 v[50:53], v[170:173], v[178:181], v[50:53]
	v_mfma_f32_16x16x32_bf16 v[42:45], v[162:165], v[194:197], v[42:45]
	v_mfma_f32_16x16x32_bf16 v[34:37], v[170:173], v[194:197], v[34:37]
	v_mfma_f32_16x16x32_bf16 v[26:29], v[162:165], v[218:221], v[26:29]
	v_mfma_f32_16x16x32_bf16 v[18:21], v[170:173], v[218:221], v[18:21]
	v_mfma_f32_16x16x32_bf16 v[10:13], v[162:165], v[226:229], v[10:13]
	v_mfma_f32_16x16x32_bf16 v[2:5], v[170:173], v[226:229], v[2:5]
	v_mfma_f32_16x16x32_bf16 v[58:61], v[166:169], v[190:193], v[58:61]
	v_mfma_f32_16x16x32_bf16 v[50:53], v[174:177], v[190:193], v[50:53]
	v_mfma_f32_16x16x32_bf16 v[42:45], v[166:169], v[214:217], v[42:45]
	v_mfma_f32_16x16x32_bf16 v[34:37], v[174:177], v[214:217], v[34:37]
	v_mfma_f32_16x16x32_bf16 v[26:29], v[166:169], v[222:225], v[26:29]
	v_mfma_f32_16x16x32_bf16 v[18:21], v[174:177], v[222:225], v[18:21]
	v_mfma_f32_16x16x32_bf16 v[10:13], v[166:169], v[230:233], v[10:13]
	v_mfma_f32_16x16x32_bf16 v[2:5], v[174:177], v[230:233], v[2:5]
	s_setprio 0
	s_barrier
	s_add_i32 s48, 0, 0x18000
	s_add_i32 s49, 0, 0x1c000
	v_add_u32_e32 v158, s48, v142
	v_add_u32_e32 v174, s49, v142
	ds_read_b128 v[146:149], v158
	ds_read_b128 v[150:153], v158 offset:1024
	ds_read_b128 v[154:157], v158 offset:2048
	ds_read_b128 v[158:161], v158 offset:3072
	ds_read_b128 v[162:165], v174
	ds_read_b128 v[166:169], v174 offset:1024
	ds_read_b128 v[170:173], v174 offset:2048
	ds_read_b128 v[174:177], v174 offset:3072
	s_add_u32 s0, s30, 0x40000
	s_addc_u32 s1, s31, 0
	s_mov_b32 m0, s38
	v_lshl_add_u64 v[240:241], s[0:1], 0, v[130:131]
	ds_read_b128 v[178:181], v145 offset:32768
	ds_read_b128 v[190:193], v145 offset:33792
	ds_read_b128 v[194:197], v145 offset:34816
	ds_read_b128 v[214:217], v145 offset:35840
	ds_read_b128 v[218:221], v145 offset:36864
	ds_read_b128 v[222:225], v145 offset:37888
	ds_read_b128 v[226:229], v145 offset:38912
	ds_read_b128 v[230:233], v145 offset:39936
	global_load_lds_dwordx4 v[240:241], off
	v_lshl_add_u64 v[240:241], s[0:1], 0, v[132:133]
	s_mov_b32 m0, s39
	s_nop 0
	global_load_lds_dwordx4 v[240:241], off
	s_waitcnt vmcnt(8)
	s_waitcnt lgkmcnt(0)
	s_barrier
	s_setprio 1
	v_mfma_f32_16x16x32_bf16 v[126:129], v[146:149], v[178:181], v[126:129]
	v_mfma_f32_16x16x32_bf16 v[118:121], v[154:157], v[178:181], v[118:121]
	v_mfma_f32_16x16x32_bf16 v[110:113], v[146:149], v[194:197], v[110:113]
	v_mfma_f32_16x16x32_bf16 v[102:105], v[154:157], v[194:197], v[102:105]
	v_mfma_f32_16x16x32_bf16 v[94:97], v[146:149], v[218:221], v[94:97]
	v_mfma_f32_16x16x32_bf16 v[86:89], v[154:157], v[218:221], v[86:89]
	v_mfma_f32_16x16x32_bf16 v[78:81], v[146:149], v[226:229], v[78:81]
	v_mfma_f32_16x16x32_bf16 v[70:73], v[154:157], v[226:229], v[70:73]
	v_mfma_f32_16x16x32_bf16 v[126:129], v[150:153], v[190:193], v[126:129]
	v_mfma_f32_16x16x32_bf16 v[118:121], v[158:161], v[190:193], v[118:121]
	v_mfma_f32_16x16x32_bf16 v[110:113], v[150:153], v[214:217], v[110:113]
	v_mfma_f32_16x16x32_bf16 v[102:105], v[158:161], v[214:217], v[102:105]
	v_mfma_f32_16x16x32_bf16 v[94:97], v[150:153], v[222:225], v[94:97]
	v_mfma_f32_16x16x32_bf16 v[86:89], v[158:161], v[222:225], v[86:89]
	v_mfma_f32_16x16x32_bf16 v[78:81], v[150:153], v[230:233], v[78:81]
	v_mfma_f32_16x16x32_bf16 v[70:73], v[158:161], v[230:233], v[70:73]
	v_mfma_f32_16x16x32_bf16 v[122:125], v[162:165], v[178:181], v[122:125]
	v_mfma_f32_16x16x32_bf16 v[114:117], v[170:173], v[178:181], v[114:117]
	v_mfma_f32_16x16x32_bf16 v[106:109], v[162:165], v[194:197], v[106:109]
	v_mfma_f32_16x16x32_bf16 v[98:101], v[170:173], v[194:197], v[98:101]
	v_mfma_f32_16x16x32_bf16 v[90:93], v[162:165], v[218:221], v[90:93]
	v_mfma_f32_16x16x32_bf16 v[82:85], v[170:173], v[218:221], v[82:85]
	v_mfma_f32_16x16x32_bf16 v[74:77], v[162:165], v[226:229], v[74:77]
	v_mfma_f32_16x16x32_bf16 v[66:69], v[170:173], v[226:229], v[66:69]
	v_mfma_f32_16x16x32_bf16 v[122:125], v[166:169], v[190:193], v[122:125]
	v_mfma_f32_16x16x32_bf16 v[114:117], v[174:177], v[190:193], v[114:117]
	v_mfma_f32_16x16x32_bf16 v[106:109], v[166:169], v[214:217], v[106:109]
	v_mfma_f32_16x16x32_bf16 v[98:101], v[174:177], v[214:217], v[98:101]
	v_mfma_f32_16x16x32_bf16 v[90:93], v[166:169], v[222:225], v[90:93]
	v_mfma_f32_16x16x32_bf16 v[82:85], v[174:177], v[222:225], v[82:85]
	v_mfma_f32_16x16x32_bf16 v[74:77], v[166:169], v[230:233], v[74:77]
	v_mfma_f32_16x16x32_bf16 v[66:69], v[174:177], v[230:233], v[66:69]
	s_setprio 0
	s_barrier
	s_add_i32 s0, s48, s35
	v_lshl_add_u64 v[182:183], v[182:183], 0, s[96:97]
	s_mov_b32 m0, s0
	ds_read_b128 v[178:181], v145 offset:49152
	ds_read_b128 v[190:193], v145 offset:50176
	ds_read_b128 v[194:197], v145 offset:51200
	ds_read_b128 v[214:217], v145 offset:52224
	ds_read_b128 v[218:221], v145 offset:53248
	ds_read_b128 v[222:225], v145 offset:54272
	ds_read_b128 v[226:229], v145 offset:55296
	ds_read_b128 v[230:233], v145 offset:56320
	global_load_lds_dwordx4 v[182:183], off
	s_add_i32 m0, s0, 0x2000
	s_add_u32 s0, s28, 0x40080
	v_lshl_add_u64 v[182:183], v[234:235], 0, s[96:97]
	s_addc_u32 s1, s29, 0
	s_add_i32 s28, s49, s35
	global_load_lds_dwordx4 v[182:183], off
	v_lshl_add_u64 v[182:183], s[0:1], 0, v[0:1]
	s_mov_b32 m0, s28
	s_nop 0
	global_load_lds_dwordx4 v[182:183], off
	v_lshl_add_u64 v[182:183], s[0:1], 0, v[134:135]
	s_add_i32 m0, s28, 0x2000
	s_nop 0
	global_load_lds_dwordx4 v[182:183], off
	v_lshl_add_u64 v[182:183], v[236:237], 0, s[96:97]
	s_mov_b32 m0, s40
	s_nop 0
	global_load_lds_dwordx4 v[182:183], off
	v_lshl_add_u64 v[182:183], v[238:239], 0, s[96:97]
	s_mov_b32 m0, s41
	s_nop 0
	global_load_lds_dwordx4 v[182:183], off
	s_waitcnt vmcnt(8)
	s_waitcnt lgkmcnt(0)
	s_barrier
	s_setprio 1
	v_mfma_f32_16x16x32_bf16 v[62:65], v[146:149], v[178:181], v[62:65]
	v_mfma_f32_16x16x32_bf16 v[54:57], v[154:157], v[178:181], v[54:57]
	v_mfma_f32_16x16x32_bf16 v[46:49], v[146:149], v[194:197], v[46:49]
	v_mfma_f32_16x16x32_bf16 v[38:41], v[154:157], v[194:197], v[38:41]
	v_mfma_f32_16x16x32_bf16 v[30:33], v[146:149], v[218:221], v[30:33]
	v_mfma_f32_16x16x32_bf16 v[22:25], v[154:157], v[218:221], v[22:25]
	v_mfma_f32_16x16x32_bf16 v[14:17], v[146:149], v[226:229], v[14:17]
	v_mfma_f32_16x16x32_bf16 v[6:9], v[154:157], v[226:229], v[6:9]
	v_mfma_f32_16x16x32_bf16 v[62:65], v[150:153], v[190:193], v[62:65]
	v_mfma_f32_16x16x32_bf16 v[54:57], v[158:161], v[190:193], v[54:57]
	v_mfma_f32_16x16x32_bf16 v[46:49], v[150:153], v[214:217], v[46:49]
	v_mfma_f32_16x16x32_bf16 v[38:41], v[158:161], v[214:217], v[38:41]
	v_mfma_f32_16x16x32_bf16 v[30:33], v[150:153], v[222:225], v[30:33]
	v_mfma_f32_16x16x32_bf16 v[22:25], v[158:161], v[222:225], v[22:25]
	v_mfma_f32_16x16x32_bf16 v[14:17], v[150:153], v[230:233], v[14:17]
	v_mfma_f32_16x16x32_bf16 v[6:9], v[158:161], v[230:233], v[6:9]
	v_mfma_f32_16x16x32_bf16 v[58:61], v[162:165], v[178:181], v[58:61]
	v_mfma_f32_16x16x32_bf16 v[50:53], v[170:173], v[178:181], v[50:53]
	v_mfma_f32_16x16x32_bf16 v[42:45], v[162:165], v[194:197], v[42:45]
	v_mfma_f32_16x16x32_bf16 v[34:37], v[170:173], v[194:197], v[34:37]
	v_mfma_f32_16x16x32_bf16 v[26:29], v[162:165], v[218:221], v[26:29]
	v_mfma_f32_16x16x32_bf16 v[18:21], v[170:173], v[218:221], v[18:21]
	v_mfma_f32_16x16x32_bf16 v[10:13], v[162:165], v[226:229], v[10:13]
	v_mfma_f32_16x16x32_bf16 v[2:5], v[170:173], v[226:229], v[2:5]
	v_mfma_f32_16x16x32_bf16 v[58:61], v[166:169], v[190:193], v[58:61]
	v_mfma_f32_16x16x32_bf16 v[50:53], v[174:177], v[190:193], v[50:53]
	v_mfma_f32_16x16x32_bf16 v[42:45], v[166:169], v[214:217], v[42:45]
	v_mfma_f32_16x16x32_bf16 v[34:37], v[174:177], v[214:217], v[34:37]
	v_mfma_f32_16x16x32_bf16 v[26:29], v[166:169], v[222:225], v[26:29]
	v_mfma_f32_16x16x32_bf16 v[18:21], v[174:177], v[222:225], v[18:21]
	v_mfma_f32_16x16x32_bf16 v[10:13], v[166:169], v[230:233], v[10:13]
	v_mfma_f32_16x16x32_bf16 v[2:5], v[174:177], v[230:233], v[2:5]
	s_setprio 0
	s_barrier
	s_add_i32 s68, s68, 2
	s_add_u32 s26, s26, 0x100
	s_addc_u32 s27, s27, 0
	s_add_u32 s58, s58, 0x100
	s_addc_u32 s59, s59, 0
	s_cmp_gt_u32 s68, 13
	s_cbranch_scc0 .LBB11_2567
	s_and_b64 vcc, exec, s[20:21]
	s_cbranch_vccz .LBB11_2570
	s_barrier

.LBB11_2770:
	s_add_u32 s24, s22, 0x100
	s_addc_u32 s25, s23, 0
	s_add_i32 s0, 0, 0x10000
	s_cmp_eq_u32 s59, 40
	s_cselect_b32 s29, s8, s25
	s_cselect_b32 s28, s9, s24
	v_add_u32_e32 v148, s0, v151
	s_cselect_b32 s27, s47, s58
	s_cselect_b32 s26, s56, s57
	s_add_i32 s48, 0, 0x14000
	ds_read_b128 v[140:143], v148
	ds_read_b128 v[144:147], v148 offset:1024
	ds_read_b128 v[154:157], v148 offset:2048
	ds_read_b128 v[158:161], v148 offset:3072
	v_add_u32_e32 v148, s48, v151
	ds_read_b128 v[162:165], v148
	ds_read_b128 v[166:169], v148 offset:1024
	ds_read_b128 v[170:173], v148 offset:2048
	ds_read_b128 v[174:177], v148 offset:3072
	v_lshl_add_u64 v[148:149], s[22:23], 0, v[136:137]
	s_add_i32 m0, s31, 0xc000
	ds_read_b128 v[178:181], v153
	ds_read_b128 v[190:193], v153 offset:1024
	ds_read_b128 v[194:197], v153 offset:2048
	ds_read_b128 v[214:217], v153 offset:3072
	ds_read_b128 v[218:221], v153 offset:4096
	ds_read_b128 v[222:225], v153 offset:5120
	ds_read_b128 v[226:229], v153 offset:6144
	ds_read_b128 v[230:233], v153 offset:7168
	global_load_lds_dwordx4 v[148:149], off
	v_lshl_add_u64 v[148:149], s[22:23], 0, v[138:139]
	s_add_i32 m0, s31, 0xe000
	s_nop 0
	global_load_lds_dwordx4 v[148:149], off
	s_waitcnt vmcnt(8)
	s_waitcnt lgkmcnt(0)
	s_barrier
	s_setprio 1
	v_mfma_f32_16x16x32_bf16 v[126:129], v[140:143], v[178:181], v[126:129]
	v_mfma_f32_16x16x32_bf16 v[122:125], v[154:157], v[178:181], v[122:125]
	v_mfma_f32_16x16x32_bf16 v[110:113], v[140:143], v[194:197], v[110:113]
	v_mfma_f32_16x16x32_bf16 v[106:109], v[154:157], v[194:197], v[106:109]
	v_mfma_f32_16x16x32_bf16 v[94:97], v[140:143], v[218:221], v[94:97]
	v_mfma_f32_16x16x32_bf16 v[90:93], v[154:157], v[218:221], v[90:93]
	v_mfma_f32_16x16x32_bf16 v[78:81], v[140:143], v[226:229], v[78:81]
	v_mfma_f32_16x16x32_bf16 v[74:77], v[154:157], v[226:229], v[74:77]
	v_mfma_f32_16x16x32_bf16 v[126:129], v[144:147], v[190:193], v[126:129]
	v_mfma_f32_16x16x32_bf16 v[122:125], v[158:161], v[190:193], v[122:125]
	v_mfma_f32_16x16x32_bf16 v[110:113], v[144:147], v[214:217], v[110:113]
	v_mfma_f32_16x16x32_bf16 v[106:109], v[158:161], v[214:217], v[106:109]
	v_mfma_f32_16x16x32_bf16 v[94:97], v[144:147], v[222:225], v[94:97]
	v_mfma_f32_16x16x32_bf16 v[90:93], v[158:161], v[222:225], v[90:93]
	v_mfma_f32_16x16x32_bf16 v[78:81], v[144:147], v[230:233], v[78:81]
	v_mfma_f32_16x16x32_bf16 v[74:77], v[158:161], v[230:233], v[74:77]
	v_mfma_f32_16x16x32_bf16 v[118:121], v[162:165], v[178:181], v[118:121]
	v_mfma_f32_16x16x32_bf16 v[114:117], v[170:173], v[178:181], v[114:117]
	v_mfma_f32_16x16x32_bf16 v[102:105], v[162:165], v[194:197], v[102:105]
	v_mfma_f32_16x16x32_bf16 v[98:101], v[170:173], v[194:197], v[98:101]
	v_mfma_f32_16x16x32_bf16 v[86:89], v[162:165], v[218:221], v[86:89]
	v_mfma_f32_16x16x32_bf16 v[82:85], v[170:173], v[218:221], v[82:85]
	v_mfma_f32_16x16x32_bf16 v[70:73], v[162:165], v[226:229], v[70:73]
	v_mfma_f32_16x16x32_bf16 v[66:69], v[170:173], v[226:229], v[66:69]
	v_mfma_f32_16x16x32_bf16 v[118:121], v[166:169], v[190:193], v[118:121]
	v_mfma_f32_16x16x32_bf16 v[114:117], v[174:177], v[190:193], v[114:117]
	v_mfma_f32_16x16x32_bf16 v[102:105], v[166:169], v[214:217], v[102:105]
	v_mfma_f32_16x16x32_bf16 v[98:101], v[174:177], v[214:217], v[98:101]
	v_mfma_f32_16x16x32_bf16 v[86:89], v[166:169], v[222:225], v[86:89]
	v_mfma_f32_16x16x32_bf16 v[82:85], v[174:177], v[222:225], v[82:85]
	v_mfma_f32_16x16x32_bf16 v[70:73], v[166:169], v[230:233], v[70:73]
	v_mfma_f32_16x16x32_bf16 v[66:69], v[174:177], v[230:233], v[66:69]
	s_setprio 0
	s_barrier
	s_add_i32 s0, s0, s30
	v_lshl_add_u64 v[148:149], s[26:27], 0, v[0:1]
	s_mov_b32 m0, s0
	ds_read_b128 v[178:181], v153 offset:16384
	ds_read_b128 v[190:193], v153 offset:17408
	ds_read_b128 v[194:197], v153 offset:18432
	ds_read_b128 v[214:217], v153 offset:19456
	ds_read_b128 v[218:221], v153 offset:20480
	ds_read_b128 v[222:225], v153 offset:21504
	ds_read_b128 v[226:229], v153 offset:22528
	ds_read_b128 v[230:233], v153 offset:23552
	global_load_lds_dwordx4 v[148:149], off
	s_add_i32 m0, s0, 0x2000
	s_add_u32 s0, s26, 0xb0000
	v_lshl_add_u64 v[182:183], s[26:27], 0, v[130:131]
	s_addc_u32 s1, s27, 0
	s_add_i32 s22, s48, s30
	global_load_lds_dwordx4 v[182:183], off
	v_lshl_add_u64 v[234:235], s[0:1], 0, v[0:1]
	s_mov_b32 m0, s22
	v_lshl_add_u64 v[236:237], s[28:29], 0, v[132:133]
	global_load_lds_dwordx4 v[234:235], off
	v_lshl_add_u64 v[234:235], s[0:1], 0, v[130:131]
	s_add_i32 m0, s22, 0x2000
	s_nop 0
	global_load_lds_dwordx4 v[234:235], off
	v_lshl_add_u64 v[234:235], s[28:29], 0, v[134:135]
	s_mov_b32 m0, s31
	s_nop 0
	global_load_lds_dwordx4 v[234:235], off
	s_mov_b32 m0, s34
	s_nop 0
	global_load_lds_dwordx4 v[236:237], off
	s_waitcnt vmcnt(8)
	s_waitcnt lgkmcnt(0)
	s_barrier
	s_setprio 1
	v_mfma_f32_16x16x32_bf16 v[62:65], v[140:143], v[178:181], v[62:65]
	v_mfma_f32_16x16x32_bf16 v[58:61], v[154:157], v[178:181], v[58:61]
	v_mfma_f32_16x16x32_bf16 v[46:49], v[140:143], v[194:197], v[46:49]
	v_mfma_f32_16x16x32_bf16 v[42:45], v[154:157], v[194:197], v[42:45]
	v_mfma_f32_16x16x32_bf16 v[30:33], v[140:143], v[218:221], v[30:33]
	v_mfma_f32_16x16x32_bf16 v[26:29], v[154:157], v[218:221], v[26:29]
	v_mfma_f32_16x16x32_bf16 v[14:17], v[140:143], v[226:229], v[14:17]
	v_mfma_f32_16x16x32_bf16 v[10:13], v[154:157], v[226:229], v[10:13]
	v_mfma_f32_16x16x32_bf16 v[62:65], v[144:147], v[190:193], v[62:65]
	v_mfma_f32_16x16x32_bf16 v[58:61], v[158:161], v[190:193], v[58:61]
	v_mfma_f32_16x16x32_bf16 v[46:49], v[144:147], v[214:217], v[46:49]
	v_mfma_f32_16x16x32_bf16 v[42:45], v[158:161], v[214:217], v[42:45]
	v_mfma_f32_16x16x32_bf16 v[30:33], v[144:147], v[222:225], v[30:33]
	v_mfma_f32_16x16x32_bf16 v[26:29], v[158:161], v[222:225], v[26:29]
	v_mfma_f32_16x16x32_bf16 v[14:17], v[144:147], v[230:233], v[14:17]
	v_mfma_f32_16x16x32_bf16 v[10:13], v[158:161], v[230:233], v[10:13]
	v_mfma_f32_16x16x32_bf16 v[54:57], v[162:165], v[178:181], v[54:57]
	v_mfma_f32_16x16x32_bf16 v[50:53], v[170:173], v[178:181], v[50:53]
	v_mfma_f32_16x16x32_bf16 v[38:41], v[162:165], v[194:197], v[38:41]
	v_mfma_f32_16x16x32_bf16 v[34:37], v[170:173], v[194:197], v[34:37]
	v_mfma_f32_16x16x32_bf16 v[22:25], v[162:165], v[218:221], v[22:25]
	v_mfma_f32_16x16x32_bf16 v[18:21], v[170:173], v[218:221], v[18:21]
	v_mfma_f32_16x16x32_bf16 v[6:9], v[162:165], v[226:229], v[6:9]
	v_mfma_f32_16x16x32_bf16 v[2:5], v[170:173], v[226:229], v[2:5]
	v_mfma_f32_16x16x32_bf16 v[54:57], v[166:169], v[190:193], v[54:57]
	v_mfma_f32_16x16x32_bf16 v[50:53], v[174:177], v[190:193], v[50:53]
	v_mfma_f32_16x16x32_bf16 v[38:41], v[166:169], v[214:217], v[38:41]
	v_mfma_f32_16x16x32_bf16 v[34:37], v[174:177], v[214:217], v[34:37]
	v_mfma_f32_16x16x32_bf16 v[22:25], v[166:169], v[222:225], v[22:25]
	v_mfma_f32_16x16x32_bf16 v[18:21], v[174:177], v[222:225], v[18:21]
	v_mfma_f32_16x16x32_bf16 v[6:9], v[166:169], v[230:233], v[6:9]
	v_mfma_f32_16x16x32_bf16 v[2:5], v[174:177], v[230:233], v[2:5]
	s_setprio 0
	s_barrier
	s_add_i32 s22, 0, 0x18000
	s_add_i32 s23, 0, 0x1c000
	v_add_u32_e32 v158, s22, v151
	v_add_u32_e32 v174, s23, v151
	ds_read_b128 v[140:143], v158
	ds_read_b128 v[144:147], v158 offset:1024
	ds_read_b128 v[154:157], v158 offset:2048
	ds_read_b128 v[158:161], v158 offset:3072
	ds_read_b128 v[162:165], v174
	ds_read_b128 v[166:169], v174 offset:1024
	ds_read_b128 v[170:173], v174 offset:2048
	ds_read_b128 v[174:177], v174 offset:3072
	s_add_u32 s0, s28, 0xb0000
	s_addc_u32 s1, s29, 0
	s_mov_b32 m0, s35
	v_lshl_add_u64 v[238:239], s[0:1], 0, v[134:135]
	ds_read_b128 v[178:181], v153 offset:32768
	ds_read_b128 v[190:193], v153 offset:33792
	ds_read_b128 v[194:197], v153 offset:34816
	ds_read_b128 v[214:217], v153 offset:35840
	ds_read_b128 v[218:221], v153 offset:36864
	ds_read_b128 v[222:225], v153 offset:37888
	ds_read_b128 v[226:229], v153 offset:38912
	ds_read_b128 v[230:233], v153 offset:39936
	global_load_lds_dwordx4 v[238:239], off
	v_lshl_add_u64 v[238:239], s[0:1], 0, v[132:133]
	s_mov_b32 m0, s40
	s_nop 0
	global_load_lds_dwordx4 v[238:239], off
	s_waitcnt vmcnt(8)
	s_waitcnt lgkmcnt(0)
	s_barrier
	s_setprio 1
	v_mfma_f32_16x16x32_bf16 v[126:129], v[140:143], v[178:181], v[126:129]
	v_mfma_f32_16x16x32_bf16 v[122:125], v[154:157], v[178:181], v[122:125]
	v_mfma_f32_16x16x32_bf16 v[110:113], v[140:143], v[194:197], v[110:113]
	v_mfma_f32_16x16x32_bf16 v[106:109], v[154:157], v[194:197], v[106:109]
	v_mfma_f32_16x16x32_bf16 v[94:97], v[140:143], v[218:221], v[94:97]
	v_mfma_f32_16x16x32_bf16 v[90:93], v[154:157], v[218:221], v[90:93]
	v_mfma_f32_16x16x32_bf16 v[78:81], v[140:143], v[226:229], v[78:81]
	v_mfma_f32_16x16x32_bf16 v[74:77], v[154:157], v[226:229], v[74:77]
	v_mfma_f32_16x16x32_bf16 v[126:129], v[144:147], v[190:193], v[126:129]
	v_mfma_f32_16x16x32_bf16 v[122:125], v[158:161], v[190:193], v[122:125]
	v_mfma_f32_16x16x32_bf16 v[110:113], v[144:147], v[214:217], v[110:113]
	v_mfma_f32_16x16x32_bf16 v[106:109], v[158:161], v[214:217], v[106:109]
	v_mfma_f32_16x16x32_bf16 v[94:97], v[144:147], v[222:225], v[94:97]
	v_mfma_f32_16x16x32_bf16 v[90:93], v[158:161], v[222:225], v[90:93]
	v_mfma_f32_16x16x32_bf16 v[78:81], v[144:147], v[230:233], v[78:81]
	v_mfma_f32_16x16x32_bf16 v[74:77], v[158:161], v[230:233], v[74:77]
	v_mfma_f32_16x16x32_bf16 v[118:121], v[162:165], v[178:181], v[118:121]
	v_mfma_f32_16x16x32_bf16 v[114:117], v[170:173], v[178:181], v[114:117]
	v_mfma_f32_16x16x32_bf16 v[102:105], v[162:165], v[194:197], v[102:105]
	v_mfma_f32_16x16x32_bf16 v[98:101], v[170:173], v[194:197], v[98:101]
	v_mfma_f32_16x16x32_bf16 v[86:89], v[162:165], v[218:221], v[86:89]
	v_mfma_f32_16x16x32_bf16 v[82:85], v[170:173], v[218:221], v[82:85]
	v_mfma_f32_16x16x32_bf16 v[70:73], v[162:165], v[226:229], v[70:73]
	v_mfma_f32_16x16x32_bf16 v[66:69], v[170:173], v[226:229], v[66:69]
	v_mfma_f32_16x16x32_bf16 v[118:121], v[166:169], v[190:193], v[118:121]
	v_mfma_f32_16x16x32_bf16 v[114:117], v[174:177], v[190:193], v[114:117]
	v_mfma_f32_16x16x32_bf16 v[102:105], v[166:169], v[214:217], v[102:105]
	v_mfma_f32_16x16x32_bf16 v[98:101], v[174:177], v[214:217], v[98:101]
	v_mfma_f32_16x16x32_bf16 v[86:89], v[166:169], v[222:225], v[86:89]
	v_mfma_f32_16x16x32_bf16 v[82:85], v[174:177], v[222:225], v[82:85]
	v_mfma_f32_16x16x32_bf16 v[70:73], v[166:169], v[230:233], v[70:73]
	v_mfma_f32_16x16x32_bf16 v[66:69], v[174:177], v[230:233], v[66:69]
	s_setprio 0
	s_barrier
	s_add_i32 s0, s22, s30
	v_lshl_add_u64 v[148:149], v[148:149], 0, s[96:97]
	s_mov_b32 m0, s0
	ds_read_b128 v[178:181], v153 offset:49152
	ds_read_b128 v[190:193], v153 offset:50176
	ds_read_b128 v[194:197], v153 offset:51200
	ds_read_b128 v[214:217], v153 offset:52224
	ds_read_b128 v[218:221], v153 offset:53248
	ds_read_b128 v[222:225], v153 offset:54272
	ds_read_b128 v[226:229], v153 offset:55296
	ds_read_b128 v[230:233], v153 offset:56320
	global_load_lds_dwordx4 v[148:149], off
	s_add_i32 m0, s0, 0x2000
	s_add_u32 s0, s26, 0xb0080
	v_lshl_add_u64 v[148:149], v[182:183], 0, s[96:97]
	s_addc_u32 s1, s27, 0
	s_add_i32 s22, s23, s30
	global_load_lds_dwordx4 v[148:149], off
	v_lshl_add_u64 v[148:149], s[0:1], 0, v[0:1]
	s_mov_b32 m0, s22
	s_nop 0
	global_load_lds_dwordx4 v[148:149], off
	v_lshl_add_u64 v[148:149], s[0:1], 0, v[130:131]
	s_add_i32 m0, s22, 0x2000
	s_nop 0
	global_load_lds_dwordx4 v[148:149], off
	v_lshl_add_u64 v[148:149], v[234:235], 0, s[96:97]
	s_mov_b32 m0, s41
	s_nop 0
	global_load_lds_dwordx4 v[148:149], off
	v_lshl_add_u64 v[148:149], v[236:237], 0, s[96:97]
	s_mov_b32 m0, s42
	s_nop 0
	global_load_lds_dwordx4 v[148:149], off
	s_waitcnt vmcnt(8)
	s_waitcnt lgkmcnt(0)
	s_barrier
	s_setprio 1
	v_mfma_f32_16x16x32_bf16 v[62:65], v[140:143], v[178:181], v[62:65]
	v_mfma_f32_16x16x32_bf16 v[58:61], v[154:157], v[178:181], v[58:61]
	v_mfma_f32_16x16x32_bf16 v[46:49], v[140:143], v[194:197], v[46:49]
	v_mfma_f32_16x16x32_bf16 v[42:45], v[154:157], v[194:197], v[42:45]
	v_mfma_f32_16x16x32_bf16 v[30:33], v[140:143], v[218:221], v[30:33]
	v_mfma_f32_16x16x32_bf16 v[26:29], v[154:157], v[218:221], v[26:29]
	v_mfma_f32_16x16x32_bf16 v[14:17], v[140:143], v[226:229], v[14:17]
	v_mfma_f32_16x16x32_bf16 v[10:13], v[154:157], v[226:229], v[10:13]
	v_mfma_f32_16x16x32_bf16 v[62:65], v[144:147], v[190:193], v[62:65]
	v_mfma_f32_16x16x32_bf16 v[58:61], v[158:161], v[190:193], v[58:61]
	v_mfma_f32_16x16x32_bf16 v[46:49], v[144:147], v[214:217], v[46:49]
	v_mfma_f32_16x16x32_bf16 v[42:45], v[158:161], v[214:217], v[42:45]
	v_mfma_f32_16x16x32_bf16 v[30:33], v[144:147], v[222:225], v[30:33]
	v_mfma_f32_16x16x32_bf16 v[26:29], v[158:161], v[222:225], v[26:29]
	v_mfma_f32_16x16x32_bf16 v[14:17], v[144:147], v[230:233], v[14:17]
	v_mfma_f32_16x16x32_bf16 v[10:13], v[158:161], v[230:233], v[10:13]
	v_mfma_f32_16x16x32_bf16 v[54:57], v[162:165], v[178:181], v[54:57]
	v_mfma_f32_16x16x32_bf16 v[50:53], v[170:173], v[178:181], v[50:53]
	v_mfma_f32_16x16x32_bf16 v[38:41], v[162:165], v[194:197], v[38:41]
	v_mfma_f32_16x16x32_bf16 v[34:37], v[170:173], v[194:197], v[34:37]
	v_mfma_f32_16x16x32_bf16 v[22:25], v[162:165], v[218:221], v[22:25]
	v_mfma_f32_16x16x32_bf16 v[18:21], v[170:173], v[218:221], v[18:21]
	v_mfma_f32_16x16x32_bf16 v[6:9], v[162:165], v[226:229], v[6:9]
	v_mfma_f32_16x16x32_bf16 v[2:5], v[170:173], v[226:229], v[2:5]
	v_mfma_f32_16x16x32_bf16 v[54:57], v[166:169], v[190:193], v[54:57]
	v_mfma_f32_16x16x32_bf16 v[50:53], v[174:177], v[190:193], v[50:53]
	v_mfma_f32_16x16x32_bf16 v[38:41], v[166:169], v[214:217], v[38:41]
	v_mfma_f32_16x16x32_bf16 v[34:37], v[174:177], v[214:217], v[34:37]
	v_mfma_f32_16x16x32_bf16 v[22:25], v[166:169], v[222:225], v[22:25]
	v_mfma_f32_16x16x32_bf16 v[18:21], v[174:177], v[222:225], v[18:21]
	v_mfma_f32_16x16x32_bf16 v[6:9], v[166:169], v[230:233], v[6:9]
	v_mfma_f32_16x16x32_bf16 v[2:5], v[174:177], v[230:233], v[2:5]
	s_setprio 0
	s_barrier
	s_add_i32 s59, s59, 2
	s_add_u32 s57, s57, 0x100
	s_addc_u32 s58, s58, 0
	s_cmp_gt_u32 s59, 41
	s_mov_b64 s[22:23], s[24:25]
	s_cbranch_scc0 .LBB11_2770
	s_and_b64 vcc, exec, s[14:15]
	s_cbranch_vccz .LBB11_2773
	s_barrier
